# score peer_top16: per-lane top-16-of-32 regenerated with Batcher odd-even merge sorts (63 CE per 16-sort instead of bitonic 80), same inputs/outputs
# speedup vs baseline: 1.0052x; 1.0024x over previous
; DEV int tidx() { int t = threadIdx.x; asm volatile("" : "+v"(t)); return t; }
; DEV f32x4 mfma16(bf16x8 a, bf16x8 b, f32x4 c) { return __builtin_amdgcn_mfma_f32_16x16x32_bf16(a, b, c, 0, 0, 0); }
; DEV void peer_top16(const bf16_t* __restrict__ pq, const bf16_t* sk  , float (&l)[16]) {
;   const int lane = tidx() & 63, l15 = lane & 15, quad = lane >> 4;
;   f32x4 acc[8];
; #pragma unroll
;   for (int nt = 0; nt < 8; nt++) acc[nt] = (f32x4){0.f, 0.f, 0.f, 0.f};
; #pragma unroll 1
;   for (int ks = 0; ks < 4; ks++) {
;     const bf16x8 bqk = *(const bf16x8*)(pq + ks * 32 + quad * 8);
; #pragma unroll
;     for (int nt = 0; nt < 8; nt++) {
;       bf16x8 ak = *(const bf16x8*)(sk + (nt * 16 + l15) * 144 + ks * 32 + quad * 8);
;       acc[nt] = mfma16(ak, bqk, acc[nt]);
;     }
;   }
.LBB0_168:
	global_load_dwordx4 v[148:151], v[102:103], off
	global_load_dwordx4 v[152:155], v[102:103], off offset:64
	global_load_dwordx4 v[156:159], v[102:103], off offset:128
	global_load_dwordx4 v[160:163], v[102:103], off offset:192
	ds_read_b128 v[164:167], v39
	ds_read_b128 v[168:171], v39 offset:4608
	ds_read_b128 v[172:175], v39 offset:9216
	ds_read_b128 v[176:179], v39 offset:13824
	ds_read_b128 v[180:183], v39 offset:18432
	ds_read_b128 v[184:187], v39 offset:23040
	ds_read_b128 v[188:191], v39 offset:27648
	ds_read_b128 v[108:111], v39 offset:32256
	s_waitcnt vmcnt(3) lgkmcnt(7)
	v_mfma_f32_16x16x32_bf16 v[30:33], v[164:167], v[148:151], v[30:33]
	ds_read_b128 v[164:167], v39 offset:64
	s_waitcnt lgkmcnt(7)
	v_mfma_f32_16x16x32_bf16 v[22:25], v[168:171], v[148:151], v[22:25]
	ds_read_b128 v[168:171], v39 offset:4672
	s_waitcnt lgkmcnt(7)
	v_mfma_f32_16x16x32_bf16 v[14:17], v[172:175], v[148:151], v[14:17]
	ds_read_b128 v[172:175], v39 offset:9280
	s_waitcnt lgkmcnt(7)
	v_mfma_f32_16x16x32_bf16 v[6:9], v[176:179], v[148:151], v[6:9]
	ds_read_b128 v[176:179], v39 offset:13888
	s_waitcnt lgkmcnt(7)
	v_mfma_f32_16x16x32_bf16 v[26:29], v[180:183], v[148:151], v[26:29]
	ds_read_b128 v[180:183], v39 offset:18496
	s_waitcnt lgkmcnt(7)
	v_mfma_f32_16x16x32_bf16 v[18:21], v[184:187], v[148:151], v[18:21]
	ds_read_b128 v[184:187], v39 offset:23104
	s_waitcnt lgkmcnt(7)
	v_mfma_f32_16x16x32_bf16 v[10:13], v[188:191], v[148:151], v[10:13]
	ds_read_b128 v[188:191], v39 offset:27712
	s_waitcnt lgkmcnt(7)
	v_mfma_f32_16x16x32_bf16 v[2:5], v[108:111], v[148:151], v[2:5]
	ds_read_b128 v[108:111], v39 offset:32320
	global_load_dwordx4 v[148:151], v[102:103], off offset:256
	s_waitcnt vmcnt(3) lgkmcnt(7)
	v_mfma_f32_16x16x32_bf16 v[30:33], v[164:167], v[152:155], v[30:33]
	ds_read_b128 v[164:167], v39 offset:128
	s_waitcnt lgkmcnt(7)
	v_mfma_f32_16x16x32_bf16 v[22:25], v[168:171], v[152:155], v[22:25]
	ds_read_b128 v[168:171], v39 offset:4736
	s_waitcnt lgkmcnt(7)
	v_mfma_f32_16x16x32_bf16 v[14:17], v[172:175], v[152:155], v[14:17]
	ds_read_b128 v[172:175], v39 offset:9344
	s_waitcnt lgkmcnt(7)
	v_mfma_f32_16x16x32_bf16 v[6:9], v[176:179], v[152:155], v[6:9]
	ds_read_b128 v[176:179], v39 offset:13952
	s_waitcnt lgkmcnt(7)
	v_mfma_f32_16x16x32_bf16 v[26:29], v[180:183], v[152:155], v[26:29]
	ds_read_b128 v[180:183], v39 offset:18560
	s_waitcnt lgkmcnt(7)
	v_mfma_f32_16x16x32_bf16 v[18:21], v[184:187], v[152:155], v[18:21]
	ds_read_b128 v[184:187], v39 offset:23168
	s_waitcnt lgkmcnt(7)
	v_mfma_f32_16x16x32_bf16 v[10:13], v[188:191], v[152:155], v[10:13]
	ds_read_b128 v[188:191], v39 offset:27776
	s_waitcnt lgkmcnt(7)
	v_mfma_f32_16x16x32_bf16 v[2:5], v[108:111], v[152:155], v[2:5]
	ds_read_b128 v[108:111], v39 offset:32384
	global_load_dwordx4 v[152:155], v[102:103], off offset:320
	s_waitcnt vmcnt(3) lgkmcnt(7)
	v_mfma_f32_16x16x32_bf16 v[30:33], v[164:167], v[156:159], v[30:33]
	ds_read_b128 v[164:167], v39 offset:192
	s_waitcnt lgkmcnt(7)
	v_mfma_f32_16x16x32_bf16 v[22:25], v[168:171], v[156:159], v[22:25]
	ds_read_b128 v[168:171], v39 offset:4800
	s_waitcnt lgkmcnt(7)
	v_mfma_f32_16x16x32_bf16 v[14:17], v[172:175], v[156:159], v[14:17]
	ds_read_b128 v[172:175], v39 offset:9408
	s_waitcnt lgkmcnt(7)
	v_mfma_f32_16x16x32_bf16 v[6:9], v[176:179], v[156:159], v[6:9]
	ds_read_b128 v[176:179], v39 offset:14016
	s_waitcnt lgkmcnt(7)
	v_mfma_f32_16x16x32_bf16 v[26:29], v[180:183], v[156:159], v[26:29]
	ds_read_b128 v[180:183], v39 offset:18624
	s_waitcnt lgkmcnt(7)
	v_mfma_f32_16x16x32_bf16 v[18:21], v[184:187], v[156:159], v[18:21]
	ds_read_b128 v[184:187], v39 offset:23232
	s_waitcnt lgkmcnt(7)
	v_mfma_f32_16x16x32_bf16 v[10:13], v[188:191], v[156:159], v[10:13]
	ds_read_b128 v[188:191], v39 offset:27840
	s_waitcnt lgkmcnt(7)
	v_mfma_f32_16x16x32_bf16 v[2:5], v[108:111], v[156:159], v[2:5]
	ds_read_b128 v[108:111], v39 offset:32448
	global_load_dwordx4 v[156:159], v[102:103], off offset:384
	s_waitcnt vmcnt(3) lgkmcnt(7)
	v_mfma_f32_16x16x32_bf16 v[30:33], v[164:167], v[160:163], v[30:33]
	s_waitcnt lgkmcnt(6)
	v_mfma_f32_16x16x32_bf16 v[22:25], v[168:171], v[160:163], v[22:25]
	s_waitcnt lgkmcnt(5)
	v_mfma_f32_16x16x32_bf16 v[14:17], v[172:175], v[160:163], v[14:17]
	s_waitcnt lgkmcnt(4)
	v_mfma_f32_16x16x32_bf16 v[6:9], v[176:179], v[160:163], v[6:9]
	s_waitcnt lgkmcnt(3)
	v_mfma_f32_16x16x32_bf16 v[26:29], v[180:183], v[160:163], v[26:29]
	s_waitcnt lgkmcnt(2)
	v_mfma_f32_16x16x32_bf16 v[18:21], v[184:187], v[160:163], v[18:21]
	s_waitcnt lgkmcnt(1)
	v_mfma_f32_16x16x32_bf16 v[10:13], v[188:191], v[160:163], v[10:13]
	s_waitcnt lgkmcnt(0)
; DEV f32x4 mfma16(bf16x8 a, bf16x8 b, f32x4 c) { return __builtin_amdgcn_mfma_f32_16x16x32_bf16(a, b, c, 0, 0, 0); }
; DEV void ce(float& a, float& b) { float hi = fmaxf(a, b), lo = fminf(a, b); a = hi; b = lo; }
; DEV void sort16_desc(float (&a)[16]) {
; #pragma unroll
;   for (int k = 2; k <= 16; k <<= 1)
; #pragma unroll
;     for (int j = k >> 1; j > 0; j >>= 1)
; #pragma unroll
;       for (int i = 0; i < 16; i++) {
;         const int p = i ^ j;
;         if (p > i) { if ((i & k) == 0) ce(a[i], a[p]); else ce(a[p], a[i]); }
;       }
; }
; DEV void peer_top16(const bf16_t* __restrict__ pq, const bf16_t* sk  , float (&l)[16]) {
;     ...
;       acc[nt] = mfma16(ak, bqk, acc[nt]);
;     }
;   }
;   float hi[16];
; #pragma unroll
;   for (int nt = 0; nt < 4; nt++)
; #pragma unroll
;     for (int r = 0; r < 4; r++) {
;       l[nt * 4 + r] = __uint_as_float((__float_as_uint(acc[nt][r]) & ~127u) | (unsigned)(nt * 16 + quad * 4 + r));
;       hi[nt * 4 + r] = __uint_as_float((__float_as_uint(acc[nt + 4][r]) & ~127u) | (unsigned)((nt + 4) * 16 + quad * 4 + r));
;     }
;   sort16_desc(l);
	v_mfma_f32_16x16x32_bf16 v[2:5], v[108:111], v[160:163], v[2:5]
	global_load_dwordx4 v[160:163], v[102:103], off offset:448
	s_movk_i32 s0, 0x100
	v_lshlrev_b32_e32 v0, 2, v0
	s_movk_i32 s0, 0xff80
	v_and_or_b32 v30, v30, s0, v0
	v_and_b32_e32 v27, 0xffffff80, v27
	s_movk_i32 s0, 0x41
	v_or3_b32 v27, v0, v27, s0
	v_and_b32_e32 v28, 0xffffff80, v28
	s_movk_i32 s0, 0x42
	v_or3_b32 v28, v0, v28, s0
	v_and_b32_e32 v29, 0xffffff80, v29
	s_movk_i32 s0, 0x43
	v_or3_b32 v29, v0, v29, s0
	v_and_b32_e32 v18, 0xffffff80, v18
	s_movk_i32 s0, 0x50
	v_or3_b32 v18, v0, v18, s0
	v_and_b32_e32 v19, 0xffffff80, v19
	s_movk_i32 s0, 0x51
	v_or3_b32 v19, v0, v19, s0
	v_and_b32_e32 v20, 0xffffff80, v20
	s_movk_i32 s0, 0x52
	v_or3_b32 v20, v0, v20, s0
	v_and_b32_e32 v21, 0xffffff80, v21
	s_movk_i32 s0, 0x53
	v_or3_b32 v21, v0, v21, s0
	v_and_b32_e32 v10, 0xffffff80, v10
	s_movk_i32 s0, 0x60
	v_or3_b32 v10, v0, v10, s0
	v_and_b32_e32 v11, 0xffffff80, v11
	s_movk_i32 s0, 0x61
	v_or3_b32 v11, v0, v11, s0
	v_and_b32_e32 v12, 0xffffff80, v12
	s_movk_i32 s0, 0x62
	v_or3_b32 v12, v0, v12, s0
	v_and_b32_e32 v13, 0xffffff80, v13
	s_movk_i32 s0, 0x63
	v_or3_b32 v13, v0, v13, s0
	v_and_b32_e32 v2, 0xffffff80, v2
	s_movk_i32 s0, 0x70
	v_or3_b32 v2, v0, v2, s0
	v_and_b32_e32 v3, 0xffffff80, v3
	s_movk_i32 s0, 0x71
	v_and_b32_e32 v26, 0xffffff80, v26
	v_and_b32_e32 v31, 0xffffff80, v31
	v_or3_b32 v3, v0, v3, s0
	v_and_b32_e32 v4, 0xffffff80, v4
	s_movk_i32 s0, 0x72
	v_or3_b32 v26, v0, v26, 64
	v_or3_b32 v31, v0, v31, 1
	v_and_b32_e32 v32, 0xffffff80, v32
	v_and_b32_e32 v33, 0xffffff80, v33
	v_and_b32_e32 v22, 0xffffff80, v22
	v_and_b32_e32 v23, 0xffffff80, v23
	v_and_b32_e32 v24, 0xffffff80, v24
	v_and_b32_e32 v25, 0xffffff80, v25
	v_and_b32_e32 v14, 0xffffff80, v14
	v_and_b32_e32 v15, 0xffffff80, v15
	v_and_b32_e32 v16, 0xffffff80, v16
	v_and_b32_e32 v17, 0xffffff80, v17
	v_and_b32_e32 v6, 0xffffff80, v6
	v_and_b32_e32 v7, 0xffffff80, v7
	v_and_b32_e32 v8, 0xffffff80, v8
	v_or3_b32 v4, v0, v4, s0
	v_and_b32_e32 v9, 0xffffff80, v9
	v_and_b32_e32 v5, 0xffffff80, v5
	s_movk_i32 s0, 0x73
	v_or3_b32 v32, v0, v32, 2
	v_or3_b32 v33, v0, v33, 3
	v_or3_b32 v22, v0, v22, 16
	v_or3_b32 v23, v0, v23, 17
	v_or3_b32 v24, v0, v24, 18
	v_or3_b32 v25, v0, v25, 19
	v_or3_b32 v14, v0, v14, 32
	v_or3_b32 v15, v0, v15, 33
	v_or3_b32 v16, v0, v16, 34
	v_or3_b32 v17, v0, v17, 35
	v_or3_b32 v6, v0, v6, 48
	v_or3_b32 v7, v0, v7, 49
	v_or3_b32 v8, v0, v8, 50
	v_or3_b32 v9, v0, v9, 51
	v_or3_b32 v0, v0, v5, s0
	v_max_f32_e32 v180, v30, v27
	v_min_f32_e32 v27, v30, v27
	v_max_f32_e32 v30, v28, v29
	v_min_f32_e32 v29, v28, v29
	v_max_f32_e32 v28, v180, v30
	v_min_f32_e32 v30, v180, v30
	v_max_f32_e32 v180, v27, v29
	v_min_f32_e32 v29, v27, v29
	v_max_f32_e32 v27, v180, v30
	v_min_f32_e32 v30, v180, v30
	v_max_f32_e32 v180, v18, v19
	v_min_f32_e32 v19, v18, v19
	v_max_f32_e32 v18, v20, v21
	v_min_f32_e32 v21, v20, v21
	v_max_f32_e32 v20, v180, v18
	v_min_f32_e32 v18, v180, v18
	v_max_f32_e32 v180, v19, v21
	v_min_f32_e32 v21, v19, v21
	v_max_f32_e32 v19, v180, v18
	v_min_f32_e32 v18, v180, v18
	v_max_f32_e32 v180, v28, v20
	v_min_f32_e32 v20, v28, v20
	v_max_f32_e32 v28, v30, v18
	v_min_f32_e32 v18, v30, v18
	v_max_f32_e32 v30, v28, v20
	v_min_f32_e32 v20, v28, v20
	v_max_f32_e32 v28, v27, v19
	v_min_f32_e32 v19, v27, v19
	v_max_f32_e32 v27, v29, v21
	v_min_f32_e32 v21, v29, v21
	v_max_f32_e32 v29, v27, v19
	v_min_f32_e32 v19, v27, v19
	v_max_f32_e32 v27, v28, v30
	v_min_f32_e32 v30, v28, v30
	v_max_f32_e32 v28, v29, v20
	v_min_f32_e32 v20, v29, v20
	v_max_f32_e32 v29, v19, v18
	v_min_f32_e32 v18, v19, v18
	v_max_f32_e32 v19, v10, v11
	v_min_f32_e32 v11, v10, v11
	v_max_f32_e32 v10, v12, v13
	v_min_f32_e32 v13, v12, v13
	v_max_f32_e32 v12, v19, v10
	v_min_f32_e32 v10, v19, v10
	v_max_f32_e32 v19, v11, v13
	v_min_f32_e32 v13, v11, v13
	v_max_f32_e32 v11, v19, v10
	v_min_f32_e32 v10, v19, v10
	v_max_f32_e32 v19, v2, v3
	v_min_f32_e32 v3, v2, v3
	v_max_f32_e32 v2, v26, v31
	v_min_f32_e32 v31, v26, v31
	v_max_f32_e32 v26, v19, v2
	v_min_f32_e32 v2, v19, v2
	v_max_f32_e32 v19, v3, v31
	v_min_f32_e32 v31, v3, v31
	v_max_f32_e32 v3, v19, v2
	v_min_f32_e32 v2, v19, v2
	v_max_f32_e32 v19, v12, v26
	v_min_f32_e32 v26, v12, v26
	v_max_f32_e32 v12, v10, v2
	v_min_f32_e32 v2, v10, v2
	v_max_f32_e32 v10, v12, v26
	v_min_f32_e32 v26, v12, v26
	v_max_f32_e32 v12, v11, v3
	v_min_f32_e32 v3, v11, v3
	v_max_f32_e32 v11, v13, v31
	v_min_f32_e32 v31, v13, v31
	v_max_f32_e32 v13, v11, v3
	v_min_f32_e32 v3, v11, v3
	v_max_f32_e32 v11, v12, v10
	v_min_f32_e32 v10, v12, v10
	v_max_f32_e32 v12, v13, v26
	v_min_f32_e32 v26, v13, v26
	v_max_f32_e32 v13, v3, v2
	v_min_f32_e32 v2, v3, v2
	v_max_f32_e32 v3, v180, v19
	v_min_f32_e32 v19, v180, v19
	v_max_f32_e32 v180, v20, v26
	v_min_f32_e32 v26, v20, v26
	v_max_f32_e32 v20, v180, v19
	v_min_f32_e32 v19, v180, v19
	v_max_f32_e32 v180, v30, v10
	v_min_f32_e32 v10, v30, v10
	v_max_f32_e32 v30, v18, v2
	v_min_f32_e32 v2, v18, v2
	v_max_f32_e32 v18, v30, v10
	v_min_f32_e32 v10, v30, v10
	v_max_f32_e32 v30, v180, v20
	v_min_f32_e32 v20, v180, v20
	v_max_f32_e32 v180, v18, v19
	v_min_f32_e32 v19, v18, v19
	v_max_f32_e32 v18, v10, v26
	v_min_f32_e32 v26, v10, v26
	v_max_f32_e32 v10, v27, v11
	v_min_f32_e32 v11, v27, v11
	v_max_f32_e32 v27, v29, v13
	v_min_f32_e32 v13, v29, v13
	v_max_f32_e32 v29, v27, v11
	v_min_f32_e32 v11, v27, v11
	v_max_f32_e32 v27, v28, v12
	v_min_f32_e32 v12, v28, v12
	v_max_f32_e32 v28, v21, v31
	v_min_f32_e32 v31, v21, v31
	v_max_f32_e32 v21, v28, v12
	v_min_f32_e32 v12, v28, v12
	v_max_f32_e32 v28, v27, v29
	v_min_f32_e32 v29, v27, v29
	v_max_f32_e32 v27, v21, v11
; DEV void ce(float& a, float& b) { float hi = fmaxf(a, b), lo = fminf(a, b); a = hi; b = lo; }
; DEV void sort16_desc(float (&a)[16]) {
; #pragma unroll
;   for (int k = 2; k <= 16; k <<= 1)
; #pragma unroll
;     for (int j = k >> 1; j > 0; j >>= 1)
; #pragma unroll
;       for (int i = 0; i < 16; i++) {
;         const int p = i ^ j;
;         if (p > i) { if ((i & k) == 0) ce(a[i], a[p]); else ce(a[p], a[i]); }
;       }
; }
; DEV void merge_xor(float (&l)[16], int mask) {
;   float t[16];
; #pragma unroll
;   for (int i = 0; i < 16; i++) t[i] = __shfl_xor(l[15 - i], mask);
; #pragma unroll
;   for (int i = 0; i < 16; i++) l[i] = fmaxf(l[i], t[i]);
;   bitonic16(l);
; }
; DEV void peer_top16(const bf16_t* __restrict__ pq, const bf16_t* sk  , float (&l)[16]) {
;     ...
;   sort16_desc(l);
;   sort16_desc(hi);
; #pragma unroll
;   for (int i = 0; i < 16; i++) l[i] = fmaxf(l[i], hi[15 - i]);
;   bitonic16(l);
;   merge_xor(l, 16);
;   merge_xor(l, 32);
	v_min_f32_e32 v11, v21, v11
	v_max_f32_e32 v21, v12, v13
	v_min_f32_e32 v13, v12, v13
	v_max_f32_e32 v12, v10, v30
	v_min_f32_e32 v30, v10, v30
	v_max_f32_e32 v10, v28, v20
	v_min_f32_e32 v20, v28, v20
	v_max_f32_e32 v28, v29, v180
	v_min_f32_e32 v180, v29, v180
	v_max_f32_e32 v29, v27, v19
	v_min_f32_e32 v19, v27, v19
	v_max_f32_e32 v27, v11, v18
	v_min_f32_e32 v18, v11, v18
	v_max_f32_e32 v11, v21, v26
	v_min_f32_e32 v26, v21, v26
	v_max_f32_e32 v21, v13, v2
	v_min_f32_e32 v2, v13, v2
	v_max_f32_e32 v13, v4, v32
	v_min_f32_e32 v32, v4, v32
	v_max_f32_e32 v4, v33, v22
	v_min_f32_e32 v22, v33, v22
	v_max_f32_e32 v33, v13, v4
	v_min_f32_e32 v4, v13, v4
	v_max_f32_e32 v13, v32, v22
	v_min_f32_e32 v22, v32, v22
	v_max_f32_e32 v32, v13, v4
	v_min_f32_e32 v4, v13, v4
	v_max_f32_e32 v13, v23, v24
	v_min_f32_e32 v24, v23, v24
	v_max_f32_e32 v23, v25, v14
	v_min_f32_e32 v14, v25, v14
	v_max_f32_e32 v25, v13, v23
	v_min_f32_e32 v23, v13, v23
	v_max_f32_e32 v13, v24, v14
	v_min_f32_e32 v14, v24, v14
	v_max_f32_e32 v24, v13, v23
	v_min_f32_e32 v23, v13, v23
	v_max_f32_e32 v13, v33, v25
	v_min_f32_e32 v25, v33, v25
	v_max_f32_e32 v33, v4, v23
	v_min_f32_e32 v23, v4, v23
	v_max_f32_e32 v4, v33, v25
	v_min_f32_e32 v25, v33, v25
	v_max_f32_e32 v33, v32, v24
	v_min_f32_e32 v24, v32, v24
	v_max_f32_e32 v32, v22, v14
	v_min_f32_e32 v14, v22, v14
	v_max_f32_e32 v22, v32, v24
	v_min_f32_e32 v24, v32, v24
	v_max_f32_e32 v32, v33, v4
	v_min_f32_e32 v4, v33, v4
	v_max_f32_e32 v33, v22, v25
	v_min_f32_e32 v25, v22, v25
	v_max_f32_e32 v22, v24, v23
	v_min_f32_e32 v23, v24, v23
	v_max_f32_e32 v24, v15, v16
	v_min_f32_e32 v16, v15, v16
	v_max_f32_e32 v15, v17, v6
	v_min_f32_e32 v6, v17, v6
	v_max_f32_e32 v17, v24, v15
	v_min_f32_e32 v15, v24, v15
	v_max_f32_e32 v24, v16, v6
	v_min_f32_e32 v6, v16, v6
	v_max_f32_e32 v16, v24, v15
	v_min_f32_e32 v15, v24, v15
	v_max_f32_e32 v24, v7, v8
	v_min_f32_e32 v8, v7, v8
	v_max_f32_e32 v7, v9, v0
	v_min_f32_e32 v0, v9, v0
	v_max_f32_e32 v9, v24, v7
	v_min_f32_e32 v7, v24, v7
	v_max_f32_e32 v24, v8, v0
	v_min_f32_e32 v0, v8, v0
	v_max_f32_e32 v8, v24, v7
	v_min_f32_e32 v7, v24, v7
	v_max_f32_e32 v24, v17, v9
	v_min_f32_e32 v9, v17, v9
	v_max_f32_e32 v17, v15, v7
	v_min_f32_e32 v7, v15, v7
	v_max_f32_e32 v15, v17, v9
	v_min_f32_e32 v9, v17, v9
	v_max_f32_e32 v17, v16, v8
	v_min_f32_e32 v8, v16, v8
	v_max_f32_e32 v16, v6, v0
	v_min_f32_e32 v0, v6, v0
	v_max_f32_e32 v6, v16, v8
	v_min_f32_e32 v8, v16, v8
	v_max_f32_e32 v16, v17, v15
	v_min_f32_e32 v15, v17, v15
	v_max_f32_e32 v17, v6, v9
	v_min_f32_e32 v9, v6, v9
	v_max_f32_e32 v6, v8, v7
	v_min_f32_e32 v7, v8, v7
	v_max_f32_e32 v8, v13, v24
	v_min_f32_e32 v24, v13, v24
	v_max_f32_e32 v13, v25, v9
	v_min_f32_e32 v9, v25, v9
	v_max_f32_e32 v25, v13, v24
	v_min_f32_e32 v24, v13, v24
	v_max_f32_e32 v13, v4, v15
	v_min_f32_e32 v15, v4, v15
	v_max_f32_e32 v4, v23, v7
	v_min_f32_e32 v7, v23, v7
	v_max_f32_e32 v23, v4, v15
	v_min_f32_e32 v15, v4, v15
	v_max_f32_e32 v4, v13, v25
	v_min_f32_e32 v25, v13, v25
	v_max_f32_e32 v13, v23, v24
	v_min_f32_e32 v24, v23, v24
	v_max_f32_e32 v23, v15, v9
	v_min_f32_e32 v9, v15, v9
	v_max_f32_e32 v15, v32, v16
	v_min_f32_e32 v16, v32, v16
	v_max_f32_e32 v32, v22, v6
	v_min_f32_e32 v6, v22, v6
	v_max_f32_e32 v22, v32, v16
	v_min_f32_e32 v16, v32, v16
	v_max_f32_e32 v32, v33, v17
	v_min_f32_e32 v17, v33, v17
	v_max_f32_e32 v33, v14, v0
	v_min_f32_e32 v0, v14, v0
	v_max_f32_e32 v14, v33, v17
	v_min_f32_e32 v17, v33, v17
	v_max_f32_e32 v33, v32, v22
	v_min_f32_e32 v22, v32, v22
	v_max_f32_e32 v32, v14, v16
	v_min_f32_e32 v16, v14, v16
	v_max_f32_e32 v14, v17, v6
	v_min_f32_e32 v6, v17, v6
	v_max_f32_e32 v17, v15, v4
	v_min_f32_e32 v4, v15, v4
	v_max_f32_e32 v15, v33, v25
	v_min_f32_e32 v25, v33, v25
	v_max_f32_e32 v33, v22, v13
	v_min_f32_e32 v13, v22, v13
	v_max_f32_e32 v22, v32, v24
	v_min_f32_e32 v24, v32, v24
	v_max_f32_e32 v32, v16, v23
	v_min_f32_e32 v23, v16, v23
	v_max_f32_e32 v16, v14, v9
	v_min_f32_e32 v9, v14, v9
	v_max_f32_e32 v14, v6, v7
	v_min_f32_e32 v7, v6, v7
	v_max_f32_e32 v3, v3, v0
	v_max_f32_e32 v12, v12, v7
	v_max_f32_e32 v30, v30, v14
	v_max_f32_e32 v10, v10, v9
	v_max_f32_e32 v20, v20, v16
	v_max_f32_e32 v28, v28, v23
	v_max_f32_e32 v180, v180, v32
	v_max_f32_e32 v29, v29, v24
	v_max_f32_e32 v19, v19, v22
	v_max_f32_e32 v27, v27, v13
	v_max_f32_e32 v18, v18, v33
	v_max_f32_e32 v11, v11, v25
	v_max_f32_e32 v26, v26, v15
	v_max_f32_e32 v21, v21, v4
	v_max_f32_e32 v2, v2, v17
	v_max_f32_e32 v31, v31, v8
	v_max_f32_e32 v6, v3, v19
	v_min_f32_e32 v19, v3, v19
	v_max_f32_e32 v3, v12, v27
	v_min_f32_e32 v27, v12, v27
	v_max_f32_e32 v12, v30, v18
	v_min_f32_e32 v18, v30, v18
	v_max_f32_e32 v30, v10, v11
	v_min_f32_e32 v11, v10, v11
	v_max_f32_e32 v10, v20, v26
	v_min_f32_e32 v26, v20, v26
	v_max_f32_e32 v20, v28, v21
	v_min_f32_e32 v21, v28, v21
	v_max_f32_e32 v28, v180, v2
	v_min_f32_e32 v2, v180, v2
	v_max_f32_e32 v180, v29, v31
	v_min_f32_e32 v31, v29, v31
	v_max_f32_e32 v29, v6, v10
	v_min_f32_e32 v10, v6, v10
	v_max_f32_e32 v6, v3, v20
	v_min_f32_e32 v20, v3, v20
	v_max_f32_e32 v3, v12, v28
	v_min_f32_e32 v28, v12, v28
	v_max_f32_e32 v12, v30, v180
	v_min_f32_e32 v180, v30, v180
	v_max_f32_e32 v30, v19, v26
	v_min_f32_e32 v26, v19, v26
	v_max_f32_e32 v19, v27, v21
	v_min_f32_e32 v21, v27, v21
	v_max_f32_e32 v27, v18, v2
	v_min_f32_e32 v2, v18, v2
	v_max_f32_e32 v18, v11, v31
	v_min_f32_e32 v31, v11, v31
	v_max_f32_e32 v11, v29, v3
	v_min_f32_e32 v3, v29, v3
	v_max_f32_e32 v29, v6, v12
	v_min_f32_e32 v12, v6, v12
	v_max_f32_e32 v6, v10, v28
	v_min_f32_e32 v28, v10, v28
	v_max_f32_e32 v10, v20, v180
	v_min_f32_e32 v180, v20, v180
	v_max_f32_e32 v20, v30, v27
	v_min_f32_e32 v27, v30, v27
	v_max_f32_e32 v30, v19, v18
	v_min_f32_e32 v18, v19, v18
	v_max_f32_e32 v19, v26, v2
	v_min_f32_e32 v2, v26, v2
	v_max_f32_e32 v26, v21, v31
	v_min_f32_e32 v31, v21, v31
	v_max_f32_e32 v164, v11, v29
	v_min_f32_e32 v165, v11, v29
	v_max_f32_e32 v166, v3, v12
	v_min_f32_e32 v167, v3, v12
	v_max_f32_e32 v168, v6, v10
	v_min_f32_e32 v169, v6, v10
	v_max_f32_e32 v170, v28, v180
	v_min_f32_e32 v171, v28, v180
	v_max_f32_e32 v172, v20, v30
	v_min_f32_e32 v173, v20, v30
	v_max_f32_e32 v174, v27, v18
	v_min_f32_e32 v175, v27, v18
	v_max_f32_e32 v176, v19, v26
	v_min_f32_e32 v177, v19, v26
	v_max_f32_e32 v178, v2, v31
	v_min_f32_e32 v179, v2, v31
	v_mbcnt_hi_u32_b32 v2, -1, v215
	v_and_b32_e32 v19, 64, v2
	v_xor_b32_e32 v18, 16, v2
	v_add_u32_e32 v19, 64, v19
	v_cmp_lt_i32_e32 vcc, v18, v19
	s_add_u32 s14, s12, s14
	s_addc_u32 s15, s13, s15
	v_cndmask_b32_e32 v18, v2, v18, vcc
	v_lshlrev_b32_e32 v95, 2, v18
	ds_bpermute_b32 v18, v95, v179
	ds_bpermute_b32 v20, v95, v178
	ds_bpermute_b32 v21, v95, v177
	ds_bpermute_b32 v22, v95, v176
	ds_bpermute_b32 v23, v95, v175
	ds_bpermute_b32 v24, v95, v174
	s_waitcnt lgkmcnt(5)
; DEV int tidx() { int t = threadIdx.x; asm volatile("" : "+v"(t)); return t; }
; DEV f32x4 mfma16(bf16x8 a, bf16x8 b, f32x4 c) { return __builtin_amdgcn_mfma_f32_16x16x32_bf16(a, b, c, 0, 0, 0); }
; DEV void merge_xor(float (&l)[16], int mask) {
;   float t[16];
; #pragma unroll
;   for (int i = 0; i < 16; i++) t[i] = __shfl_xor(l[15 - i], mask);
; #pragma unroll
;   for (int i = 0; i < 16; i++) l[i] = fmaxf(l[i], t[i]);
;   bitonic16(l);
; }
; DEV void peer_top16(const bf16_t* __restrict__ pq, const bf16_t* sk  , float (&l)[16]) {
;   const int lane = tidx() & 63, l15 = lane & 15, quad = lane >> 4;
;   f32x4 acc[8];
; #pragma unroll
;   for (int nt = 0; nt < 8; nt++) acc[nt] = (f32x4){0.f, 0.f, 0.f, 0.f};
; #pragma unroll 1
;   for (int ks = 0; ks < 4; ks++) {
;     const bf16x8 bqk = *(const bf16x8*)(pq + ks * 32 + quad * 8);
; #pragma unroll
;     for (int nt = 0; nt < 8; nt++) {
;       bf16x8 ak = *(const bf16x8*)(sk + (nt * 16 + l15) * 144 + ks * 32 + quad * 8);
;       acc[nt] = mfma16(ak, bqk, acc[nt]);
;     }
;   }
;   float hi[16];
; #pragma unroll
;   for (int nt = 0; nt < 4; nt++)
; #pragma unroll
;     for (int r = 0; r < 4; r++) {
;       l[nt * 4 + r] = __uint_as_float((__float_as_uint(acc[nt][r]) & ~127u) | (unsigned)(nt * 16 + quad * 4 + r));
;       hi[nt * 4 + r] = __uint_as_float((__float_as_uint(acc[nt + 4][r]) & ~127u) | (unsigned)((nt + 4) * 16 + quad * 4 + r));
;     }
;   sort16_desc(l);
;   sort16_desc(hi);
; #pragma unroll
;   for (int i = 0; i < 16; i++) l[i] = fmaxf(l[i], hi[15 - i]);
;   bitonic16(l);
;   merge_xor(l, 16);
;   merge_xor(l, 32);
	ds_bpermute_b32 v25, v95, v173
	ds_bpermute_b32 v39, v95, v164
	v_max_f32_e32 v3, v164, v18
	s_waitcnt lgkmcnt(6)
	ds_bpermute_b32 v26, v95, v172
	ds_bpermute_b32 v33, v95, v165
	v_max_f32_e32 v9, v165, v20
	s_waitcnt lgkmcnt(7)
	ds_bpermute_b32 v27, v95, v171
	ds_bpermute_b32 v32, v95, v166
	v_max_f32_e32 v17, v166, v21
	s_waitcnt lgkmcnt(8)
	ds_bpermute_b32 v28, v95, v170
	ds_bpermute_b32 v31, v95, v167
	v_max_f32_e32 v11, v167, v22
	s_waitcnt lgkmcnt(9)
	ds_bpermute_b32 v29, v95, v169
	ds_bpermute_b32 v30, v95, v168
	v_max_f32_e32 v13, v168, v23
	s_waitcnt lgkmcnt(10)
	v_max_f32_e32 v10, v169, v24
	s_waitcnt lgkmcnt(9)
	v_max_f32_e32 v16, v170, v25
	s_waitcnt lgkmcnt(7)
	v_max_f32_e32 v5, v171, v26
	s_waitcnt lgkmcnt(5)
	v_max_f32_e32 v7, v172, v27
	s_waitcnt lgkmcnt(3)
	v_max_f32_e32 v14, v173, v28
	s_waitcnt lgkmcnt(1)
	v_max_f32_e32 v15, v174, v29
	s_waitcnt lgkmcnt(0)
	v_max_f32_e32 v4, v175, v30
	v_max_f32_e32 v12, v176, v31
	v_max_f32_e32 v6, v177, v32
	v_max_f32_e32 v8, v178, v33
	v_max_f32_e32 v0, v179, v39
	v_max_f32_e32 v18, v3, v7
	v_min_f32_e32 v3, v3, v7
	v_max_f32_e32 v7, v9, v14
	v_min_f32_e32 v9, v9, v14
	v_max_f32_e32 v14, v17, v15
	v_min_f32_e32 v15, v17, v15
	v_max_f32_e32 v17, v11, v4
	v_min_f32_e32 v4, v11, v4
	v_max_f32_e32 v11, v13, v12
	v_min_f32_e32 v12, v13, v12
	v_max_f32_e32 v13, v10, v6
	v_min_f32_e32 v6, v10, v6
	v_max_f32_e32 v10, v16, v8
	v_min_f32_e32 v8, v16, v8
	v_max_f32_e32 v16, v5, v0
	v_min_f32_e32 v0, v5, v0
	v_max_f32_e32 v5, v18, v11
	v_min_f32_e32 v11, v18, v11
	v_max_f32_e32 v18, v7, v13
	v_min_f32_e32 v7, v7, v13
	v_max_f32_e32 v13, v14, v10
	v_min_f32_e32 v10, v14, v10
	v_max_f32_e32 v14, v17, v16
	v_min_f32_e32 v16, v17, v16
	v_max_f32_e32 v17, v3, v12
	v_min_f32_e32 v3, v3, v12
	v_max_f32_e32 v12, v9, v6
	v_min_f32_e32 v6, v9, v6
	v_max_f32_e32 v9, v15, v8
	v_min_f32_e32 v8, v15, v8
	v_max_f32_e32 v15, v4, v0
	v_min_f32_e32 v0, v4, v0
	v_max_f32_e32 v4, v5, v13
	v_min_f32_e32 v5, v5, v13
	v_max_f32_e32 v13, v18, v14
	v_min_f32_e32 v14, v18, v14
	v_max_f32_e32 v18, v11, v10
	v_min_f32_e32 v10, v11, v10
	v_max_f32_e32 v11, v7, v16
	v_min_f32_e32 v7, v7, v16
	v_max_f32_e32 v16, v17, v9
	v_min_f32_e32 v9, v17, v9
	v_max_f32_e32 v17, v12, v15
	v_min_f32_e32 v12, v12, v15
	v_max_f32_e32 v15, v3, v8
	v_min_f32_e32 v3, v3, v8
	v_max_f32_e32 v8, v6, v0
	v_min_f32_e32 v0, v6, v0
	v_max_f32_e32 v43, v3, v0
	v_min_f32_e32 v39, v3, v0
	v_xor_b32_e32 v0, 32, v2
	v_cmp_lt_i32_e32 vcc, v0, v19
	v_max_f32_e32 v109, v4, v13
	v_min_f32_e32 v107, v4, v13
	v_cndmask_b32_e32 v0, v2, v0, vcc
	v_max_f32_e32 v105, v5, v14
	v_min_f32_e32 v103, v5, v14
	v_max_f32_e32 v87, v18, v11
	v_min_f32_e32 v79, v18, v11
	v_max_f32_e32 v75, v10, v7
	v_min_f32_e32 v71, v10, v7
	v_max_f32_e32 v67, v16, v17
	v_min_f32_e32 v63, v16, v17
	v_max_f32_e32 v59, v9, v12
	v_min_f32_e32 v55, v9, v12
	v_max_f32_e32 v51, v15, v8
	v_min_f32_e32 v47, v15, v8
	v_lshlrev_b32_e32 v99, 2, v0
	v_mov_b32_e32 v0, v195
	ds_bpermute_b32 v121, v99, v39
	ds_bpermute_b32 v120, v99, v43
	ds_bpermute_b32 v119, v99, v47
	ds_bpermute_b32 v118, v99, v51
	ds_bpermute_b32 v116, v99, v55
	ds_bpermute_b32 v115, v99, v59
	ds_bpermute_b32 v114, v99, v63
	ds_bpermute_b32 v113, v99, v67
	ds_bpermute_b32 v112, v99, v71
	ds_bpermute_b32 v111, v99, v75
	ds_bpermute_b32 v110, v99, v79
	ds_bpermute_b32 v108, v99, v87
	ds_bpermute_b32 v106, v99, v103
	ds_bpermute_b32 v104, v99, v105
	ds_bpermute_b32 v91, v99, v107
	ds_bpermute_b32 v83, v99, v109
	s_mov_b32 s0, 0
	v_bfe_u32 v102, v0, 4, 2
	v_and_b32_e32 v2, 15, v0
	v_lshlrev_b32_e32 v0, 4, v102
	v_mad_u32_u24 v122, v2, s20, v0
	v_lshl_add_u64 v[2:3], v[100:101], 0, v[0:1]
	v_lshl_add_u64 v[100:101], s[14:15], 0, v[2:3]
	v_mov_b32_e32 v2, 0
	v_mov_b32_e32 v3, v2
	v_mov_b32_e32 v4, v2
	v_mov_b32_e32 v5, v2
	v_mov_b32_e32 v10, v2
	v_mov_b32_e32 v11, v2
	v_mov_b32_e32 v12, v2
	v_mov_b32_e32 v13, v2
	v_mov_b32_e32 v18, v2
	v_mov_b32_e32 v19, v2
	v_mov_b32_e32 v20, v2
	v_mov_b32_e32 v21, v2
	v_mov_b32_e32 v26, v2
	v_mov_b32_e32 v27, v2
	v_mov_b32_e32 v28, v2
	v_mov_b32_e32 v29, v2
	v_mov_b32_e32 v6, v2
	v_mov_b32_e32 v7, v2
	v_mov_b32_e32 v8, v2
	v_mov_b32_e32 v9, v2
	v_mov_b32_e32 v14, v2
	v_mov_b32_e32 v15, v2
	v_mov_b32_e32 v16, v2
	v_mov_b32_e32 v17, v2
	v_mov_b32_e32 v22, v2
	v_mov_b32_e32 v23, v2
	v_mov_b32_e32 v24, v2
	v_mov_b32_e32 v25, v2
	v_mov_b32_e32 v30, v2
	v_mov_b32_e32 v31, v2
	v_mov_b32_e32 v32, v2
	v_mov_b32_e32 v33, v2
; DEV f32x4 mfma16(bf16x8 a, bf16x8 b, f32x4 c) { return __builtin_amdgcn_mfma_f32_16x16x32_bf16(a, b, c, 0, 0, 0); }
; DEV void peer_top16(const bf16_t* __restrict__ pq, const bf16_t* sk  , float (&l)[16]) {
;     ...
; #pragma unroll 1
;   for (int ks = 0; ks < 4; ks++) {
;     const bf16x8 bqk = *(const bf16x8*)(pq + ks * 32 + quad * 8);
; #pragma unroll
;     for (int nt = 0; nt < 8; nt++) {
;       bf16x8 ak = *(const bf16x8*)(sk + (nt * 16 + l15) * 144 + ks * 32 + quad * 8);
;       acc[nt] = mfma16(ak, bqk, acc[nt]);
;     }
;   }
.LBB0_170:
	v_add_u32_e32 v139, 0x10e00, v122
	ds_read_b128 v[164:167], v122 offset:36864
	ds_read_b128 v[168:171], v122 offset:41472
	ds_read_b128 v[172:175], v122 offset:46080
	ds_read_b128 v[176:179], v122 offset:50688
	ds_read_b128 v[180:183], v122 offset:55296
	ds_read_b128 v[184:187], v122 offset:59904
	ds_read_b128 v[188:191], v122 offset:64512
	ds_read_b128 v[128:131], v139
	s_waitcnt vmcnt(3) lgkmcnt(7)
	v_mfma_f32_16x16x32_bf16 v[30:33], v[164:167], v[148:151], v[30:33]
	ds_read_b128 v[164:167], v122 offset:36928
	s_waitcnt lgkmcnt(7)
	v_mfma_f32_16x16x32_bf16 v[22:25], v[168:171], v[148:151], v[22:25]
	ds_read_b128 v[168:171], v122 offset:41536
	s_waitcnt lgkmcnt(7)
	v_mfma_f32_16x16x32_bf16 v[14:17], v[172:175], v[148:151], v[14:17]
	ds_read_b128 v[172:175], v122 offset:46144
	s_waitcnt lgkmcnt(7)
	v_mfma_f32_16x16x32_bf16 v[6:9], v[176:179], v[148:151], v[6:9]
	ds_read_b128 v[176:179], v122 offset:50752
	s_waitcnt lgkmcnt(7)
	v_mfma_f32_16x16x32_bf16 v[26:29], v[180:183], v[148:151], v[26:29]
	ds_read_b128 v[180:183], v122 offset:55360
	s_waitcnt lgkmcnt(7)
	v_mfma_f32_16x16x32_bf16 v[18:21], v[184:187], v[148:151], v[18:21]
	ds_read_b128 v[184:187], v122 offset:59968
	s_waitcnt lgkmcnt(7)
	v_mfma_f32_16x16x32_bf16 v[10:13], v[188:191], v[148:151], v[10:13]
	ds_read_b128 v[188:191], v122 offset:64576
	s_waitcnt lgkmcnt(7)
	v_mfma_f32_16x16x32_bf16 v[2:5], v[128:131], v[148:151], v[2:5]
	ds_read_b128 v[128:131], v139 offset:64
	s_waitcnt vmcnt(2) lgkmcnt(7)
	v_mfma_f32_16x16x32_bf16 v[30:33], v[164:167], v[152:155], v[30:33]
	ds_read_b128 v[164:167], v122 offset:36992
	s_waitcnt lgkmcnt(7)
	v_mfma_f32_16x16x32_bf16 v[22:25], v[168:171], v[152:155], v[22:25]
	ds_read_b128 v[168:171], v122 offset:41600
	s_waitcnt lgkmcnt(7)
	v_mfma_f32_16x16x32_bf16 v[14:17], v[172:175], v[152:155], v[14:17]
	ds_read_b128 v[172:175], v122 offset:46208
	s_waitcnt lgkmcnt(7)
	v_mfma_f32_16x16x32_bf16 v[6:9], v[176:179], v[152:155], v[6:9]
	ds_read_b128 v[176:179], v122 offset:50816
	s_waitcnt lgkmcnt(7)
	v_mfma_f32_16x16x32_bf16 v[26:29], v[180:183], v[152:155], v[26:29]
	ds_read_b128 v[180:183], v122 offset:55424
	s_waitcnt lgkmcnt(7)
	v_mfma_f32_16x16x32_bf16 v[18:21], v[184:187], v[152:155], v[18:21]
	ds_read_b128 v[184:187], v122 offset:60032
	s_waitcnt lgkmcnt(7)
	v_mfma_f32_16x16x32_bf16 v[10:13], v[188:191], v[152:155], v[10:13]
	ds_read_b128 v[188:191], v122 offset:64640
	s_waitcnt lgkmcnt(7)
	v_mfma_f32_16x16x32_bf16 v[2:5], v[128:131], v[152:155], v[2:5]
	ds_read_b128 v[128:131], v139 offset:128
	s_waitcnt vmcnt(1) lgkmcnt(7)
	v_mfma_f32_16x16x32_bf16 v[30:33], v[164:167], v[156:159], v[30:33]
	ds_read_b128 v[164:167], v122 offset:37056
	s_waitcnt lgkmcnt(7)
	v_mfma_f32_16x16x32_bf16 v[22:25], v[168:171], v[156:159], v[22:25]
	ds_read_b128 v[168:171], v122 offset:41664
	s_waitcnt lgkmcnt(7)
	v_mfma_f32_16x16x32_bf16 v[14:17], v[172:175], v[156:159], v[14:17]
	ds_read_b128 v[172:175], v122 offset:46272
	s_waitcnt lgkmcnt(7)
	v_mfma_f32_16x16x32_bf16 v[6:9], v[176:179], v[156:159], v[6:9]
	ds_read_b128 v[176:179], v122 offset:50880
	s_waitcnt lgkmcnt(7)
	v_mfma_f32_16x16x32_bf16 v[26:29], v[180:183], v[156:159], v[26:29]
	ds_read_b128 v[180:183], v122 offset:55488
	s_waitcnt lgkmcnt(7)
	v_mfma_f32_16x16x32_bf16 v[18:21], v[184:187], v[156:159], v[18:21]
	ds_read_b128 v[184:187], v122 offset:60096
	s_waitcnt lgkmcnt(7)
	v_mfma_f32_16x16x32_bf16 v[10:13], v[188:191], v[156:159], v[10:13]
	ds_read_b128 v[188:191], v122 offset:64704
	s_waitcnt lgkmcnt(7)
	v_mfma_f32_16x16x32_bf16 v[2:5], v[128:131], v[156:159], v[2:5]
	ds_read_b128 v[128:131], v139 offset:192
	s_waitcnt vmcnt(0) lgkmcnt(7)
	v_mfma_f32_16x16x32_bf16 v[30:33], v[164:167], v[160:163], v[30:33]
	s_waitcnt lgkmcnt(6)
	v_mfma_f32_16x16x32_bf16 v[22:25], v[168:171], v[160:163], v[22:25]
	s_waitcnt lgkmcnt(5)
	v_mfma_f32_16x16x32_bf16 v[14:17], v[172:175], v[160:163], v[14:17]
	s_waitcnt lgkmcnt(4)
	v_mfma_f32_16x16x32_bf16 v[6:9], v[176:179], v[160:163], v[6:9]
	s_waitcnt lgkmcnt(3)
	v_mfma_f32_16x16x32_bf16 v[26:29], v[180:183], v[160:163], v[26:29]
	s_waitcnt lgkmcnt(2)
	v_mfma_f32_16x16x32_bf16 v[18:21], v[184:187], v[160:163], v[18:21]
	s_waitcnt lgkmcnt(1)
	v_mfma_f32_16x16x32_bf16 v[10:13], v[188:191], v[160:163], v[10:13]
	s_waitcnt lgkmcnt(0)
; DEV f32x4 mfma16(bf16x8 a, bf16x8 b, f32x4 c) { return __builtin_amdgcn_mfma_f32_16x16x32_bf16(a, b, c, 0, 0, 0); }
; DEV void merge_xor(float (&l)[16], int mask) {
;   float t[16];
; #pragma unroll
;   for (int i = 0; i < 16; i++) t[i] = __shfl_xor(l[15 - i], mask);
; #pragma unroll
;   for (int i = 0; i < 16; i++) l[i] = fmaxf(l[i], t[i]);
;   bitonic16(l);
; DEV void peer_top16(const bf16_t* __restrict__ pq, const bf16_t* sk  , float (&l)[16]) {
;     ...
;       acc[nt] = mfma16(ak, bqk, acc[nt]);
;     }
;   }
;   float hi[16];
; #pragma unroll
;   for (int nt = 0; nt < 4; nt++)
; #pragma unroll
;     for (int r = 0; r < 4; r++) {
;       l[nt * 4 + r] = __uint_as_float((__float_as_uint(acc[nt][r]) & ~127u) | (unsigned)(nt * 16 + quad * 4 + r));
;       hi[nt * 4 + r] = __uint_as_float((__float_as_uint(acc[nt + 4][r]) & ~127u) | (unsigned)((nt + 4) * 16 + quad * 4 + r));
;     }
;   sort16_desc(l);
	v_mfma_f32_16x16x32_bf16 v[2:5], v[128:131], v[160:163], v[2:5]
	s_movk_i32 s0, 0x100
	v_max_f32_e32 v0, v109, v121
	v_max_f32_e32 v100, v107, v120
	v_max_f32_e32 v101, v105, v119
	v_max_f32_e32 v103, v103, v118
	v_max_f32_e32 v87, v87, v116
	v_max_f32_e32 v79, v79, v115
	v_max_f32_e32 v75, v75, v114
	v_max_f32_e32 v71, v71, v113
	v_max_f32_e32 v67, v67, v112
	v_max_f32_e32 v63, v63, v111
	v_max_f32_e32 v59, v59, v110
	v_max_f32_e32 v55, v55, v108
	v_max_f32_e32 v51, v51, v106
	v_max_f32_e32 v47, v47, v104
	v_max_f32_e32 v43, v43, v91
	v_max_f32_e32 v39, v39, v83
	v_max_f32_e32 v83, v0, v67
	v_min_f32_e32 v0, v0, v67
	v_max_f32_e32 v67, v100, v63
	v_min_f32_e32 v63, v100, v63
	v_max_f32_e32 v91, v101, v59
	v_min_f32_e32 v59, v101, v59
	v_max_f32_e32 v100, v103, v55
	v_min_f32_e32 v55, v103, v55
	v_max_f32_e32 v101, v87, v51
	v_min_f32_e32 v51, v87, v51
	v_max_f32_e32 v87, v79, v47
	v_min_f32_e32 v47, v79, v47
	v_max_f32_e32 v79, v75, v43
	v_min_f32_e32 v43, v75, v43
	v_max_f32_e32 v75, v71, v39
	v_min_f32_e32 v39, v71, v39
	v_max_f32_e32 v71, v83, v101
	v_min_f32_e32 v101, v83, v101
	v_max_f32_e32 v103, v67, v87
	v_min_f32_e32 v67, v67, v87
	v_max_f32_e32 v87, v91, v79
	v_min_f32_e32 v79, v91, v79
	v_max_f32_e32 v91, v100, v75
	v_min_f32_e32 v75, v100, v75
	v_max_f32_e32 v100, v0, v51
	v_min_f32_e32 v0, v0, v51
	v_max_f32_e32 v51, v63, v47
	v_max_f32_e32 v105, v59, v43
	v_min_f32_e32 v43, v59, v43
	v_max_f32_e32 v59, v55, v39
	v_min_f32_e32 v107, v101, v79
	v_min_f32_e32 v108, v67, v75
	v_min_f32_e32 v110, v51, v59
	v_max_f32_e32 v79, v101, v79
	v_max_f32_e32 v67, v67, v75
	v_max_f32_e32 v101, v100, v105
	v_max_f32_e32 v51, v51, v59
	v_min_f32_e32 v75, v79, v67
	v_min_f32_e32 v59, v101, v51
	v_max_f32_e32 v79, v79, v67
	v_max_f32_e32 v67, v101, v51
	v_lshlrev_b32_e32 v101, 2, v102
	s_movk_i32 s0, 0xff80
	v_and_or_b32 v30, v30, s0, v101
	v_and_b32_e32 v27, 0xffffff80, v27
	s_movk_i32 s0, 0x41
	v_or3_b32 v27, v101, v27, s0
	v_and_b32_e32 v28, 0xffffff80, v28
	s_movk_i32 s0, 0x42
	v_or3_b32 v28, v101, v28, s0
	v_and_b32_e32 v29, 0xffffff80, v29
	s_movk_i32 s0, 0x43
	v_or3_b32 v29, v101, v29, s0
	v_and_b32_e32 v18, 0xffffff80, v18
	s_movk_i32 s0, 0x50
	v_or3_b32 v18, v101, v18, s0
	v_and_b32_e32 v19, 0xffffff80, v19
	s_movk_i32 s0, 0x51
	v_or3_b32 v19, v101, v19, s0
	v_and_b32_e32 v20, 0xffffff80, v20
	s_movk_i32 s0, 0x52
	v_or3_b32 v20, v101, v20, s0
	v_and_b32_e32 v21, 0xffffff80, v21
	s_movk_i32 s0, 0x53
	v_or3_b32 v21, v101, v21, s0
	v_and_b32_e32 v10, 0xffffff80, v10
	s_movk_i32 s0, 0x60
	v_or3_b32 v10, v101, v10, s0
	v_and_b32_e32 v11, 0xffffff80, v11
	s_movk_i32 s0, 0x61
	v_or3_b32 v11, v101, v11, s0
	v_and_b32_e32 v12, 0xffffff80, v12
	s_movk_i32 s0, 0x62
	v_or3_b32 v12, v101, v12, s0
	v_and_b32_e32 v13, 0xffffff80, v13
	s_movk_i32 s0, 0x63
	v_or3_b32 v13, v101, v13, s0
	v_and_b32_e32 v2, 0xffffff80, v2
	s_movk_i32 s0, 0x70
	v_and_b32_e32 v26, 0xffffff80, v26
	v_and_b32_e32 v31, 0xffffff80, v31
	v_or3_b32 v2, v101, v2, s0
	v_and_b32_e32 v3, 0xffffff80, v3
	s_movk_i32 s0, 0x71
	v_or3_b32 v26, v101, v26, 64
	v_or3_b32 v31, v101, v31, 1
	v_and_b32_e32 v32, 0xffffff80, v32
	v_and_b32_e32 v33, 0xffffff80, v33
	v_and_b32_e32 v22, 0xffffff80, v22
	v_and_b32_e32 v23, 0xffffff80, v23
	v_or3_b32 v3, v101, v3, s0
	v_and_b32_e32 v4, 0xffffff80, v4
	s_movk_i32 s0, 0x72
	v_min_f32_e32 v39, v55, v39
	v_min_f32_e32 v55, v71, v87
	v_min_f32_e32 v106, v103, v91
	v_min_f32_e32 v109, v100, v105
	v_max_f32_e32 v71, v71, v87
	v_max_f32_e32 v87, v103, v91
	v_or3_b32 v32, v101, v32, 2
	v_or3_b32 v33, v101, v33, 3
	v_or3_b32 v22, v101, v22, 16
	v_or3_b32 v23, v101, v23, 17
	v_and_b32_e32 v24, 0xffffff80, v24
	v_and_b32_e32 v25, 0xffffff80, v25
	v_and_b32_e32 v14, 0xffffff80, v14
	v_and_b32_e32 v15, 0xffffff80, v15
	v_and_b32_e32 v16, 0xffffff80, v16
	v_and_b32_e32 v17, 0xffffff80, v17
	v_and_b32_e32 v6, 0xffffff80, v6
	v_and_b32_e32 v7, 0xffffff80, v7
	v_and_b32_e32 v8, 0xffffff80, v8
	v_or3_b32 v4, v101, v4, s0
	v_and_b32_e32 v9, 0xffffff80, v9
	v_and_b32_e32 v5, 0xffffff80, v5
	s_movk_i32 s0, 0x73
	v_min_f32_e32 v104, v63, v47
	v_min_f32_e32 v83, v55, v106
	v_min_f32_e32 v47, v109, v110
	v_min_f32_e32 v91, v71, v87
	v_max_f32_e32 v100, v71, v87
	v_max_f32_e32 v87, v55, v106
	v_max_f32_e32 v55, v109, v110
	v_or3_b32 v24, v101, v24, 18
	v_or3_b32 v25, v101, v25, 19
	v_or3_b32 v14, v101, v14, 32
	v_or3_b32 v15, v101, v15, 33
	v_or3_b32 v16, v101, v16, 34
	v_or3_b32 v17, v101, v17, 35
	v_or3_b32 v6, v101, v6, 48
	v_or3_b32 v7, v101, v7, 49
	v_or3_b32 v8, v101, v8, 50
	v_or3_b32 v9, v101, v9, 51
	v_or3_b32 v5, v101, v5, s0
	v_max_f32_e32 v180, v30, v27
	v_min_f32_e32 v27, v30, v27
	v_max_f32_e32 v30, v28, v29
	v_min_f32_e32 v29, v28, v29
	v_max_f32_e32 v28, v180, v30
	v_min_f32_e32 v30, v180, v30
	v_max_f32_e32 v180, v27, v29
	v_min_f32_e32 v29, v27, v29
	v_max_f32_e32 v27, v180, v30
	v_min_f32_e32 v30, v180, v30
	v_max_f32_e32 v180, v18, v19
	v_min_f32_e32 v19, v18, v19
	v_max_f32_e32 v18, v20, v21
	v_min_f32_e32 v21, v20, v21
	v_max_f32_e32 v20, v180, v18
	v_min_f32_e32 v18, v180, v18
	v_max_f32_e32 v180, v19, v21
	v_min_f32_e32 v21, v19, v21
	v_max_f32_e32 v19, v180, v18
	v_min_f32_e32 v18, v180, v18
	v_max_f32_e32 v180, v28, v20
	v_min_f32_e32 v20, v28, v20
	v_max_f32_e32 v28, v30, v18
	v_min_f32_e32 v18, v30, v18
	v_max_f32_e32 v30, v28, v20
	v_min_f32_e32 v20, v28, v20
	v_max_f32_e32 v28, v27, v19
	v_min_f32_e32 v19, v27, v19
	v_max_f32_e32 v27, v29, v21
	v_min_f32_e32 v21, v29, v21
	v_max_f32_e32 v29, v27, v19
	v_min_f32_e32 v19, v27, v19
	v_max_f32_e32 v27, v28, v30
	v_min_f32_e32 v30, v28, v30
	v_max_f32_e32 v28, v29, v20
	v_min_f32_e32 v20, v29, v20
; DEV void ce(float& a, float& b) { float hi = fmaxf(a, b), lo = fminf(a, b); a = hi; b = lo; }
; DEV void sort16_desc(float (&a)[16]) {
; #pragma unroll
;   for (int k = 2; k <= 16; k <<= 1)
; #pragma unroll
;     for (int j = k >> 1; j > 0; j >>= 1)
; #pragma unroll
;       for (int i = 0; i < 16; i++) {
;         const int p = i ^ j;
;         if (p > i) { if ((i & k) == 0) ce(a[i], a[p]); else ce(a[p], a[i]); }
;       }
; }
; DEV void peer_top16(const bf16_t* __restrict__ pq, const bf16_t* sk  , float (&l)[16]) {
;     ...
;   sort16_desc(l);
;   sort16_desc(hi);
	v_max_f32_e32 v29, v19, v18
	v_min_f32_e32 v18, v19, v18
	v_max_f32_e32 v19, v10, v11
	v_min_f32_e32 v11, v10, v11
	v_max_f32_e32 v10, v12, v13
	v_min_f32_e32 v13, v12, v13
	v_max_f32_e32 v12, v19, v10
	v_min_f32_e32 v10, v19, v10
	v_max_f32_e32 v19, v11, v13
	v_min_f32_e32 v13, v11, v13
	v_max_f32_e32 v11, v19, v10
	v_min_f32_e32 v10, v19, v10
	v_max_f32_e32 v19, v2, v26
	v_min_f32_e32 v26, v2, v26
	v_max_f32_e32 v2, v31, v3
	v_min_f32_e32 v3, v31, v3
	v_max_f32_e32 v31, v19, v2
	v_min_f32_e32 v2, v19, v2
	v_max_f32_e32 v19, v26, v3
	v_min_f32_e32 v3, v26, v3
	v_max_f32_e32 v26, v19, v2
	v_min_f32_e32 v2, v19, v2
	v_max_f32_e32 v19, v12, v31
	v_min_f32_e32 v31, v12, v31
	v_max_f32_e32 v12, v10, v2
	v_min_f32_e32 v2, v10, v2
	v_max_f32_e32 v10, v12, v31
	v_min_f32_e32 v31, v12, v31
	v_max_f32_e32 v12, v11, v26
	v_min_f32_e32 v26, v11, v26
	v_max_f32_e32 v11, v13, v3
	v_min_f32_e32 v3, v13, v3
	v_max_f32_e32 v13, v11, v26
	v_min_f32_e32 v26, v11, v26
	v_max_f32_e32 v11, v12, v10
	v_min_f32_e32 v10, v12, v10
	v_max_f32_e32 v12, v13, v31
	v_min_f32_e32 v31, v13, v31
	v_max_f32_e32 v13, v26, v2
	v_min_f32_e32 v2, v26, v2
	v_max_f32_e32 v26, v180, v19
	v_min_f32_e32 v19, v180, v19
	v_max_f32_e32 v180, v20, v31
	v_min_f32_e32 v31, v20, v31
	v_max_f32_e32 v20, v180, v19
	v_min_f32_e32 v19, v180, v19
	v_max_f32_e32 v180, v30, v10
	v_min_f32_e32 v10, v30, v10
	v_max_f32_e32 v30, v18, v2
	v_min_f32_e32 v2, v18, v2
	v_max_f32_e32 v18, v30, v10
	v_min_f32_e32 v10, v30, v10
	v_max_f32_e32 v30, v180, v20
	v_min_f32_e32 v20, v180, v20
	v_max_f32_e32 v180, v18, v19
	v_min_f32_e32 v19, v18, v19
	v_max_f32_e32 v18, v10, v31
	v_min_f32_e32 v31, v10, v31
	v_max_f32_e32 v10, v27, v11
	v_min_f32_e32 v11, v27, v11
	v_max_f32_e32 v27, v29, v13
	v_min_f32_e32 v13, v29, v13
	v_max_f32_e32 v29, v27, v11
	v_min_f32_e32 v11, v27, v11
	v_max_f32_e32 v27, v28, v12
	v_min_f32_e32 v12, v28, v12
	v_max_f32_e32 v28, v21, v3
	v_min_f32_e32 v3, v21, v3
	v_max_f32_e32 v21, v28, v12
	v_min_f32_e32 v12, v28, v12
	v_max_f32_e32 v28, v27, v29
	v_min_f32_e32 v29, v27, v29
	v_max_f32_e32 v27, v21, v11
	v_min_f32_e32 v11, v21, v11
	v_max_f32_e32 v21, v12, v13
	v_min_f32_e32 v13, v12, v13
	v_max_f32_e32 v12, v10, v30
	v_min_f32_e32 v30, v10, v30
	v_max_f32_e32 v10, v28, v20
	v_min_f32_e32 v20, v28, v20
	v_max_f32_e32 v28, v29, v180
	v_min_f32_e32 v180, v29, v180
	v_max_f32_e32 v29, v27, v19
	v_min_f32_e32 v19, v27, v19
	v_max_f32_e32 v27, v11, v18
	v_min_f32_e32 v18, v11, v18
	v_max_f32_e32 v11, v21, v31
	v_min_f32_e32 v31, v21, v31
	v_max_f32_e32 v21, v13, v2
	v_min_f32_e32 v2, v13, v2
	v_max_f32_e32 v13, v32, v33
	v_min_f32_e32 v33, v32, v33
	v_max_f32_e32 v32, v22, v23
	v_min_f32_e32 v23, v22, v23
	v_max_f32_e32 v22, v13, v32
	v_min_f32_e32 v32, v13, v32
	v_max_f32_e32 v13, v33, v23
	v_min_f32_e32 v23, v33, v23
	v_max_f32_e32 v33, v13, v32
	v_min_f32_e32 v32, v13, v32
	v_max_f32_e32 v13, v4, v24
	v_min_f32_e32 v24, v4, v24
	v_max_f32_e32 v4, v25, v14
	v_min_f32_e32 v14, v25, v14
	v_max_f32_e32 v25, v13, v4
	v_min_f32_e32 v4, v13, v4
	v_max_f32_e32 v13, v24, v14
	v_min_f32_e32 v14, v24, v14
	v_max_f32_e32 v24, v13, v4
	v_min_f32_e32 v4, v13, v4
	v_max_f32_e32 v13, v22, v25
	v_min_f32_e32 v25, v22, v25
	v_max_f32_e32 v22, v32, v4
	v_min_f32_e32 v4, v32, v4
	v_max_f32_e32 v32, v22, v25
	v_min_f32_e32 v25, v22, v25
	v_max_f32_e32 v22, v33, v24
	v_min_f32_e32 v24, v33, v24
	v_max_f32_e32 v33, v23, v14
	v_min_f32_e32 v14, v23, v14
	v_max_f32_e32 v23, v33, v24
	v_min_f32_e32 v24, v33, v24
	v_max_f32_e32 v33, v22, v32
	v_min_f32_e32 v32, v22, v32
	v_max_f32_e32 v22, v23, v25
	v_min_f32_e32 v25, v23, v25
	v_max_f32_e32 v23, v24, v4
	v_min_f32_e32 v4, v24, v4
	v_max_f32_e32 v24, v15, v16
	v_min_f32_e32 v16, v15, v16
	v_max_f32_e32 v15, v17, v6
	v_min_f32_e32 v6, v17, v6
	v_max_f32_e32 v17, v24, v15
	v_min_f32_e32 v15, v24, v15
	v_max_f32_e32 v24, v16, v6
	v_min_f32_e32 v6, v16, v6
	v_max_f32_e32 v16, v24, v15
	v_min_f32_e32 v15, v24, v15
	v_max_f32_e32 v24, v7, v8
	v_min_f32_e32 v8, v7, v8
	v_max_f32_e32 v7, v9, v5
	v_min_f32_e32 v5, v9, v5
	v_max_f32_e32 v9, v24, v7
	v_min_f32_e32 v7, v24, v7
	v_max_f32_e32 v24, v8, v5
	v_min_f32_e32 v5, v8, v5
	v_max_f32_e32 v8, v24, v7
	v_min_f32_e32 v7, v24, v7
	v_max_f32_e32 v24, v17, v9
	v_min_f32_e32 v9, v17, v9
	v_max_f32_e32 v17, v15, v7
	v_min_f32_e32 v7, v15, v7
	v_max_f32_e32 v15, v17, v9
	v_min_f32_e32 v9, v17, v9
	v_max_f32_e32 v17, v16, v8
	v_min_f32_e32 v8, v16, v8
	v_max_f32_e32 v16, v6, v5
	v_min_f32_e32 v5, v6, v5
	v_max_f32_e32 v6, v16, v8
	v_min_f32_e32 v8, v16, v8
	v_max_f32_e32 v16, v17, v15
	v_min_f32_e32 v15, v17, v15
	v_max_f32_e32 v17, v6, v9
	v_min_f32_e32 v9, v6, v9
	v_max_f32_e32 v6, v8, v7
	v_min_f32_e32 v7, v8, v7
	v_max_f32_e32 v8, v13, v24
	v_min_f32_e32 v24, v13, v24
	v_max_f32_e32 v13, v25, v9
	v_min_f32_e32 v9, v25, v9
	v_max_f32_e32 v25, v13, v24
	v_min_f32_e32 v24, v13, v24
	v_max_f32_e32 v13, v32, v15
	v_min_f32_e32 v15, v32, v15
	v_max_f32_e32 v32, v4, v7
	v_min_f32_e32 v7, v4, v7
	v_max_f32_e32 v4, v32, v15
	v_min_f32_e32 v15, v32, v15
	v_max_f32_e32 v32, v13, v25
	v_min_f32_e32 v25, v13, v25
	v_max_f32_e32 v13, v4, v24
	v_min_f32_e32 v24, v4, v24
	v_max_f32_e32 v4, v15, v9
	v_min_f32_e32 v9, v15, v9
	v_max_f32_e32 v15, v33, v16
	v_min_f32_e32 v16, v33, v16
	v_max_f32_e32 v33, v23, v6
	v_min_f32_e32 v6, v23, v6
	v_max_f32_e32 v23, v33, v16
	v_min_f32_e32 v16, v33, v16
	v_max_f32_e32 v33, v22, v17
	v_min_f32_e32 v17, v22, v17
	v_max_f32_e32 v22, v14, v5
	v_min_f32_e32 v5, v14, v5
	v_max_f32_e32 v14, v22, v17
	v_min_f32_e32 v17, v22, v17
	v_max_f32_e32 v22, v33, v23
	v_min_f32_e32 v23, v33, v23
	v_max_f32_e32 v33, v14, v16
; DEV void ce(float& a, float& b) { float hi = fmaxf(a, b), lo = fminf(a, b); a = hi; b = lo; }
; DEV void bitonic16(float (&l)[16]) {
; #pragma unroll
;   for (int s = 8; s > 0; s >>= 1)
; #pragma unroll
;     for (int i = 0; i < 16; i++)
;       if (!(i & s)) ce(l[i], l[i + s]);
; }
; DEV void sort16_desc(float (&a)[16]) {
; #pragma unroll
;   for (int k = 2; k <= 16; k <<= 1)
; #pragma unroll
;     for (int j = k >> 1; j > 0; j >>= 1)
; #pragma unroll
;       for (int i = 0; i < 16; i++) {
;         const int p = i ^ j;
;         if (p > i) { if ((i & k) == 0) ce(a[i], a[p]); else ce(a[p], a[i]); }
;       }
; }
; DEV void merge_xor(float (&l)[16], int mask) {
;   float t[16];
; #pragma unroll
;   for (int i = 0; i < 16; i++) t[i] = __shfl_xor(l[15 - i], mask);
; #pragma unroll
;   for (int i = 0; i < 16; i++) l[i] = fmaxf(l[i], t[i]);
;   bitonic16(l);
; }
; DEV void peer_top16(const bf16_t* __restrict__ pq, const bf16_t* sk  , float (&l)[16]) {
;     ...
;   sort16_desc(l);
;   sort16_desc(hi);
; #pragma unroll
;   for (int i = 0; i < 16; i++) l[i] = fmaxf(l[i], hi[15 - i]);
;   bitonic16(l);
;   merge_xor(l, 16);
;   merge_xor(l, 32);
	v_min_f32_e32 v16, v14, v16
	v_max_f32_e32 v14, v17, v6
	v_min_f32_e32 v6, v17, v6
	v_max_f32_e32 v17, v15, v32
	v_min_f32_e32 v32, v15, v32
	v_max_f32_e32 v15, v22, v25
	v_min_f32_e32 v25, v22, v25
	v_max_f32_e32 v22, v23, v13
	v_min_f32_e32 v13, v23, v13
	v_max_f32_e32 v23, v33, v24
	v_min_f32_e32 v24, v33, v24
	v_max_f32_e32 v33, v16, v4
	v_min_f32_e32 v4, v16, v4
	v_max_f32_e32 v16, v14, v9
	v_min_f32_e32 v9, v14, v9
	v_max_f32_e32 v14, v6, v7
	v_min_f32_e32 v7, v6, v7
	v_max_f32_e32 v26, v26, v5
	v_max_f32_e32 v12, v12, v7
	v_max_f32_e32 v30, v30, v14
	v_max_f32_e32 v10, v10, v9
	v_max_f32_e32 v20, v20, v16
	v_max_f32_e32 v28, v28, v4
	v_max_f32_e32 v180, v180, v33
	v_max_f32_e32 v29, v29, v24
	v_max_f32_e32 v19, v19, v23
	v_max_f32_e32 v27, v27, v13
	v_max_f32_e32 v18, v18, v22
	v_max_f32_e32 v11, v11, v25
	v_max_f32_e32 v31, v31, v15
	v_max_f32_e32 v21, v21, v32
	v_max_f32_e32 v2, v2, v17
	v_max_f32_e32 v3, v3, v8
	v_max_f32_e32 v6, v26, v19
	v_min_f32_e32 v19, v26, v19
	v_max_f32_e32 v26, v12, v27
	v_min_f32_e32 v27, v12, v27
	v_max_f32_e32 v12, v30, v18
	v_min_f32_e32 v18, v30, v18
	v_max_f32_e32 v30, v10, v11
	v_min_f32_e32 v11, v10, v11
	v_max_f32_e32 v10, v20, v31
	v_min_f32_e32 v31, v20, v31
	v_max_f32_e32 v20, v28, v21
	v_min_f32_e32 v21, v28, v21
	v_max_f32_e32 v28, v180, v2
	v_min_f32_e32 v2, v180, v2
	v_max_f32_e32 v180, v29, v3
	v_min_f32_e32 v3, v29, v3
	v_max_f32_e32 v29, v6, v10
	v_min_f32_e32 v10, v6, v10
	v_max_f32_e32 v6, v26, v20
	v_min_f32_e32 v20, v26, v20
	v_max_f32_e32 v26, v12, v28
	v_min_f32_e32 v28, v12, v28
	v_max_f32_e32 v12, v30, v180
	v_min_f32_e32 v180, v30, v180
	v_max_f32_e32 v30, v19, v31
	v_min_f32_e32 v31, v19, v31
	v_max_f32_e32 v19, v27, v21
	v_min_f32_e32 v21, v27, v21
	v_max_f32_e32 v27, v18, v2
	v_min_f32_e32 v2, v18, v2
	v_max_f32_e32 v18, v11, v3
	v_min_f32_e32 v3, v11, v3
	v_max_f32_e32 v11, v29, v26
	v_min_f32_e32 v26, v29, v26
	v_max_f32_e32 v29, v6, v12
	v_min_f32_e32 v12, v6, v12
	v_max_f32_e32 v6, v10, v28
	v_min_f32_e32 v28, v10, v28
	v_max_f32_e32 v10, v20, v180
	v_min_f32_e32 v180, v20, v180
	v_max_f32_e32 v20, v30, v27
	v_min_f32_e32 v27, v30, v27
	v_max_f32_e32 v30, v19, v18
	v_min_f32_e32 v18, v19, v18
	v_max_f32_e32 v19, v31, v2
	v_min_f32_e32 v2, v31, v2
	v_max_f32_e32 v31, v21, v3
	v_min_f32_e32 v3, v21, v3
	v_max_f32_e32 v164, v11, v29
	v_min_f32_e32 v165, v11, v29
	v_max_f32_e32 v166, v26, v12
	v_min_f32_e32 v167, v26, v12
	v_max_f32_e32 v168, v6, v10
	v_min_f32_e32 v169, v6, v10
	v_max_f32_e32 v170, v28, v180
	v_min_f32_e32 v171, v28, v180
	v_max_f32_e32 v172, v20, v30
	v_min_f32_e32 v173, v20, v30
	v_max_f32_e32 v174, v27, v18
	v_min_f32_e32 v175, v27, v18
	v_max_f32_e32 v176, v19, v31
	v_min_f32_e32 v177, v19, v31
	v_max_f32_e32 v178, v2, v3
	v_min_f32_e32 v179, v2, v3
	v_max_f32_e32 v111, v0, v43
	v_min_f32_e32 v112, v104, v39
	v_max_f32_e32 v103, v104, v39
	v_min_f32_e32 v0, v0, v43
	v_min_f32_e32 v63, v107, v108
	v_min_f32_e32 v39, v111, v103
	v_max_f32_e32 v71, v107, v108
	v_max_f32_e32 v51, v111, v103
	v_max_f32_e32 v43, v0, v112
	v_min_f32_e32 v0, v0, v112
	ds_bpermute_b32 v3, v95, v179
	ds_bpermute_b32 v19, v95, v178
	ds_bpermute_b32 v20, v95, v177
	ds_bpermute_b32 v21, v95, v176
	ds_bpermute_b32 v22, v95, v175
	ds_bpermute_b32 v23, v95, v174
	s_waitcnt lgkmcnt(5)
	ds_bpermute_b32 v24, v95, v173
	ds_bpermute_b32 v33, v95, v164
	v_max_f32_e32 v3, v164, v3
	s_waitcnt lgkmcnt(6)
	ds_bpermute_b32 v25, v95, v172
	ds_bpermute_b32 v32, v95, v165
	v_max_f32_e32 v4, v165, v19
	s_waitcnt lgkmcnt(7)
	ds_bpermute_b32 v26, v95, v171
	ds_bpermute_b32 v31, v95, v166
	v_max_f32_e32 v9, v166, v20
	s_waitcnt lgkmcnt(8)
	ds_bpermute_b32 v27, v95, v170
	ds_bpermute_b32 v30, v95, v167
	v_max_f32_e32 v13, v167, v21
	s_waitcnt lgkmcnt(9)
	ds_bpermute_b32 v28, v95, v169
	ds_bpermute_b32 v29, v95, v168
	v_max_f32_e32 v15, v168, v22
	s_waitcnt lgkmcnt(10)
	v_max_f32_e32 v10, v169, v23
	s_waitcnt lgkmcnt(9)
	v_max_f32_e32 v17, v170, v24
	s_waitcnt lgkmcnt(7)
	v_max_f32_e32 v6, v171, v25
	s_waitcnt lgkmcnt(5)
	v_max_f32_e32 v8, v172, v26
	s_waitcnt lgkmcnt(3)
	v_max_f32_e32 v14, v173, v27
	s_waitcnt lgkmcnt(1)
	v_max_f32_e32 v16, v174, v28
	s_waitcnt lgkmcnt(0)
	v_max_f32_e32 v5, v175, v29
	v_max_f32_e32 v12, v176, v30
	v_max_f32_e32 v7, v177, v31
	v_max_f32_e32 v11, v178, v32
	v_max_f32_e32 v2, v179, v33
	v_max_f32_e32 v18, v3, v8
	v_min_f32_e32 v3, v3, v8
	v_max_f32_e32 v8, v4, v14
	v_min_f32_e32 v4, v4, v14
	v_max_f32_e32 v14, v9, v16
	v_min_f32_e32 v9, v9, v16
	v_max_f32_e32 v16, v13, v5
	v_min_f32_e32 v5, v13, v5
	v_max_f32_e32 v13, v15, v12
	v_min_f32_e32 v12, v15, v12
	v_max_f32_e32 v15, v10, v7
	v_min_f32_e32 v7, v10, v7
	v_max_f32_e32 v10, v17, v11
	v_min_f32_e32 v11, v17, v11
	v_max_f32_e32 v17, v6, v2
	v_min_f32_e32 v2, v6, v2
	v_max_f32_e32 v6, v18, v13
	v_min_f32_e32 v13, v18, v13
	v_max_f32_e32 v18, v8, v15
	v_min_f32_e32 v8, v8, v15
	v_max_f32_e32 v15, v14, v10
	v_min_f32_e32 v10, v14, v10
	v_max_f32_e32 v14, v16, v17
	v_min_f32_e32 v16, v16, v17
	v_max_f32_e32 v17, v3, v12
	v_min_f32_e32 v3, v3, v12
	v_max_f32_e32 v12, v4, v7
	v_min_f32_e32 v4, v4, v7
	v_max_f32_e32 v7, v9, v11
	v_min_f32_e32 v9, v9, v11
	v_max_f32_e32 v11, v5, v2
	v_min_f32_e32 v2, v5, v2
	v_max_f32_e32 v5, v6, v15
	v_min_f32_e32 v6, v6, v15
	v_max_f32_e32 v15, v18, v14
	v_min_f32_e32 v14, v18, v14
	v_max_f32_e32 v18, v13, v10
	v_min_f32_e32 v10, v13, v10
	v_max_f32_e32 v13, v8, v16
	v_min_f32_e32 v8, v8, v16
	v_max_f32_e32 v16, v17, v7
	v_min_f32_e32 v7, v17, v7
	v_max_f32_e32 v17, v12, v11
	v_min_f32_e32 v11, v12, v11
	v_max_f32_e32 v12, v3, v9
	v_min_f32_e32 v3, v3, v9
	v_max_f32_e32 v9, v4, v2
	v_min_f32_e32 v2, v4, v2
	v_max_f32_e32 v4, v5, v15
	v_min_f32_e32 v5, v5, v15
	v_max_f32_e32 v15, v6, v14
	v_min_f32_e32 v6, v6, v14
	v_max_f32_e32 v14, v18, v13
	v_min_f32_e32 v13, v18, v13
	v_max_f32_e32 v18, v10, v8
	v_min_f32_e32 v8, v10, v8
	v_max_f32_e32 v10, v16, v17
	v_min_f32_e32 v16, v16, v17
	v_max_f32_e32 v17, v7, v11
	v_min_f32_e32 v7, v7, v11
	v_max_f32_e32 v11, v12, v9
	v_min_f32_e32 v9, v12, v9
	v_max_f32_e32 v12, v3, v2
	v_min_f32_e32 v2, v3, v2
	ds_bpermute_b32 v3, v99, v2
	ds_bpermute_b32 v19, v99, v12
	ds_bpermute_b32 v20, v99, v9
	ds_bpermute_b32 v21, v99, v11
	ds_bpermute_b32 v22, v99, v7
	ds_bpermute_b32 v23, v99, v17
	s_waitcnt lgkmcnt(5)
; DEV void merge_xor(float (&l)[16], int mask) {
;   float t[16];
; #pragma unroll
;   for (int i = 0; i < 16; i++) t[i] = __shfl_xor(l[15 - i], mask);
; #pragma unroll
;   for (int i = 0; i < 16; i++) l[i] = fmaxf(l[i], t[i]);
;   bitonic16(l);
; }
; DEV void phase_peer_score(const Params& p, int layer, int M, char* smem) {
;     ...
;     unsigned char* tab = (unsigned char*)smem + 73728 + (w * 16 + l15) * 32;
; #pragma unroll
;     for (int i = 0; i < 16; i++) { tab[i] = (unsigned char)(__float_as_uint(L0[i]) & 127u); tab[16 + i] = (unsigned char)(__float_as_uint(L1[i]) & 127u); }
	ds_bpermute_b32 v24, v99, v16
	ds_bpermute_b32 v33, v99, v4
	v_max_f32_e32 v3, v4, v3
	s_waitcnt lgkmcnt(6)
	ds_bpermute_b32 v25, v99, v10
	ds_bpermute_b32 v32, v99, v5
	v_max_f32_e32 v4, v5, v19
	s_waitcnt lgkmcnt(7)
	ds_bpermute_b32 v26, v99, v8
	ds_bpermute_b32 v31, v99, v15
	v_max_f32_e32 v5, v15, v20
	s_waitcnt lgkmcnt(8)
	ds_bpermute_b32 v27, v99, v18
	ds_bpermute_b32 v30, v99, v6
	v_max_f32_e32 v6, v6, v21
	s_waitcnt lgkmcnt(9)
	ds_bpermute_b32 v28, v99, v13
	ds_bpermute_b32 v29, v99, v14
	v_max_f32_e32 v14, v14, v22
	s_waitcnt lgkmcnt(10)
	v_max_f32_e32 v13, v13, v23
	s_waitcnt lgkmcnt(9)
	v_max_f32_e32 v15, v18, v24
	s_waitcnt lgkmcnt(7)
	v_max_f32_e32 v8, v8, v25
	s_waitcnt lgkmcnt(5)
	v_max_f32_e32 v10, v10, v26
	s_waitcnt lgkmcnt(3)
	v_max_f32_e32 v16, v16, v27
	s_waitcnt lgkmcnt(1)
	v_max_f32_e32 v17, v17, v28
	s_waitcnt lgkmcnt(0)
	v_max_f32_e32 v7, v7, v29
	v_max_f32_e32 v11, v11, v30
	v_max_f32_e32 v9, v9, v31
	v_max_f32_e32 v12, v12, v32
	v_max_f32_e32 v2, v2, v33
	v_max_f32_e32 v18, v3, v10
	v_min_f32_e32 v3, v3, v10
	v_max_f32_e32 v10, v4, v16
	v_min_f32_e32 v4, v4, v16
	v_max_f32_e32 v16, v5, v17
	v_min_f32_e32 v5, v5, v17
	v_max_f32_e32 v17, v6, v7
	v_min_f32_e32 v6, v6, v7
	v_max_f32_e32 v7, v14, v11
	v_min_f32_e32 v11, v14, v11
	v_max_f32_e32 v14, v13, v9
	v_min_f32_e32 v9, v13, v9
	v_max_f32_e32 v13, v15, v12
	v_min_f32_e32 v12, v15, v12
	v_max_f32_e32 v15, v8, v2
	v_min_f32_e32 v2, v8, v2
	v_max_f32_e32 v8, v18, v7
	v_min_f32_e32 v7, v18, v7
	v_max_f32_e32 v18, v10, v14
	v_min_f32_e32 v10, v10, v14
	v_max_f32_e32 v14, v16, v13
	v_min_f32_e32 v13, v16, v13
	v_max_f32_e32 v16, v17, v15
	v_min_f32_e32 v15, v17, v15
	v_max_f32_e32 v17, v3, v11
	v_min_f32_e32 v3, v3, v11
	v_max_f32_e32 v11, v4, v9
	v_min_f32_e32 v4, v4, v9
	v_max_f32_e32 v9, v5, v12
	v_min_f32_e32 v5, v5, v12
	v_max_f32_e32 v12, v6, v2
	v_min_f32_e32 v2, v6, v2
	v_max_f32_e32 v6, v8, v14
	v_min_f32_e32 v8, v8, v14
	v_max_f32_e32 v14, v18, v16
	v_min_f32_e32 v16, v18, v16
	v_max_f32_e32 v18, v7, v13
	v_max_f32_e32 v19, v10, v15
	s_movk_i32 s0, 0x7f
	v_min_f32_e32 v13, v7, v13
	v_min_f32_e32 v10, v10, v15
	v_max_f32_e32 v15, v17, v9
	v_min_f32_e32 v21, v17, v9
	v_max_f32_e32 v17, v11, v12
	v_min_f32_e32 v22, v11, v12
	v_max_f32_e32 v23, v3, v5
	v_min_f32_e32 v3, v3, v5
	v_max_f32_e32 v5, v4, v2
	v_min_f32_e32 v24, v4, v2
	v_max_f32_e32 v9, v18, v19
	v_min_f32_e32 v12, v18, v19
	v_and_b32_sdwa v18, v63, s0 dst_sel:BYTE_1 dst_unused:UNUSED_PAD src0_sel:DWORD src1_sel:DWORD
	v_max_f32_e32 v2, v6, v14
	v_min_f32_e32 v4, v6, v14
	v_max_f32_e32 v11, v13, v10
	v_min_f32_e32 v10, v13, v10
	v_max_f32_e32 v14, v23, v5
	v_min_f32_e32 v13, v23, v5
	v_max_f32_e32 v6, v3, v24
	v_min_f32_e32 v5, v3, v24
	v_and_b32_sdwa v3, v75, s0 dst_sel:BYTE_1 dst_unused:UNUSED_PAD src0_sel:DWORD src1_sel:DWORD
	v_bitop3_b16 v18, v71, v18, s0 bitop3:0xec
	v_bitop3_b16 v3, v79, v3, s0 bitop3:0xec
	v_lshlrev_b32_e32 v18, 16, v18
	v_or_b32_sdwa v23, v3, v18 dst_sel:DWORD dst_unused:UNUSED_PAD src0_sel:WORD_0 src1_sel:DWORD
	v_and_b32_sdwa v18, v83, s0 dst_sel:BYTE_1 dst_unused:UNUSED_PAD src0_sel:DWORD src1_sel:DWORD
	v_and_b32_sdwa v3, v91, s0 dst_sel:BYTE_1 dst_unused:UNUSED_PAD src0_sel:DWORD src1_sel:DWORD
	v_bitop3_b16 v18, v87, v18, s0 bitop3:0xec
	v_bitop3_b16 v3, v100, v3, s0 bitop3:0xec
	v_lshlrev_b32_e32 v18, 16, v18
	v_max_f32_e32 v7, v8, v16
	v_min_f32_e32 v8, v8, v16
	v_max_f32_e32 v20, v15, v17
	v_min_f32_e32 v17, v15, v17
	v_max_f32_e32 v16, v21, v22
	v_min_f32_e32 v15, v21, v22
	v_or_b32_sdwa v22, v3, v18 dst_sel:DWORD dst_unused:UNUSED_PAD src0_sel:WORD_0 src1_sel:DWORD
	v_and_b32_sdwa v18, v10, s0 dst_sel:BYTE_1 dst_unused:UNUSED_PAD src0_sel:DWORD src1_sel:DWORD
	v_and_b32_sdwa v3, v12, s0 dst_sel:BYTE_1 dst_unused:UNUSED_PAD src0_sel:DWORD src1_sel:DWORD
	v_bitop3_b16 v18, v11, v18, s0 bitop3:0xec
	v_bitop3_b16 v3, v9, v3, s0 bitop3:0xec
	v_lshlrev_b32_e32 v18, 16, v18
	v_or_b32_sdwa v27, v3, v18 dst_sel:DWORD dst_unused:UNUSED_PAD src0_sel:WORD_0 src1_sel:DWORD
	v_and_b32_sdwa v18, v8, s0 dst_sel:BYTE_1 dst_unused:UNUSED_PAD src0_sel:DWORD src1_sel:DWORD
	v_and_b32_sdwa v3, v4, s0 dst_sel:BYTE_1 dst_unused:UNUSED_PAD src0_sel:DWORD src1_sel:DWORD
	v_bitop3_b16 v18, v7, v18, s0 bitop3:0xec
	v_bitop3_b16 v3, v2, v3, s0 bitop3:0xec
	v_lshlrev_b32_e32 v18, 16, v18
	v_or_b32_sdwa v26, v3, v18 dst_sel:DWORD dst_unused:UNUSED_PAD src0_sel:WORD_0 src1_sel:DWORD
	v_and_b32_sdwa v18, v0, s0 dst_sel:BYTE_1 dst_unused:UNUSED_PAD src0_sel:DWORD src1_sel:DWORD
	v_and_b32_sdwa v3, v39, s0 dst_sel:BYTE_1 dst_unused:UNUSED_PAD src0_sel:DWORD src1_sel:DWORD
	v_bitop3_b16 v18, v43, v18, s0 bitop3:0xec
	v_bitop3_b16 v3, v51, v3, s0 bitop3:0xec
	v_lshlrev_b32_e32 v18, 16, v18
	v_or_b32_sdwa v25, v3, v18 dst_sel:DWORD dst_unused:UNUSED_PAD src0_sel:WORD_0 src1_sel:DWORD
	v_and_b32_sdwa v18, v47, s0 dst_sel:BYTE_1 dst_unused:UNUSED_PAD src0_sel:DWORD src1_sel:DWORD
	v_and_b32_sdwa v3, v59, s0 dst_sel:BYTE_1 dst_unused:UNUSED_PAD src0_sel:DWORD src1_sel:DWORD
	v_bitop3_b16 v18, v55, v18, s0 bitop3:0xec
	v_bitop3_b16 v3, v67, v3, s0 bitop3:0xec
	v_lshlrev_b32_e32 v18, 16, v18
	v_or_b32_sdwa v24, v3, v18 dst_sel:DWORD dst_unused:UNUSED_PAD src0_sel:WORD_0 src1_sel:DWORD
	v_and_b32_sdwa v18, v5, s0 dst_sel:BYTE_1 dst_unused:UNUSED_PAD src0_sel:DWORD src1_sel:DWORD
	v_and_b32_sdwa v3, v13, s0 dst_sel:BYTE_1 dst_unused:UNUSED_PAD src0_sel:DWORD src1_sel:DWORD
	v_bitop3_b16 v18, v6, v18, s0 bitop3:0xec
	v_bitop3_b16 v3, v14, v3, s0 bitop3:0xec
	v_lshlrev_b32_e32 v18, 16, v18
	v_or_b32_sdwa v29, v3, v18 dst_sel:DWORD dst_unused:UNUSED_PAD src0_sel:WORD_0 src1_sel:DWORD
	v_and_b32_sdwa v18, v15, s0 dst_sel:BYTE_1 dst_unused:UNUSED_PAD src0_sel:DWORD src1_sel:DWORD
	v_and_b32_sdwa v3, v17, s0 dst_sel:BYTE_1 dst_unused:UNUSED_PAD src0_sel:DWORD src1_sel:DWORD
	v_bitop3_b16 v18, v16, v18, s0 bitop3:0xec
	v_bitop3_b16 v3, v20, v3, s0 bitop3:0xec
	v_lshlrev_b32_e32 v18, 16, v18
	v_or_b32_sdwa v28, v3, v18 dst_sel:DWORD dst_unused:UNUSED_PAD src0_sel:WORD_0 src1_sel:DWORD
	ds_write_b128 v138, v[22:25]
	ds_write_b128 v138, v[26:29] offset:16
	s_and_saveexec_b64 s[14:15], s[38:39]
	s_cbranch_execz .LBB0_162
; DEV void ce(float& a, float& b) { float hi = fmaxf(a, b), lo = fminf(a, b); a = hi; b = lo; }
; DEV void phase_peer_score(const Params& p, int layer, int M, char* smem) {
;     ...
;     float R[16];
; #pragma unroll
;     for (int i = 0; i < 16; i++) R[i] = -3.0e38f;
; #pragma unroll
;     for (int i = 0; i < 16; i++)
; #pragma unroll
;       for (int j = 0; j < 16; j++)
;         if ((i + 1) * (j + 1) <= 16) {
;           float v = L0[i] + L1[j];
;           v = __uint_as_float((__float_as_uint(v) & ~255u) | (unsigned)(i * 16 + j));
; #pragma unroll
;           for (int t = 0; t < 16; t++)
;             if (t >= (i + 1) * (j + 1) - 1) ce(R[t], v);
;         }
	s_movk_i32 s0, 0xff00
	v_add_f32_e32 v164, v100, v2
	v_and_or_b32 v164, v164, s0, 0
	v_max_f32_e32 v148, 0xff61b1e6, v164
	v_add_f32_e32 v164, v100, v4
	v_and_or_b32 v164, v164, s0, 1
	v_max_f32_e32 v149, 0xff61b1e6, v164
	v_add_f32_e32 v164, v100, v7
	v_and_or_b32 v164, v164, s0, 2
	v_max_f32_e32 v150, 0xff61b1e6, v164
	v_add_f32_e32 v164, v100, v8
	v_and_or_b32 v164, v164, s0, 3
	v_max_f32_e32 v151, 0xff61b1e6, v164
	v_add_f32_e32 v164, v100, v9
	v_and_or_b32 v164, v164, s0, 4
	v_max_f32_e32 v152, 0xff61b1e6, v164
	v_add_f32_e32 v164, v100, v12
	v_and_or_b32 v164, v164, s0, 5
	v_max_f32_e32 v153, 0xff61b1e6, v164
	v_add_f32_e32 v164, v100, v11
	v_and_or_b32 v164, v164, s0, 6
	v_max_f32_e32 v154, 0xff61b1e6, v164
	v_add_f32_e32 v164, v100, v10
	v_and_or_b32 v164, v164, s0, 7
	v_max_f32_e32 v155, 0xff61b1e6, v164
	v_add_f32_e32 v164, v100, v20
	v_and_or_b32 v164, v164, s0, 8
	v_max_f32_e32 v156, 0xff61b1e6, v164
	v_add_f32_e32 v164, v100, v17
	v_and_or_b32 v164, v164, s0, 9
	v_max_f32_e32 v157, 0xff61b1e6, v164
	v_add_f32_e32 v164, v100, v16
	v_and_or_b32 v164, v164, s0, 10
	v_max_f32_e32 v158, 0xff61b1e6, v164
	v_add_f32_e32 v164, v100, v15
	v_and_or_b32 v164, v164, s0, 11
	v_max_f32_e32 v159, 0xff61b1e6, v164
	v_add_f32_e32 v164, v100, v14
	v_and_or_b32 v164, v164, s0, 12
	v_max_f32_e32 v160, 0xff61b1e6, v164
	v_add_f32_e32 v164, v100, v13
	v_and_or_b32 v164, v164, s0, 13
	v_max_f32_e32 v161, 0xff61b1e6, v164
	v_add_f32_e32 v164, v100, v6
	v_and_or_b32 v164, v164, s0, 14
	v_max_f32_e32 v162, 0xff61b1e6, v164
	v_add_f32_e32 v164, v100, v5
	v_and_or_b32 v164, v164, s0, 15
	v_max_f32_e32 v163, 0xff61b1e6, v164
	v_min_f32_e32 v164, v148, v149
	v_max_f32_e32 v148, v148, v149
	v_min_f32_e32 v149, v164, v150
	v_max_f32_e32 v164, v164, v150
	v_min_f32_e32 v150, v149, v151
	v_max_f32_e32 v149, v149, v151
	v_min_f32_e32 v151, v150, v152
	v_max_f32_e32 v150, v150, v152
	v_min_f32_e32 v152, v151, v153
	v_max_f32_e32 v151, v151, v153
	v_min_f32_e32 v153, v152, v154
	v_max_f32_e32 v152, v152, v154
	v_min_f32_e32 v154, v153, v155
	v_max_f32_e32 v153, v153, v155
	v_min_f32_e32 v155, v154, v156
	v_max_f32_e32 v154, v154, v156
	v_min_f32_e32 v156, v155, v157
	v_max_f32_e32 v155, v155, v157
	v_min_f32_e32 v157, v156, v158
	v_max_f32_e32 v156, v156, v158
	v_min_f32_e32 v158, v157, v159
	v_max_f32_e32 v157, v157, v159
	v_min_f32_e32 v159, v158, v160
	v_max_f32_e32 v158, v158, v160
	v_min_f32_e32 v160, v159, v161
	v_max_f32_e32 v159, v159, v161
	v_min_f32_e32 v161, v160, v162
	v_max_f32_e32 v160, v160, v162
	v_min_f32_e32 v162, v161, v163
	v_max_f32_e32 v161, v161, v163
	v_add_f32_e32 v163, v91, v2
	v_and_or_b32 v163, v163, s0, 16
	v_med3_f32 v162, v161, v162, v163
	v_med3_f32 v161, v160, v161, v163
	v_med3_f32 v160, v159, v160, v163
	v_med3_f32 v159, v158, v159, v163
	v_med3_f32 v158, v157, v158, v163
	v_med3_f32 v157, v156, v157, v163
	v_med3_f32 v156, v155, v156, v163
	v_med3_f32 v155, v154, v155, v163
	v_med3_f32 v154, v153, v154, v163
	v_med3_f32 v153, v152, v153, v163
	v_med3_f32 v152, v151, v152, v163
	v_med3_f32 v151, v150, v151, v163
	v_med3_f32 v150, v149, v150, v163
	v_med3_f32 v149, v164, v149, v163
	v_med3_f32 v164, v148, v164, v163
	v_max_f32_e32 v148, v148, v163
	v_add_f32_e32 v163, v91, v4
	v_and_or_b32 v163, v163, s0, 17
	v_med3_f32 v162, v161, v162, v163
	v_med3_f32 v161, v160, v161, v163
	v_med3_f32 v160, v159, v160, v163
	v_med3_f32 v159, v158, v159, v163
	v_med3_f32 v158, v157, v158, v163
	v_med3_f32 v157, v156, v157, v163
	v_med3_f32 v156, v155, v156, v163
	v_med3_f32 v155, v154, v155, v163
	v_med3_f32 v154, v153, v154, v163
	v_med3_f32 v153, v152, v153, v163
	v_med3_f32 v152, v151, v152, v163
	v_med3_f32 v151, v150, v151, v163
	v_med3_f32 v150, v149, v150, v163
	v_max_f32_e32 v149, v149, v163
	v_add_f32_e32 v163, v91, v7
	v_and_or_b32 v163, v163, s0, 18
	v_med3_f32 v162, v161, v162, v163
	v_med3_f32 v161, v160, v161, v163
	v_med3_f32 v160, v159, v160, v163
	v_med3_f32 v159, v158, v159, v163
	v_med3_f32 v158, v157, v158, v163
	v_med3_f32 v157, v156, v157, v163
	v_med3_f32 v156, v155, v156, v163
	v_med3_f32 v155, v154, v155, v163
	v_med3_f32 v154, v153, v154, v163
	v_med3_f32 v153, v152, v153, v163
	v_med3_f32 v152, v151, v152, v163
	v_max_f32_e32 v151, v151, v163
	v_add_f32_e32 v163, v91, v8
	v_and_or_b32 v163, v163, s0, 19
	v_med3_f32 v162, v161, v162, v163
	v_med3_f32 v161, v160, v161, v163
	v_med3_f32 v160, v159, v160, v163
	v_med3_f32 v159, v158, v159, v163
	v_med3_f32 v158, v157, v158, v163
	v_med3_f32 v157, v156, v157, v163
	v_med3_f32 v156, v155, v156, v163
	v_med3_f32 v155, v154, v155, v163
	v_med3_f32 v154, v153, v154, v163
	v_max_f32_e32 v153, v153, v163
	v_add_f32_e32 v163, v91, v9
	v_and_or_b32 v163, v163, s0, 20
	v_med3_f32 v162, v161, v162, v163
	v_med3_f32 v161, v160, v161, v163
	v_med3_f32 v160, v159, v160, v163
	v_med3_f32 v159, v158, v159, v163
	v_med3_f32 v158, v157, v158, v163
	v_med3_f32 v157, v156, v157, v163
	v_med3_f32 v156, v155, v156, v163
	v_max_f32_e32 v155, v155, v163
	v_add_f32_e32 v163, v91, v12
	v_and_or_b32 v163, v163, s0, 21
	v_med3_f32 v162, v161, v162, v163
	v_med3_f32 v161, v160, v161, v163
	v_med3_f32 v160, v159, v160, v163
	v_med3_f32 v159, v158, v159, v163
	v_med3_f32 v158, v157, v158, v163
	v_max_f32_e32 v157, v157, v163
	v_add_f32_e32 v163, v91, v11
	v_and_or_b32 v163, v163, s0, 22
	v_med3_f32 v162, v161, v162, v163
	v_med3_f32 v161, v160, v161, v163
	v_med3_f32 v160, v159, v160, v163
	v_max_f32_e32 v159, v159, v163
	v_add_f32_e32 v163, v91, v10
	v_and_or_b32 v163, v163, s0, 23
	v_med3_f32 v162, v161, v162, v163
	v_max_f32_e32 v161, v161, v163
	v_add_f32_e32 v163, v87, v2
	v_and_or_b32 v163, v163, s0, 32
; DEV void ce(float& a, float& b) { float hi = fmaxf(a, b), lo = fminf(a, b); a = hi; b = lo; }
; DEV void phase_peer_score(const Params& p, int layer, int M, char* smem) {
;     ...
;     float R[16];
; #pragma unroll
;     for (int i = 0; i < 16; i++) R[i] = -3.0e38f;
; #pragma unroll
;     for (int i = 0; i < 16; i++)
; #pragma unroll
;       for (int j = 0; j < 16; j++)
;         if ((i + 1) * (j + 1) <= 16) {
;           float v = L0[i] + L1[j];
;           v = __uint_as_float((__float_as_uint(v) & ~255u) | (unsigned)(i * 16 + j));
; #pragma unroll
;           for (int t = 0; t < 16; t++)
;             if (t >= (i + 1) * (j + 1) - 1) ce(R[t], v);
;         }
	v_med3_f32 v162, v161, v162, v163
	v_med3_f32 v161, v160, v161, v163
	v_med3_f32 v160, v159, v160, v163
	v_med3_f32 v159, v158, v159, v163
	v_med3_f32 v158, v157, v158, v163
	v_med3_f32 v157, v156, v157, v163
	v_med3_f32 v156, v155, v156, v163
	v_med3_f32 v155, v154, v155, v163
	v_med3_f32 v154, v153, v154, v163
	v_med3_f32 v153, v152, v153, v163
	v_med3_f32 v152, v151, v152, v163
	v_med3_f32 v151, v150, v151, v163
	v_med3_f32 v150, v149, v150, v163
	v_med3_f32 v149, v164, v149, v163
	v_max_f32_e32 v164, v164, v163
	v_add_f32_e32 v163, v87, v4
	v_and_or_b32 v163, v163, s0, 33
	v_med3_f32 v162, v161, v162, v163
	v_med3_f32 v161, v160, v161, v163
	v_med3_f32 v160, v159, v160, v163
	v_med3_f32 v159, v158, v159, v163
	v_med3_f32 v158, v157, v158, v163
	v_med3_f32 v157, v156, v157, v163
	v_med3_f32 v156, v155, v156, v163
	v_med3_f32 v155, v154, v155, v163
	v_med3_f32 v154, v153, v154, v163
	v_med3_f32 v153, v152, v153, v163
	v_med3_f32 v152, v151, v152, v163
	v_max_f32_e32 v151, v151, v163
	v_add_f32_e32 v163, v87, v7
	v_and_or_b32 v163, v163, s0, 34
	v_med3_f32 v162, v161, v162, v163
	v_med3_f32 v161, v160, v161, v163
	v_med3_f32 v160, v159, v160, v163
	v_med3_f32 v159, v158, v159, v163
	v_med3_f32 v158, v157, v158, v163
	v_med3_f32 v157, v156, v157, v163
	v_med3_f32 v156, v155, v156, v163
	v_med3_f32 v155, v154, v155, v163
	v_max_f32_e32 v154, v154, v163
	v_add_f32_e32 v163, v87, v8
	v_and_or_b32 v163, v163, s0, 35
	v_med3_f32 v162, v161, v162, v163
	v_med3_f32 v161, v160, v161, v163
	v_med3_f32 v160, v159, v160, v163
	v_med3_f32 v159, v158, v159, v163
	v_med3_f32 v158, v157, v158, v163
	v_max_f32_e32 v157, v157, v163
	v_add_f32_e32 v163, v87, v9
	v_and_or_b32 v163, v163, s0, 36
	v_med3_f32 v162, v161, v162, v163
	v_med3_f32 v161, v160, v161, v163
	v_max_f32_e32 v160, v160, v163
	v_add_f32_e32 v163, v83, v2
	v_and_or_b32 v163, v163, s0, 48
	v_med3_f32 v162, v161, v162, v163
	v_med3_f32 v161, v160, v161, v163
	v_med3_f32 v160, v159, v160, v163
	v_med3_f32 v159, v158, v159, v163
	v_med3_f32 v158, v157, v158, v163
	v_med3_f32 v157, v156, v157, v163
	v_med3_f32 v156, v155, v156, v163
	v_med3_f32 v155, v154, v155, v163
	v_med3_f32 v154, v153, v154, v163
	v_med3_f32 v153, v152, v153, v163
	v_med3_f32 v152, v151, v152, v163
	v_med3_f32 v151, v150, v151, v163
	v_med3_f32 v150, v149, v150, v163
	v_max_f32_e32 v149, v149, v163
	v_add_f32_e32 v163, v83, v4
	v_and_or_b32 v163, v163, s0, 49
	v_med3_f32 v162, v161, v162, v163
	v_med3_f32 v161, v160, v161, v163
	v_med3_f32 v160, v159, v160, v163
	v_med3_f32 v159, v158, v159, v163
	v_med3_f32 v158, v157, v158, v163
	v_med3_f32 v157, v156, v157, v163
	v_med3_f32 v156, v155, v156, v163
	v_med3_f32 v155, v154, v155, v163
	v_med3_f32 v154, v153, v154, v163
	v_max_f32_e32 v153, v153, v163
	v_add_f32_e32 v163, v83, v7
	v_and_or_b32 v163, v163, s0, 50
	v_med3_f32 v162, v161, v162, v163
	v_med3_f32 v161, v160, v161, v163
	v_med3_f32 v160, v159, v160, v163
	v_med3_f32 v159, v158, v159, v163
	v_med3_f32 v158, v157, v158, v163
	v_max_f32_e32 v157, v157, v163
	v_add_f32_e32 v163, v83, v8
	v_and_or_b32 v163, v163, s0, 51
	v_med3_f32 v162, v161, v162, v163
	v_max_f32_e32 v161, v161, v163
	v_add_f32_e32 v163, v79, v2
	v_and_or_b32 v163, v163, s0, 64
	v_med3_f32 v162, v161, v162, v163
	v_med3_f32 v161, v160, v161, v163
	v_med3_f32 v160, v159, v160, v163
	v_med3_f32 v159, v158, v159, v163
	v_med3_f32 v158, v157, v158, v163
	v_med3_f32 v157, v156, v157, v163
	v_med3_f32 v156, v155, v156, v163
	v_med3_f32 v155, v154, v155, v163
	v_med3_f32 v154, v153, v154, v163
	v_med3_f32 v153, v152, v153, v163
	v_med3_f32 v152, v151, v152, v163
	v_med3_f32 v151, v150, v151, v163
	v_max_f32_e32 v150, v150, v163
	v_add_f32_e32 v163, v79, v4
	v_and_b32_e32 v163, 0xffffff00, v163
	v_or_b32_e32 v163, 0x41, v163
	v_med3_f32 v162, v161, v162, v163
	v_med3_f32 v161, v160, v161, v163
	v_med3_f32 v160, v159, v160, v163
	v_med3_f32 v159, v158, v159, v163
	v_med3_f32 v158, v157, v158, v163
	v_med3_f32 v157, v156, v157, v163
	v_med3_f32 v156, v155, v156, v163
	v_max_f32_e32 v155, v155, v163
	v_add_f32_e32 v163, v79, v7
	v_and_b32_e32 v163, 0xffffff00, v163
	v_or_b32_e32 v163, 0x42, v163
	v_med3_f32 v162, v161, v162, v163
	v_med3_f32 v161, v160, v161, v163
	v_max_f32_e32 v160, v160, v163
	v_add_f32_e32 v163, v75, v2
	v_and_b32_e32 v163, 0xffffff00, v163
	v_or_b32_e32 v163, 0x50, v163
	v_med3_f32 v162, v161, v162, v163
	v_med3_f32 v161, v160, v161, v163
	v_med3_f32 v160, v159, v160, v163
	v_med3_f32 v159, v158, v159, v163
	v_med3_f32 v158, v157, v158, v163
	v_med3_f32 v157, v156, v157, v163
	v_med3_f32 v156, v155, v156, v163
	v_med3_f32 v155, v154, v155, v163
	v_med3_f32 v154, v153, v154, v163
	v_med3_f32 v153, v152, v153, v163
	v_med3_f32 v152, v151, v152, v163
	v_max_f32_e32 v151, v151, v163
	v_add_f32_e32 v163, v75, v4
	v_and_b32_e32 v163, 0xffffff00, v163
	v_or_b32_e32 v163, 0x51, v163
	v_med3_f32 v162, v161, v162, v163
	v_med3_f32 v161, v160, v161, v163
	v_med3_f32 v160, v159, v160, v163
	v_med3_f32 v159, v158, v159, v163
	v_med3_f32 v158, v157, v158, v163
	v_max_f32_e32 v157, v157, v163
	v_add_f32_e32 v163, v71, v2
	v_and_b32_e32 v163, 0xffffff00, v163
	v_or_b32_e32 v163, 0x60, v163
	v_med3_f32 v162, v161, v162, v163
	v_med3_f32 v161, v160, v161, v163
	v_med3_f32 v160, v159, v160, v163
	v_med3_f32 v159, v158, v159, v163
	v_med3_f32 v158, v157, v158, v163
	v_med3_f32 v157, v156, v157, v163
	v_med3_f32 v156, v155, v156, v163
	v_med3_f32 v155, v154, v155, v163
	v_med3_f32 v154, v153, v154, v163
	v_med3_f32 v153, v152, v153, v163
	v_max_f32_e32 v152, v152, v163
	v_add_f32_e32 v163, v71, v4
	v_and_b32_e32 v163, 0xffffff00, v163
	v_or_b32_e32 v163, 0x61, v163
; DEV void ce(float& a, float& b) { float hi = fmaxf(a, b), lo = fminf(a, b); a = hi; b = lo; }
; DEV void phase_peer_score(const Params& p, int layer, int M, char* smem) {
;     ...
;     float R[16];
; #pragma unroll
;     for (int i = 0; i < 16; i++) R[i] = -3.0e38f;
; #pragma unroll
;     for (int i = 0; i < 16; i++)
; #pragma unroll
;       for (int j = 0; j < 16; j++)
;         if ((i + 1) * (j + 1) <= 16) {
;           float v = L0[i] + L1[j];
;           v = __uint_as_float((__float_as_uint(v) & ~255u) | (unsigned)(i * 16 + j));
; #pragma unroll
;           for (int t = 0; t < 16; t++)
;             if (t >= (i + 1) * (j + 1) - 1) ce(R[t], v);
;         }
	v_med3_f32 v162, v161, v162, v163
	v_med3_f32 v161, v160, v161, v163
	v_med3_f32 v160, v159, v160, v163
	v_max_f32_e32 v159, v159, v163
	v_add_f32_e32 v163, v63, v2
	v_and_b32_e32 v163, 0xffffff00, v163
	v_or_b32_e32 v163, 0x70, v163
	v_med3_f32 v162, v161, v162, v163
	v_med3_f32 v161, v160, v161, v163
	v_med3_f32 v160, v159, v160, v163
	v_med3_f32 v159, v158, v159, v163
	v_med3_f32 v158, v157, v158, v163
	v_med3_f32 v157, v156, v157, v163
	v_med3_f32 v156, v155, v156, v163
	v_med3_f32 v155, v154, v155, v163
	v_med3_f32 v154, v153, v154, v163
	v_max_f32_e32 v153, v153, v163
	v_add_f32_e32 v163, v63, v4
	v_and_b32_e32 v163, 0xffffff00, v163
	v_or_b32_e32 v163, 0x71, v163
	v_med3_f32 v162, v161, v162, v163
	v_max_f32_e32 v161, v161, v163
	v_add_f32_e32 v163, v67, v2
	v_and_b32_e32 v163, 0xffffff00, v163
	v_or_b32_e32 v163, 0x80, v163
	v_med3_f32 v162, v161, v162, v163
	v_med3_f32 v161, v160, v161, v163
	v_med3_f32 v160, v159, v160, v163
	v_med3_f32 v159, v158, v159, v163
	v_med3_f32 v158, v157, v158, v163
	v_med3_f32 v157, v156, v157, v163
	v_med3_f32 v156, v155, v156, v163
	v_med3_f32 v155, v154, v155, v163
	v_max_f32_e32 v154, v154, v163
	v_add_f32_e32 v163, v59, v2
	v_and_b32_e32 v163, 0xffffff00, v163
	v_or_b32_e32 v163, 0x90, v163
	v_med3_f32 v162, v161, v162, v163
	v_med3_f32 v161, v160, v161, v163
	v_med3_f32 v160, v159, v160, v163
	v_med3_f32 v159, v158, v159, v163
	v_med3_f32 v158, v157, v158, v163
	v_med3_f32 v157, v156, v157, v163
	v_med3_f32 v156, v155, v156, v163
	v_max_f32_e32 v155, v155, v163
	v_add_f32_e32 v163, v55, v2
	v_and_b32_e32 v163, 0xffffff00, v163
	v_or_b32_e32 v163, 0xa0, v163
	v_med3_f32 v162, v161, v162, v163
	v_med3_f32 v161, v160, v161, v163
	v_med3_f32 v160, v159, v160, v163
	v_med3_f32 v159, v158, v159, v163
	v_med3_f32 v158, v157, v158, v163
	v_med3_f32 v157, v156, v157, v163
	v_max_f32_e32 v156, v156, v163
	v_add_f32_e32 v163, v47, v2
	v_and_b32_e32 v163, 0xffffff00, v163
	v_or_b32_e32 v163, 0xb0, v163
	v_med3_f32 v162, v161, v162, v163
	v_med3_f32 v161, v160, v161, v163
	v_med3_f32 v160, v159, v160, v163
	v_med3_f32 v159, v158, v159, v163
	v_med3_f32 v158, v157, v158, v163
	v_max_f32_e32 v157, v157, v163
	v_add_f32_e32 v163, v51, v2
	v_and_b32_e32 v163, 0xffffff00, v163
	v_or_b32_e32 v163, 0xc0, v163
	v_med3_f32 v162, v161, v162, v163
	v_med3_f32 v161, v160, v161, v163
	v_med3_f32 v160, v159, v160, v163
	v_med3_f32 v159, v158, v159, v163
	v_max_f32_e32 v158, v158, v163
	v_add_f32_e32 v163, v39, v2
	v_and_b32_e32 v163, 0xffffff00, v163
	v_or_b32_e32 v163, 0xd0, v163
	v_med3_f32 v162, v161, v162, v163
	v_med3_f32 v161, v160, v161, v163
	v_med3_f32 v160, v159, v160, v163
	v_max_f32_e32 v159, v159, v163
	v_add_f32_e32 v163, v43, v2
	v_and_b32_e32 v163, 0xffffff00, v163
	v_or_b32_e32 v163, 0xe0, v163
	v_med3_f32 v162, v161, v162, v163
	v_med3_f32 v161, v160, v161, v163
	v_max_f32_e32 v160, v160, v163
	v_add_f32_e32 v163, v0, v2
	v_and_b32_e32 v163, 0xffffff00, v163
	v_or_b32_e32 v163, 0xf0, v163
	v_med3_f32 v162, v161, v162, v163
	v_max_f32_e32 v161, v161, v163
	v_cmp_le_f32_e64 s[40:41], v148, v164
	v_cmp_le_f32_e32 vcc, v164, v149
	s_or_b64 s[40:41], s[40:41], vcc
	v_cmp_le_f32_e32 vcc, v149, v150
	s_or_b64 s[40:41], s[40:41], vcc
	v_cmp_le_f32_e32 vcc, v150, v151
	s_or_b64 s[40:41], s[40:41], vcc
	v_cmp_le_f32_e32 vcc, v151, v152
	s_or_b64 s[40:41], s[40:41], vcc
	v_cmp_le_f32_e32 vcc, v152, v153
	s_or_b64 s[40:41], s[40:41], vcc
	v_cmp_le_f32_e32 vcc, v153, v154
	s_or_b64 s[40:41], s[40:41], vcc
	v_cmp_le_f32_e32 vcc, v154, v155
	s_or_b64 s[40:41], s[40:41], vcc
	v_cmp_le_f32_e32 vcc, v155, v156
	s_or_b64 s[40:41], s[40:41], vcc
	v_cmp_le_f32_e32 vcc, v156, v157
	s_or_b64 s[40:41], s[40:41], vcc
	v_cmp_le_f32_e32 vcc, v157, v158
	s_or_b64 s[40:41], s[40:41], vcc
	v_cmp_le_f32_e32 vcc, v158, v159
	s_or_b64 s[40:41], s[40:41], vcc
	v_cmp_le_f32_e32 vcc, v159, v160
	s_or_b64 s[40:41], s[40:41], vcc
	v_cmp_le_f32_e32 vcc, v160, v161
	s_or_b64 s[40:41], s[40:41], vcc
	v_cmp_le_f32_e32 vcc, v161, v162
	s_or_b64 s[40:41], s[40:41], vcc
	s_and_b64 s[40:41], s[40:41], exec
	s_cbranch_scc0 .Lmed3_ok_bb_172
	v_mov_b32_e32 v148, 0xff61b1e6
	v_mov_b32_e32 v164, 0xff61b1e6
	v_mov_b32_e32 v149, 0xff61b1e6
	v_mov_b32_e32 v150, 0xff61b1e6
	v_mov_b32_e32 v151, 0xff61b1e6
	v_mov_b32_e32 v152, 0xff61b1e6
	v_mov_b32_e32 v153, 0xff61b1e6
	v_mov_b32_e32 v154, 0xff61b1e6
	v_mov_b32_e32 v155, 0xff61b1e6
	v_mov_b32_e32 v156, 0xff61b1e6
	v_mov_b32_e32 v157, 0xff61b1e6
	v_mov_b32_e32 v158, 0xff61b1e6
	v_mov_b32_e32 v159, 0xff61b1e6
	v_mov_b32_e32 v160, 0xff61b1e6
	v_mov_b32_e32 v161, 0xff61b1e6
	v_mov_b32_e32 v162, 0xff61b1e6
	v_add_f32_e32 v163, v100, v2
	v_and_or_b32 v163, v163, s0, 0
	v_min_f32_e32 v165, v148, v163
	v_max_f32_e32 v148, v148, v163
	v_min_f32_e32 v163, v164, v165
	v_max_f32_e32 v164, v164, v165
	v_min_f32_e32 v165, v149, v163
	v_max_f32_e32 v149, v149, v163
	v_min_f32_e32 v163, v150, v165
	v_max_f32_e32 v150, v150, v165
	v_min_f32_e32 v165, v151, v163
	v_max_f32_e32 v151, v151, v163
	v_min_f32_e32 v163, v152, v165
	v_max_f32_e32 v152, v152, v165
	v_min_f32_e32 v165, v153, v163
	v_max_f32_e32 v153, v153, v163
	v_min_f32_e32 v163, v154, v165
	v_max_f32_e32 v154, v154, v165
	v_min_f32_e32 v165, v155, v163
	v_max_f32_e32 v155, v155, v163
	v_min_f32_e32 v163, v156, v165
	v_max_f32_e32 v156, v156, v165
	v_min_f32_e32 v165, v157, v163
	v_max_f32_e32 v157, v157, v163
	v_min_f32_e32 v163, v158, v165
	v_max_f32_e32 v158, v158, v165
	v_min_f32_e32 v165, v159, v163
	v_max_f32_e32 v159, v159, v163
	v_min_f32_e32 v163, v160, v165
	v_max_f32_e32 v160, v160, v165
	v_min_f32_e32 v165, v161, v163
	v_max_f32_e32 v161, v161, v163
; DEV void ce(float& a, float& b) { float hi = fmaxf(a, b), lo = fminf(a, b); a = hi; b = lo; }
; DEV void phase_peer_score(const Params& p, int layer, int M, char* smem) {
;     ...
; #pragma unroll
;     for (int i = 0; i < 16; i++) R[i] = -3.0e38f;
; #pragma unroll
;     for (int i = 0; i < 16; i++)
; #pragma unroll
;       for (int j = 0; j < 16; j++)
;         if ((i + 1) * (j + 1) <= 16) {
;           float v = L0[i] + L1[j];
;           v = __uint_as_float((__float_as_uint(v) & ~255u) | (unsigned)(i * 16 + j));
; #pragma unroll
;           for (int t = 0; t < 16; t++)
;             if (t >= (i + 1) * (j + 1) - 1) ce(R[t], v);
;         }
	v_max_f32_e32 v162, v162, v165
	v_add_f32_e32 v163, v100, v4
	v_and_or_b32 v163, v163, s0, 1
	v_min_f32_e32 v165, v164, v163
	v_max_f32_e32 v164, v164, v163
	v_min_f32_e32 v163, v149, v165
	v_max_f32_e32 v149, v149, v165
	v_min_f32_e32 v165, v150, v163
	v_max_f32_e32 v150, v150, v163
	v_min_f32_e32 v163, v151, v165
	v_max_f32_e32 v151, v151, v165
	v_min_f32_e32 v165, v152, v163
	v_max_f32_e32 v152, v152, v163
	v_min_f32_e32 v163, v153, v165
	v_max_f32_e32 v153, v153, v165
	v_min_f32_e32 v165, v154, v163
	v_max_f32_e32 v154, v154, v163
	v_min_f32_e32 v163, v155, v165
	v_max_f32_e32 v155, v155, v165
	v_min_f32_e32 v165, v156, v163
	v_max_f32_e32 v156, v156, v163
	v_min_f32_e32 v163, v157, v165
	v_max_f32_e32 v157, v157, v165
	v_min_f32_e32 v165, v158, v163
	v_max_f32_e32 v158, v158, v163
	v_min_f32_e32 v163, v159, v165
	v_max_f32_e32 v159, v159, v165
	v_min_f32_e32 v165, v160, v163
	v_max_f32_e32 v160, v160, v163
	v_min_f32_e32 v163, v161, v165
	v_max_f32_e32 v161, v161, v165
	v_max_f32_e32 v162, v162, v163
	v_add_f32_e32 v163, v100, v7
	v_and_or_b32 v163, v163, s0, 2
	v_min_f32_e32 v165, v149, v163
	v_max_f32_e32 v149, v149, v163
	v_min_f32_e32 v163, v150, v165
	v_max_f32_e32 v150, v150, v165
	v_min_f32_e32 v165, v151, v163
	v_max_f32_e32 v151, v151, v163
	v_min_f32_e32 v163, v152, v165
	v_max_f32_e32 v152, v152, v165
	v_min_f32_e32 v165, v153, v163
	v_max_f32_e32 v153, v153, v163
	v_min_f32_e32 v163, v154, v165
	v_max_f32_e32 v154, v154, v165
	v_min_f32_e32 v165, v155, v163
	v_max_f32_e32 v155, v155, v163
	v_min_f32_e32 v163, v156, v165
	v_max_f32_e32 v156, v156, v165
	v_min_f32_e32 v165, v157, v163
	v_max_f32_e32 v157, v157, v163
	v_min_f32_e32 v163, v158, v165
	v_max_f32_e32 v158, v158, v165
	v_min_f32_e32 v165, v159, v163
	v_max_f32_e32 v159, v159, v163
	v_min_f32_e32 v163, v160, v165
	v_max_f32_e32 v160, v160, v165
	v_min_f32_e32 v165, v161, v163
	v_max_f32_e32 v161, v161, v163
	v_max_f32_e32 v162, v162, v165
	v_add_f32_e32 v163, v100, v8
	v_and_or_b32 v163, v163, s0, 3
	v_min_f32_e32 v165, v150, v163
	v_max_f32_e32 v150, v150, v163
	v_min_f32_e32 v163, v151, v165
	v_max_f32_e32 v151, v151, v165
	v_min_f32_e32 v165, v152, v163
	v_max_f32_e32 v152, v152, v163
	v_min_f32_e32 v163, v153, v165
	v_max_f32_e32 v153, v153, v165
	v_min_f32_e32 v165, v154, v163
	v_max_f32_e32 v154, v154, v163
	v_min_f32_e32 v163, v155, v165
	v_max_f32_e32 v155, v155, v165
	v_min_f32_e32 v165, v156, v163
	v_max_f32_e32 v156, v156, v163
	v_min_f32_e32 v163, v157, v165
	v_max_f32_e32 v157, v157, v165
	v_min_f32_e32 v165, v158, v163
	v_max_f32_e32 v158, v158, v163
	v_min_f32_e32 v163, v159, v165
	v_max_f32_e32 v159, v159, v165
	v_min_f32_e32 v165, v160, v163
	v_max_f32_e32 v160, v160, v163
	v_min_f32_e32 v163, v161, v165
	v_max_f32_e32 v161, v161, v165
	v_max_f32_e32 v162, v162, v163
	v_add_f32_e32 v163, v100, v9
	v_and_or_b32 v163, v163, s0, 4
	v_min_f32_e32 v165, v151, v163
	v_max_f32_e32 v151, v151, v163
	v_min_f32_e32 v163, v152, v165
	v_max_f32_e32 v152, v152, v165
	v_min_f32_e32 v165, v153, v163
	v_max_f32_e32 v153, v153, v163
	v_min_f32_e32 v163, v154, v165
	v_max_f32_e32 v154, v154, v165
	v_min_f32_e32 v165, v155, v163
	v_max_f32_e32 v155, v155, v163
	v_min_f32_e32 v163, v156, v165
	v_max_f32_e32 v156, v156, v165
	v_min_f32_e32 v165, v157, v163
	v_max_f32_e32 v157, v157, v163
	v_min_f32_e32 v163, v158, v165
	v_max_f32_e32 v158, v158, v165
	v_min_f32_e32 v165, v159, v163
	v_max_f32_e32 v159, v159, v163
	v_min_f32_e32 v163, v160, v165
	v_max_f32_e32 v160, v160, v165
	v_min_f32_e32 v165, v161, v163
	v_max_f32_e32 v161, v161, v163
	v_max_f32_e32 v162, v162, v165
	v_add_f32_e32 v163, v100, v12
	v_and_or_b32 v163, v163, s0, 5
	v_min_f32_e32 v165, v152, v163
	v_max_f32_e32 v152, v152, v163
	v_min_f32_e32 v163, v153, v165
	v_max_f32_e32 v153, v153, v165
	v_min_f32_e32 v165, v154, v163
	v_max_f32_e32 v154, v154, v163
	v_min_f32_e32 v163, v155, v165
	v_max_f32_e32 v155, v155, v165
	v_min_f32_e32 v165, v156, v163
	v_max_f32_e32 v156, v156, v163
	v_min_f32_e32 v163, v157, v165
	v_max_f32_e32 v157, v157, v165
	v_min_f32_e32 v165, v158, v163
	v_max_f32_e32 v158, v158, v163
	v_min_f32_e32 v163, v159, v165
	v_max_f32_e32 v159, v159, v165
	v_min_f32_e32 v165, v160, v163
	v_max_f32_e32 v160, v160, v163
	v_min_f32_e32 v163, v161, v165
	v_max_f32_e32 v161, v161, v165
	v_max_f32_e32 v162, v162, v163
	v_add_f32_e32 v163, v100, v11
	v_and_or_b32 v163, v163, s0, 6
	v_min_f32_e32 v165, v153, v163
	v_max_f32_e32 v153, v153, v163
	v_min_f32_e32 v163, v154, v165
	v_max_f32_e32 v154, v154, v165
	v_min_f32_e32 v165, v155, v163
	v_max_f32_e32 v155, v155, v163
	v_min_f32_e32 v163, v156, v165
	v_max_f32_e32 v156, v156, v165
	v_min_f32_e32 v165, v157, v163
	v_max_f32_e32 v157, v157, v163
	v_min_f32_e32 v163, v158, v165
	v_max_f32_e32 v158, v158, v165
	v_min_f32_e32 v165, v159, v163
	v_max_f32_e32 v159, v159, v163
	v_min_f32_e32 v163, v160, v165
	v_max_f32_e32 v160, v160, v165
	v_min_f32_e32 v165, v161, v163
	v_max_f32_e32 v161, v161, v163
	v_max_f32_e32 v162, v162, v165
	v_add_f32_e32 v163, v100, v10
	v_and_or_b32 v163, v163, s0, 7
	v_min_f32_e32 v165, v154, v163
	v_max_f32_e32 v154, v154, v163
	v_min_f32_e32 v163, v155, v165
	v_max_f32_e32 v155, v155, v165
	v_min_f32_e32 v165, v156, v163
	v_max_f32_e32 v156, v156, v163
	v_min_f32_e32 v163, v157, v165
	v_max_f32_e32 v157, v157, v165
	v_min_f32_e32 v165, v158, v163
	v_max_f32_e32 v158, v158, v163
	v_min_f32_e32 v163, v159, v165
	v_max_f32_e32 v159, v159, v165
	v_min_f32_e32 v165, v160, v163
	v_max_f32_e32 v160, v160, v163
	v_min_f32_e32 v163, v161, v165
	v_max_f32_e32 v161, v161, v165
	v_max_f32_e32 v162, v162, v163
	v_add_f32_e32 v163, v100, v20
; DEV void ce(float& a, float& b) { float hi = fmaxf(a, b), lo = fminf(a, b); a = hi; b = lo; }
; DEV void phase_peer_score(const Params& p, int layer, int M, char* smem) {
;     ...
; #pragma unroll
;     for (int i = 0; i < 16; i++) R[i] = -3.0e38f;
; #pragma unroll
;     for (int i = 0; i < 16; i++)
; #pragma unroll
;       for (int j = 0; j < 16; j++)
;         if ((i + 1) * (j + 1) <= 16) {
;           float v = L0[i] + L1[j];
;           v = __uint_as_float((__float_as_uint(v) & ~255u) | (unsigned)(i * 16 + j));
; #pragma unroll
;           for (int t = 0; t < 16; t++)
;             if (t >= (i + 1) * (j + 1) - 1) ce(R[t], v);
;         }
	v_and_or_b32 v163, v163, s0, 8
	v_min_f32_e32 v165, v155, v163
	v_max_f32_e32 v155, v155, v163
	v_min_f32_e32 v163, v156, v165
	v_max_f32_e32 v156, v156, v165
	v_min_f32_e32 v165, v157, v163
	v_max_f32_e32 v157, v157, v163
	v_min_f32_e32 v163, v158, v165
	v_max_f32_e32 v158, v158, v165
	v_min_f32_e32 v165, v159, v163
	v_max_f32_e32 v159, v159, v163
	v_min_f32_e32 v163, v160, v165
	v_max_f32_e32 v160, v160, v165
	v_min_f32_e32 v165, v161, v163
	v_max_f32_e32 v161, v161, v163
	v_max_f32_e32 v162, v162, v165
	v_add_f32_e32 v163, v100, v17
	v_and_or_b32 v163, v163, s0, 9
	v_min_f32_e32 v165, v156, v163
	v_max_f32_e32 v156, v156, v163
	v_min_f32_e32 v163, v157, v165
	v_max_f32_e32 v157, v157, v165
	v_min_f32_e32 v165, v158, v163
	v_max_f32_e32 v158, v158, v163
	v_min_f32_e32 v163, v159, v165
	v_max_f32_e32 v159, v159, v165
	v_min_f32_e32 v165, v160, v163
	v_max_f32_e32 v160, v160, v163
	v_min_f32_e32 v163, v161, v165
	v_max_f32_e32 v161, v161, v165
	v_max_f32_e32 v162, v162, v163
	v_add_f32_e32 v163, v100, v16
	v_and_or_b32 v163, v163, s0, 10
	v_min_f32_e32 v165, v157, v163
	v_max_f32_e32 v157, v157, v163
	v_min_f32_e32 v163, v158, v165
	v_max_f32_e32 v158, v158, v165
	v_min_f32_e32 v165, v159, v163
	v_max_f32_e32 v159, v159, v163
	v_min_f32_e32 v163, v160, v165
	v_max_f32_e32 v160, v160, v165
	v_min_f32_e32 v165, v161, v163
	v_max_f32_e32 v161, v161, v163
	v_max_f32_e32 v162, v162, v165
	v_add_f32_e32 v163, v100, v15
	v_and_or_b32 v163, v163, s0, 11
	v_min_f32_e32 v165, v158, v163
	v_max_f32_e32 v158, v158, v163
	v_min_f32_e32 v163, v159, v165
	v_max_f32_e32 v159, v159, v165
	v_min_f32_e32 v165, v160, v163
	v_max_f32_e32 v160, v160, v163
	v_min_f32_e32 v163, v161, v165
	v_max_f32_e32 v161, v161, v165
	v_max_f32_e32 v162, v162, v163
	v_add_f32_e32 v163, v100, v14
	v_and_or_b32 v163, v163, s0, 12
	v_min_f32_e32 v165, v159, v163
	v_max_f32_e32 v159, v159, v163
	v_min_f32_e32 v163, v160, v165
	v_max_f32_e32 v160, v160, v165
	v_min_f32_e32 v165, v161, v163
	v_max_f32_e32 v161, v161, v163
	v_max_f32_e32 v162, v162, v165
	v_add_f32_e32 v163, v100, v13
	v_and_or_b32 v163, v163, s0, 13
	v_min_f32_e32 v165, v160, v163
	v_max_f32_e32 v160, v160, v163
	v_min_f32_e32 v163, v161, v165
	v_max_f32_e32 v161, v161, v165
	v_max_f32_e32 v162, v162, v163
	v_add_f32_e32 v163, v100, v6
	v_and_or_b32 v163, v163, s0, 14
	v_min_f32_e32 v165, v161, v163
	v_max_f32_e32 v161, v161, v163
	v_max_f32_e32 v162, v162, v165
	v_add_f32_e32 v163, v100, v5
	v_and_or_b32 v163, v163, s0, 15
	v_max_f32_e32 v162, v162, v163
	v_add_f32_e32 v163, v91, v2
	v_and_or_b32 v163, v163, s0, 16
	v_min_f32_e32 v165, v164, v163
	v_max_f32_e32 v164, v164, v163
	v_min_f32_e32 v163, v149, v165
	v_max_f32_e32 v149, v149, v165
	v_min_f32_e32 v165, v150, v163
	v_max_f32_e32 v150, v150, v163
	v_min_f32_e32 v163, v151, v165
	v_max_f32_e32 v151, v151, v165
	v_min_f32_e32 v165, v152, v163
	v_max_f32_e32 v152, v152, v163
	v_min_f32_e32 v163, v153, v165
	v_max_f32_e32 v153, v153, v165
	v_min_f32_e32 v165, v154, v163
	v_max_f32_e32 v154, v154, v163
	v_min_f32_e32 v163, v155, v165
	v_max_f32_e32 v155, v155, v165
	v_min_f32_e32 v165, v156, v163
	v_max_f32_e32 v156, v156, v163
	v_min_f32_e32 v163, v157, v165
	v_max_f32_e32 v157, v157, v165
	v_min_f32_e32 v165, v158, v163
	v_max_f32_e32 v158, v158, v163
	v_min_f32_e32 v163, v159, v165
	v_max_f32_e32 v159, v159, v165
	v_min_f32_e32 v165, v160, v163
	v_max_f32_e32 v160, v160, v163
	v_min_f32_e32 v163, v161, v165
	v_max_f32_e32 v161, v161, v165
	v_max_f32_e32 v162, v162, v163
	v_add_f32_e32 v163, v91, v4
	v_and_or_b32 v163, v163, s0, 17
	v_min_f32_e32 v165, v150, v163
	v_max_f32_e32 v150, v150, v163
	v_min_f32_e32 v163, v151, v165
	v_max_f32_e32 v151, v151, v165
	v_min_f32_e32 v165, v152, v163
	v_max_f32_e32 v152, v152, v163
	v_min_f32_e32 v163, v153, v165
	v_max_f32_e32 v153, v153, v165
	v_min_f32_e32 v165, v154, v163
	v_max_f32_e32 v154, v154, v163
	v_min_f32_e32 v163, v155, v165
	v_max_f32_e32 v155, v155, v165
	v_min_f32_e32 v165, v156, v163
	v_max_f32_e32 v156, v156, v163
	v_min_f32_e32 v163, v157, v165
	v_max_f32_e32 v157, v157, v165
	v_min_f32_e32 v165, v158, v163
	v_max_f32_e32 v158, v158, v163
	v_min_f32_e32 v163, v159, v165
	v_max_f32_e32 v159, v159, v165
	v_min_f32_e32 v165, v160, v163
	v_max_f32_e32 v160, v160, v163
	v_min_f32_e32 v163, v161, v165
	v_max_f32_e32 v161, v161, v165
	v_max_f32_e32 v162, v162, v163
	v_add_f32_e32 v163, v91, v7
	v_and_or_b32 v163, v163, s0, 18
	v_min_f32_e32 v165, v152, v163
	v_max_f32_e32 v152, v152, v163
	v_min_f32_e32 v163, v153, v165
	v_max_f32_e32 v153, v153, v165
	v_min_f32_e32 v165, v154, v163
	v_max_f32_e32 v154, v154, v163
	v_min_f32_e32 v163, v155, v165
	v_max_f32_e32 v155, v155, v165
	v_min_f32_e32 v165, v156, v163
	v_max_f32_e32 v156, v156, v163
	v_min_f32_e32 v163, v157, v165
	v_max_f32_e32 v157, v157, v165
	v_min_f32_e32 v165, v158, v163
	v_max_f32_e32 v158, v158, v163
	v_min_f32_e32 v163, v159, v165
	v_max_f32_e32 v159, v159, v165
	v_min_f32_e32 v165, v160, v163
	v_max_f32_e32 v160, v160, v163
	v_min_f32_e32 v163, v161, v165
	v_max_f32_e32 v161, v161, v165
	v_max_f32_e32 v162, v162, v163
	v_add_f32_e32 v163, v91, v8
	v_and_or_b32 v163, v163, s0, 19
	v_min_f32_e32 v165, v154, v163
	v_max_f32_e32 v154, v154, v163
	v_min_f32_e32 v163, v155, v165
	v_max_f32_e32 v155, v155, v165
	v_min_f32_e32 v165, v156, v163
	v_max_f32_e32 v156, v156, v163
	v_min_f32_e32 v163, v157, v165
	v_max_f32_e32 v157, v157, v165
	v_min_f32_e32 v165, v158, v163
	v_max_f32_e32 v158, v158, v163
	v_min_f32_e32 v163, v159, v165
	v_max_f32_e32 v159, v159, v165
	v_min_f32_e32 v165, v160, v163
	v_max_f32_e32 v160, v160, v163
	v_min_f32_e32 v163, v161, v165
; DEV void ce(float& a, float& b) { float hi = fmaxf(a, b), lo = fminf(a, b); a = hi; b = lo; }
; DEV void phase_peer_score(const Params& p, int layer, int M, char* smem) {
;     ...
; #pragma unroll
;     for (int i = 0; i < 16; i++) R[i] = -3.0e38f;
; #pragma unroll
;     for (int i = 0; i < 16; i++)
; #pragma unroll
;       for (int j = 0; j < 16; j++)
;         if ((i + 1) * (j + 1) <= 16) {
;           float v = L0[i] + L1[j];
;           v = __uint_as_float((__float_as_uint(v) & ~255u) | (unsigned)(i * 16 + j));
; #pragma unroll
;           for (int t = 0; t < 16; t++)
;             if (t >= (i + 1) * (j + 1) - 1) ce(R[t], v);
;         }
	v_max_f32_e32 v161, v161, v165
	v_max_f32_e32 v162, v162, v163
	v_add_f32_e32 v163, v91, v9
	v_and_or_b32 v163, v163, s0, 20
	v_min_f32_e32 v165, v156, v163
	v_max_f32_e32 v156, v156, v163
	v_min_f32_e32 v163, v157, v165
	v_max_f32_e32 v157, v157, v165
	v_min_f32_e32 v165, v158, v163
	v_max_f32_e32 v158, v158, v163
	v_min_f32_e32 v163, v159, v165
	v_max_f32_e32 v159, v159, v165
	v_min_f32_e32 v165, v160, v163
	v_max_f32_e32 v160, v160, v163
	v_min_f32_e32 v163, v161, v165
	v_max_f32_e32 v161, v161, v165
	v_max_f32_e32 v162, v162, v163
	v_add_f32_e32 v163, v91, v12
	v_and_or_b32 v163, v163, s0, 21
	v_min_f32_e32 v165, v158, v163
	v_max_f32_e32 v158, v158, v163
	v_min_f32_e32 v163, v159, v165
	v_max_f32_e32 v159, v159, v165
	v_min_f32_e32 v165, v160, v163
	v_max_f32_e32 v160, v160, v163
	v_min_f32_e32 v163, v161, v165
	v_max_f32_e32 v161, v161, v165
	v_max_f32_e32 v162, v162, v163
	v_add_f32_e32 v163, v91, v11
	v_and_or_b32 v163, v163, s0, 22
	v_min_f32_e32 v165, v160, v163
	v_max_f32_e32 v160, v160, v163
	v_min_f32_e32 v163, v161, v165
	v_max_f32_e32 v161, v161, v165
	v_max_f32_e32 v162, v162, v163
	v_add_f32_e32 v163, v91, v10
	v_and_or_b32 v163, v163, s0, 23
	v_max_f32_e32 v162, v162, v163
	v_add_f32_e32 v163, v87, v2
	v_and_or_b32 v163, v163, s0, 32
	v_min_f32_e32 v165, v149, v163
	v_max_f32_e32 v149, v149, v163
	v_min_f32_e32 v163, v150, v165
	v_max_f32_e32 v150, v150, v165
	v_min_f32_e32 v165, v151, v163
	v_max_f32_e32 v151, v151, v163
	v_min_f32_e32 v163, v152, v165
	v_max_f32_e32 v152, v152, v165
	v_min_f32_e32 v165, v153, v163
	v_max_f32_e32 v153, v153, v163
	v_min_f32_e32 v163, v154, v165
	v_max_f32_e32 v154, v154, v165
	v_min_f32_e32 v165, v155, v163
	v_max_f32_e32 v155, v155, v163
	v_min_f32_e32 v163, v156, v165
	v_max_f32_e32 v156, v156, v165
	v_min_f32_e32 v165, v157, v163
	v_max_f32_e32 v157, v157, v163
	v_min_f32_e32 v163, v158, v165
	v_max_f32_e32 v158, v158, v165
	v_min_f32_e32 v165, v159, v163
	v_max_f32_e32 v159, v159, v163
	v_min_f32_e32 v163, v160, v165
	v_max_f32_e32 v160, v160, v165
	v_min_f32_e32 v165, v161, v163
	v_max_f32_e32 v161, v161, v163
	v_max_f32_e32 v162, v162, v165
	v_add_f32_e32 v163, v87, v4
	v_and_or_b32 v163, v163, s0, 33
	v_min_f32_e32 v165, v152, v163
	v_max_f32_e32 v152, v152, v163
	v_min_f32_e32 v163, v153, v165
	v_max_f32_e32 v153, v153, v165
	v_min_f32_e32 v165, v154, v163
	v_max_f32_e32 v154, v154, v163
	v_min_f32_e32 v163, v155, v165
	v_max_f32_e32 v155, v155, v165
	v_min_f32_e32 v165, v156, v163
	v_max_f32_e32 v156, v156, v163
	v_min_f32_e32 v163, v157, v165
	v_max_f32_e32 v157, v157, v165
	v_min_f32_e32 v165, v158, v163
	v_max_f32_e32 v158, v158, v163
	v_min_f32_e32 v163, v159, v165
	v_max_f32_e32 v159, v159, v165
	v_min_f32_e32 v165, v160, v163
	v_max_f32_e32 v160, v160, v163
	v_min_f32_e32 v163, v161, v165
	v_max_f32_e32 v161, v161, v165
	v_max_f32_e32 v162, v162, v163
	v_add_f32_e32 v163, v87, v7
	v_and_or_b32 v163, v163, s0, 34
	v_min_f32_e32 v165, v155, v163
	v_max_f32_e32 v155, v155, v163
	v_min_f32_e32 v163, v156, v165
	v_max_f32_e32 v156, v156, v165
	v_min_f32_e32 v165, v157, v163
	v_max_f32_e32 v157, v157, v163
	v_min_f32_e32 v163, v158, v165
	v_max_f32_e32 v158, v158, v165
	v_min_f32_e32 v165, v159, v163
	v_max_f32_e32 v159, v159, v163
	v_min_f32_e32 v163, v160, v165
	v_max_f32_e32 v160, v160, v165
	v_min_f32_e32 v165, v161, v163
	v_max_f32_e32 v161, v161, v163
	v_max_f32_e32 v162, v162, v165
	v_add_f32_e32 v163, v87, v8
	v_and_or_b32 v163, v163, s0, 35
	v_min_f32_e32 v165, v158, v163
	v_max_f32_e32 v158, v158, v163
	v_min_f32_e32 v163, v159, v165
	v_max_f32_e32 v159, v159, v165
	v_min_f32_e32 v165, v160, v163
	v_max_f32_e32 v160, v160, v163
	v_min_f32_e32 v163, v161, v165
	v_max_f32_e32 v161, v161, v165
	v_max_f32_e32 v162, v162, v163
	v_add_f32_e32 v163, v87, v9
	v_and_or_b32 v163, v163, s0, 36
	v_min_f32_e32 v165, v161, v163
	v_max_f32_e32 v161, v161, v163
	v_max_f32_e32 v162, v162, v165
	v_add_f32_e32 v163, v83, v2
	v_and_or_b32 v163, v163, s0, 48
	v_min_f32_e32 v165, v150, v163
	v_max_f32_e32 v150, v150, v163
	v_min_f32_e32 v163, v151, v165
	v_max_f32_e32 v151, v151, v165
	v_min_f32_e32 v165, v152, v163
	v_max_f32_e32 v152, v152, v163
	v_min_f32_e32 v163, v153, v165
	v_max_f32_e32 v153, v153, v165
	v_min_f32_e32 v165, v154, v163
	v_max_f32_e32 v154, v154, v163
	v_min_f32_e32 v163, v155, v165
	v_max_f32_e32 v155, v155, v165
	v_min_f32_e32 v165, v156, v163
	v_max_f32_e32 v156, v156, v163
	v_min_f32_e32 v163, v157, v165
	v_max_f32_e32 v157, v157, v165
	v_min_f32_e32 v165, v158, v163
	v_max_f32_e32 v158, v158, v163
	v_min_f32_e32 v163, v159, v165
	v_max_f32_e32 v159, v159, v165
	v_min_f32_e32 v165, v160, v163
	v_max_f32_e32 v160, v160, v163
	v_min_f32_e32 v163, v161, v165
	v_max_f32_e32 v161, v161, v165
	v_max_f32_e32 v162, v162, v163
	v_add_f32_e32 v163, v83, v4
	v_and_or_b32 v163, v163, s0, 49
	v_min_f32_e32 v165, v154, v163
	v_max_f32_e32 v154, v154, v163
	v_min_f32_e32 v163, v155, v165
	v_max_f32_e32 v155, v155, v165
	v_min_f32_e32 v165, v156, v163
	v_max_f32_e32 v156, v156, v163
	v_min_f32_e32 v163, v157, v165
	v_max_f32_e32 v157, v157, v165
	v_min_f32_e32 v165, v158, v163
	v_max_f32_e32 v158, v158, v163
	v_min_f32_e32 v163, v159, v165
	v_max_f32_e32 v159, v159, v165
	v_min_f32_e32 v165, v160, v163
	v_max_f32_e32 v160, v160, v163
	v_min_f32_e32 v163, v161, v165
	v_max_f32_e32 v161, v161, v165
	v_max_f32_e32 v162, v162, v163
	v_add_f32_e32 v163, v83, v7
	v_and_or_b32 v163, v163, s0, 50
	v_min_f32_e32 v165, v158, v163
	v_max_f32_e32 v158, v158, v163
	v_min_f32_e32 v163, v159, v165
	v_max_f32_e32 v159, v159, v165
	v_min_f32_e32 v165, v160, v163
	v_max_f32_e32 v160, v160, v163
; DEV void ce(float& a, float& b) { float hi = fmaxf(a, b), lo = fminf(a, b); a = hi; b = lo; }
; DEV void phase_peer_score(const Params& p, int layer, int M, char* smem) {
;     ...
; #pragma unroll
;     for (int i = 0; i < 16; i++) R[i] = -3.0e38f;
; #pragma unroll
;     for (int i = 0; i < 16; i++)
; #pragma unroll
;       for (int j = 0; j < 16; j++)
;         if ((i + 1) * (j + 1) <= 16) {
;           float v = L0[i] + L1[j];
;           v = __uint_as_float((__float_as_uint(v) & ~255u) | (unsigned)(i * 16 + j));
; #pragma unroll
;           for (int t = 0; t < 16; t++)
;             if (t >= (i + 1) * (j + 1) - 1) ce(R[t], v);
;         }
	v_min_f32_e32 v163, v161, v165
	v_max_f32_e32 v161, v161, v165
	v_max_f32_e32 v162, v162, v163
	v_add_f32_e32 v163, v83, v8
	v_and_or_b32 v163, v163, s0, 51
	v_max_f32_e32 v162, v162, v163
	v_add_f32_e32 v163, v79, v2
	v_and_or_b32 v163, v163, s0, 64
	v_min_f32_e32 v165, v151, v163
	v_max_f32_e32 v151, v151, v163
	v_min_f32_e32 v163, v152, v165
	v_max_f32_e32 v152, v152, v165
	v_min_f32_e32 v165, v153, v163
	v_max_f32_e32 v153, v153, v163
	v_min_f32_e32 v163, v154, v165
	v_max_f32_e32 v154, v154, v165
	v_min_f32_e32 v165, v155, v163
	v_max_f32_e32 v155, v155, v163
	v_min_f32_e32 v163, v156, v165
	v_max_f32_e32 v156, v156, v165
	v_min_f32_e32 v165, v157, v163
	v_max_f32_e32 v157, v157, v163
	v_min_f32_e32 v163, v158, v165
	v_max_f32_e32 v158, v158, v165
	v_min_f32_e32 v165, v159, v163
	v_max_f32_e32 v159, v159, v163
	v_min_f32_e32 v163, v160, v165
	v_max_f32_e32 v160, v160, v165
	v_min_f32_e32 v165, v161, v163
	v_max_f32_e32 v161, v161, v163
	v_max_f32_e32 v162, v162, v165
	v_add_f32_e32 v163, v79, v4
	v_and_b32_e32 v163, 0xffffff00, v163
	v_or_b32_e32 v163, 0x41, v163
	v_min_f32_e32 v165, v156, v163
	v_max_f32_e32 v156, v156, v163
	v_min_f32_e32 v163, v157, v165
	v_max_f32_e32 v157, v157, v165
	v_min_f32_e32 v165, v158, v163
	v_max_f32_e32 v158, v158, v163
	v_min_f32_e32 v163, v159, v165
	v_max_f32_e32 v159, v159, v165
	v_min_f32_e32 v165, v160, v163
	v_max_f32_e32 v160, v160, v163
	v_min_f32_e32 v163, v161, v165
	v_max_f32_e32 v161, v161, v165
	v_max_f32_e32 v162, v162, v163
	v_add_f32_e32 v163, v79, v7
	v_and_b32_e32 v163, 0xffffff00, v163
	v_or_b32_e32 v163, 0x42, v163
	v_min_f32_e32 v165, v161, v163
	v_max_f32_e32 v161, v161, v163
	v_max_f32_e32 v162, v162, v165
	v_add_f32_e32 v163, v75, v2
	v_and_b32_e32 v163, 0xffffff00, v163
	v_or_b32_e32 v163, 0x50, v163
	v_min_f32_e32 v165, v152, v163
	v_max_f32_e32 v152, v152, v163
	v_min_f32_e32 v163, v153, v165
	v_max_f32_e32 v153, v153, v165
	v_min_f32_e32 v165, v154, v163
	v_max_f32_e32 v154, v154, v163
	v_min_f32_e32 v163, v155, v165
	v_max_f32_e32 v155, v155, v165
	v_min_f32_e32 v165, v156, v163
	v_max_f32_e32 v156, v156, v163
	v_min_f32_e32 v163, v157, v165
	v_max_f32_e32 v157, v157, v165
	v_min_f32_e32 v165, v158, v163
	v_max_f32_e32 v158, v158, v163
	v_min_f32_e32 v163, v159, v165
	v_max_f32_e32 v159, v159, v165
	v_min_f32_e32 v165, v160, v163
	v_max_f32_e32 v160, v160, v163
	v_min_f32_e32 v163, v161, v165
	v_max_f32_e32 v161, v161, v165
	v_max_f32_e32 v162, v162, v163
	v_add_f32_e32 v163, v75, v4
	v_and_b32_e32 v163, 0xffffff00, v163
	v_or_b32_e32 v163, 0x51, v163
	v_min_f32_e32 v165, v158, v163
	v_max_f32_e32 v158, v158, v163
	v_min_f32_e32 v163, v159, v165
	v_max_f32_e32 v159, v159, v165
	v_min_f32_e32 v165, v160, v163
	v_max_f32_e32 v160, v160, v163
	v_min_f32_e32 v163, v161, v165
	v_max_f32_e32 v161, v161, v165
	v_max_f32_e32 v162, v162, v163
	v_add_f32_e32 v163, v71, v2
	v_and_b32_e32 v163, 0xffffff00, v163
	v_or_b32_e32 v163, 0x60, v163
	v_min_f32_e32 v165, v153, v163
	v_max_f32_e32 v153, v153, v163
	v_min_f32_e32 v163, v154, v165
	v_max_f32_e32 v154, v154, v165
	v_min_f32_e32 v165, v155, v163
	v_max_f32_e32 v155, v155, v163
	v_min_f32_e32 v163, v156, v165
	v_max_f32_e32 v156, v156, v165
	v_min_f32_e32 v165, v157, v163
	v_max_f32_e32 v157, v157, v163
	v_min_f32_e32 v163, v158, v165
	v_max_f32_e32 v158, v158, v165
	v_min_f32_e32 v165, v159, v163
	v_max_f32_e32 v159, v159, v163
	v_min_f32_e32 v163, v160, v165
	v_max_f32_e32 v160, v160, v165
	v_min_f32_e32 v165, v161, v163
	v_max_f32_e32 v161, v161, v163
	v_max_f32_e32 v162, v162, v165
	v_add_f32_e32 v163, v71, v4
	v_and_b32_e32 v163, 0xffffff00, v163
	v_or_b32_e32 v163, 0x61, v163
	v_min_f32_e32 v165, v160, v163
	v_max_f32_e32 v160, v160, v163
; DEV void ce(float& a, float& b) { float hi = fmaxf(a, b), lo = fminf(a, b); a = hi; b = lo; }
; DEV void phase_peer_score(const Params& p, int layer, int M, char* smem) {
;     ...
; #pragma unroll
;     for (int i = 0; i < 16; i++) R[i] = -3.0e38f;
; #pragma unroll
;     for (int i = 0; i < 16; i++)
; #pragma unroll
;       for (int j = 0; j < 16; j++)
;         if ((i + 1) * (j + 1) <= 16) {
;           float v = L0[i] + L1[j];
;           v = __uint_as_float((__float_as_uint(v) & ~255u) | (unsigned)(i * 16 + j));
; #pragma unroll
;           for (int t = 0; t < 16; t++)
;             if (t >= (i + 1) * (j + 1) - 1) ce(R[t], v);
;         }
	v_min_f32_e32 v163, v161, v165
	v_max_f32_e32 v161, v161, v165
	v_max_f32_e32 v162, v162, v163
	v_add_f32_e32 v163, v63, v2
	v_and_b32_e32 v163, 0xffffff00, v163
	v_or_b32_e32 v163, 0x70, v163
	v_min_f32_e32 v165, v154, v163
	v_max_f32_e32 v154, v154, v163
	v_min_f32_e32 v163, v155, v165
	v_max_f32_e32 v155, v155, v165
	v_min_f32_e32 v165, v156, v163
	v_max_f32_e32 v156, v156, v163
	v_min_f32_e32 v163, v157, v165
	v_max_f32_e32 v157, v157, v165
	v_min_f32_e32 v165, v158, v163
	v_max_f32_e32 v158, v158, v163
	v_min_f32_e32 v163, v159, v165
	v_max_f32_e32 v159, v159, v165
	v_min_f32_e32 v165, v160, v163
	v_max_f32_e32 v160, v160, v163
	v_min_f32_e32 v163, v161, v165
	v_max_f32_e32 v161, v161, v165
	v_max_f32_e32 v162, v162, v163
	v_add_f32_e32 v163, v63, v4
	v_and_b32_e32 v163, 0xffffff00, v163
	v_or_b32_e32 v163, 0x71, v163
	v_max_f32_e32 v162, v162, v163
	v_add_f32_e32 v163, v67, v2
	v_and_b32_e32 v163, 0xffffff00, v163
	v_or_b32_e32 v163, 0x80, v163
	v_min_f32_e32 v165, v155, v163
	v_max_f32_e32 v155, v155, v163
	v_min_f32_e32 v163, v156, v165
	v_max_f32_e32 v156, v156, v165
	v_min_f32_e32 v165, v157, v163
	v_max_f32_e32 v157, v157, v163
	v_min_f32_e32 v163, v158, v165
	v_max_f32_e32 v158, v158, v165
	v_min_f32_e32 v165, v159, v163
	v_max_f32_e32 v159, v159, v163
	v_min_f32_e32 v163, v160, v165
	v_max_f32_e32 v160, v160, v165
	v_min_f32_e32 v165, v161, v163
	v_max_f32_e32 v161, v161, v163
	v_max_f32_e32 v162, v162, v165
	v_add_f32_e32 v163, v59, v2
	v_and_b32_e32 v163, 0xffffff00, v163
	v_or_b32_e32 v163, 0x90, v163
	v_min_f32_e32 v165, v156, v163
	v_max_f32_e32 v156, v156, v163
	v_min_f32_e32 v163, v157, v165
	v_max_f32_e32 v157, v157, v165
	v_min_f32_e32 v165, v158, v163
	v_max_f32_e32 v158, v158, v163
	v_min_f32_e32 v163, v159, v165
	v_max_f32_e32 v159, v159, v165
	v_min_f32_e32 v165, v160, v163
	v_max_f32_e32 v160, v160, v163
	v_min_f32_e32 v163, v161, v165
	v_max_f32_e32 v161, v161, v165
	v_max_f32_e32 v162, v162, v163
	v_add_f32_e32 v163, v55, v2
	v_and_b32_e32 v163, 0xffffff00, v163
	v_or_b32_e32 v163, 0xa0, v163
	v_min_f32_e32 v165, v157, v163
	v_max_f32_e32 v157, v157, v163
	v_min_f32_e32 v163, v158, v165
	v_max_f32_e32 v158, v158, v165
	v_min_f32_e32 v165, v159, v163
	v_max_f32_e32 v159, v159, v163
	v_min_f32_e32 v163, v160, v165
	v_max_f32_e32 v160, v160, v165
	v_min_f32_e32 v165, v161, v163
	v_max_f32_e32 v161, v161, v163
	v_max_f32_e32 v162, v162, v165
	v_add_f32_e32 v163, v47, v2
	v_and_b32_e32 v163, 0xffffff00, v163
	v_or_b32_e32 v163, 0xb0, v163
	v_min_f32_e32 v165, v158, v163
	v_max_f32_e32 v158, v158, v163
	v_min_f32_e32 v163, v159, v165
	v_max_f32_e32 v159, v159, v165
	v_min_f32_e32 v165, v160, v163
	v_max_f32_e32 v160, v160, v163
	v_min_f32_e32 v163, v161, v165
	v_max_f32_e32 v161, v161, v165
	v_max_f32_e32 v162, v162, v163
	v_add_f32_e32 v163, v51, v2
	v_and_b32_e32 v163, 0xffffff00, v163
	v_or_b32_e32 v163, 0xc0, v163
	v_min_f32_e32 v165, v159, v163
	v_max_f32_e32 v159, v159, v163
	v_min_f32_e32 v163, v160, v165
	v_max_f32_e32 v160, v160, v165
	v_min_f32_e32 v165, v161, v163
	v_max_f32_e32 v161, v161, v163
	v_max_f32_e32 v162, v162, v165
	v_add_f32_e32 v163, v39, v2
	v_and_b32_e32 v163, 0xffffff00, v163
	v_or_b32_e32 v163, 0xd0, v163
	v_min_f32_e32 v165, v160, v163
	v_max_f32_e32 v160, v160, v163
	v_min_f32_e32 v163, v161, v165
	v_max_f32_e32 v161, v161, v165
	v_max_f32_e32 v162, v162, v163
	v_add_f32_e32 v163, v43, v2
	v_and_b32_e32 v163, 0xffffff00, v163
	v_or_b32_e32 v163, 0xe0, v163
	v_min_f32_e32 v165, v161, v163
	v_max_f32_e32 v161, v161, v163
	v_max_f32_e32 v162, v162, v165
	v_add_f32_e32 v163, v0, v2
	v_and_b32_e32 v163, 0xffffff00, v163
	v_or_b32_e32 v163, 0xf0, v163
	v_max_f32_e32 v162, v162, v163

; DEV f32x4 mfma16(bf16x8 a, bf16x8 b, f32x4 c) { return __builtin_amdgcn_mfma_f32_16x16x32_bf16(a, b, c, 0, 0, 0); }
; DEV void peer_top16(const bf16_t* __restrict__ pq, const bf16_t* sk  , float (&l)[16]) {
;     ...
; #pragma unroll 1
;   for (int ks = 0; ks < 4; ks++) {
;     const bf16x8 bqk = *(const bf16x8*)(pq + ks * 32 + quad * 8);
; #pragma unroll
;     for (int nt = 0; nt < 8; nt++) {
;       bf16x8 ak = *(const bf16x8*)(sk + (nt * 16 + l15) * 144 + ks * 32 + quad * 8);
;       acc[nt] = mfma16(ak, bqk, acc[nt]);
;     }
;   }
.LBB0_633:
	global_load_dwordx4 v[148:151], v[102:103], off
	global_load_dwordx4 v[152:155], v[102:103], off offset:64
	global_load_dwordx4 v[156:159], v[102:103], off offset:128
	global_load_dwordx4 v[160:163], v[102:103], off offset:192
	ds_read_b128 v[164:167], v39
	ds_read_b128 v[168:171], v39 offset:4608
	ds_read_b128 v[172:175], v39 offset:9216
	ds_read_b128 v[176:179], v39 offset:13824
	ds_read_b128 v[180:183], v39 offset:18432
	ds_read_b128 v[184:187], v39 offset:23040
	ds_read_b128 v[188:191], v39 offset:27648
	ds_read_b128 v[108:111], v39 offset:32256
	s_waitcnt vmcnt(3) lgkmcnt(7)
	v_mfma_f32_16x16x32_bf16 v[30:33], v[164:167], v[148:151], v[30:33]
	ds_read_b128 v[164:167], v39 offset:64
	s_waitcnt lgkmcnt(7)
	v_mfma_f32_16x16x32_bf16 v[22:25], v[168:171], v[148:151], v[22:25]
	ds_read_b128 v[168:171], v39 offset:4672
	s_waitcnt lgkmcnt(7)
	v_mfma_f32_16x16x32_bf16 v[14:17], v[172:175], v[148:151], v[14:17]
	ds_read_b128 v[172:175], v39 offset:9280
	s_waitcnt lgkmcnt(7)
	v_mfma_f32_16x16x32_bf16 v[6:9], v[176:179], v[148:151], v[6:9]
	ds_read_b128 v[176:179], v39 offset:13888
	s_waitcnt lgkmcnt(7)
	v_mfma_f32_16x16x32_bf16 v[26:29], v[180:183], v[148:151], v[26:29]
	ds_read_b128 v[180:183], v39 offset:18496
	s_waitcnt lgkmcnt(7)
	v_mfma_f32_16x16x32_bf16 v[18:21], v[184:187], v[148:151], v[18:21]
	ds_read_b128 v[184:187], v39 offset:23104
	s_waitcnt lgkmcnt(7)
	v_mfma_f32_16x16x32_bf16 v[10:13], v[188:191], v[148:151], v[10:13]
	ds_read_b128 v[188:191], v39 offset:27712
	s_waitcnt lgkmcnt(7)
	v_mfma_f32_16x16x32_bf16 v[2:5], v[108:111], v[148:151], v[2:5]
	ds_read_b128 v[108:111], v39 offset:32320
	global_load_dwordx4 v[148:151], v[102:103], off offset:256
	s_waitcnt vmcnt(3) lgkmcnt(7)
	v_mfma_f32_16x16x32_bf16 v[30:33], v[164:167], v[152:155], v[30:33]
	ds_read_b128 v[164:167], v39 offset:128
	s_waitcnt lgkmcnt(7)
	v_mfma_f32_16x16x32_bf16 v[22:25], v[168:171], v[152:155], v[22:25]
	ds_read_b128 v[168:171], v39 offset:4736
	s_waitcnt lgkmcnt(7)
	v_mfma_f32_16x16x32_bf16 v[14:17], v[172:175], v[152:155], v[14:17]
	ds_read_b128 v[172:175], v39 offset:9344
	s_waitcnt lgkmcnt(7)
	v_mfma_f32_16x16x32_bf16 v[6:9], v[176:179], v[152:155], v[6:9]
	ds_read_b128 v[176:179], v39 offset:13952
	s_waitcnt lgkmcnt(7)
	v_mfma_f32_16x16x32_bf16 v[26:29], v[180:183], v[152:155], v[26:29]
	ds_read_b128 v[180:183], v39 offset:18560
	s_waitcnt lgkmcnt(7)
	v_mfma_f32_16x16x32_bf16 v[18:21], v[184:187], v[152:155], v[18:21]
	ds_read_b128 v[184:187], v39 offset:23168
	s_waitcnt lgkmcnt(7)
	v_mfma_f32_16x16x32_bf16 v[10:13], v[188:191], v[152:155], v[10:13]
	ds_read_b128 v[188:191], v39 offset:27776
	s_waitcnt lgkmcnt(7)
	v_mfma_f32_16x16x32_bf16 v[2:5], v[108:111], v[152:155], v[2:5]
	ds_read_b128 v[108:111], v39 offset:32384
	global_load_dwordx4 v[152:155], v[102:103], off offset:320
	s_waitcnt vmcnt(3) lgkmcnt(7)
	v_mfma_f32_16x16x32_bf16 v[30:33], v[164:167], v[156:159], v[30:33]
	ds_read_b128 v[164:167], v39 offset:192
	s_waitcnt lgkmcnt(7)
	v_mfma_f32_16x16x32_bf16 v[22:25], v[168:171], v[156:159], v[22:25]
	ds_read_b128 v[168:171], v39 offset:4800
	s_waitcnt lgkmcnt(7)
	v_mfma_f32_16x16x32_bf16 v[14:17], v[172:175], v[156:159], v[14:17]
	ds_read_b128 v[172:175], v39 offset:9408
	s_waitcnt lgkmcnt(7)
	v_mfma_f32_16x16x32_bf16 v[6:9], v[176:179], v[156:159], v[6:9]
	ds_read_b128 v[176:179], v39 offset:14016
	s_waitcnt lgkmcnt(7)
	v_mfma_f32_16x16x32_bf16 v[26:29], v[180:183], v[156:159], v[26:29]
	ds_read_b128 v[180:183], v39 offset:18624
	s_waitcnt lgkmcnt(7)
	v_mfma_f32_16x16x32_bf16 v[18:21], v[184:187], v[156:159], v[18:21]
	ds_read_b128 v[184:187], v39 offset:23232
	s_waitcnt lgkmcnt(7)
	v_mfma_f32_16x16x32_bf16 v[10:13], v[188:191], v[156:159], v[10:13]
	ds_read_b128 v[188:191], v39 offset:27840
	s_waitcnt lgkmcnt(7)
	v_mfma_f32_16x16x32_bf16 v[2:5], v[108:111], v[156:159], v[2:5]
	ds_read_b128 v[108:111], v39 offset:32448
	global_load_dwordx4 v[156:159], v[102:103], off offset:384
	s_waitcnt vmcnt(3) lgkmcnt(7)
	v_mfma_f32_16x16x32_bf16 v[30:33], v[164:167], v[160:163], v[30:33]
	s_waitcnt lgkmcnt(6)
	v_mfma_f32_16x16x32_bf16 v[22:25], v[168:171], v[160:163], v[22:25]
	s_waitcnt lgkmcnt(5)
	v_mfma_f32_16x16x32_bf16 v[14:17], v[172:175], v[160:163], v[14:17]
	s_waitcnt lgkmcnt(4)
	v_mfma_f32_16x16x32_bf16 v[6:9], v[176:179], v[160:163], v[6:9]
	s_waitcnt lgkmcnt(3)
	v_mfma_f32_16x16x32_bf16 v[26:29], v[180:183], v[160:163], v[26:29]
	s_waitcnt lgkmcnt(2)
	v_mfma_f32_16x16x32_bf16 v[18:21], v[184:187], v[160:163], v[18:21]
	s_waitcnt lgkmcnt(1)
	v_mfma_f32_16x16x32_bf16 v[10:13], v[188:191], v[160:163], v[10:13]
	s_waitcnt lgkmcnt(0)
; DEV void ce(float& a, float& b) { float hi = fmaxf(a, b), lo = fminf(a, b); a = hi; b = lo; }
; DEV void sort16_desc(float (&a)[16]) {
; #pragma unroll
;   for (int k = 2; k <= 16; k <<= 1)
; #pragma unroll
;     for (int j = k >> 1; j > 0; j >>= 1)
; #pragma unroll
;       for (int i = 0; i < 16; i++) {
;         const int p = i ^ j;
;         if (p > i) { if ((i & k) == 0) ce(a[i], a[p]); else ce(a[p], a[i]); }
;       }
; }
; DEV void peer_top16(const bf16_t* __restrict__ pq, const bf16_t* sk  , float (&l)[16]) {
;     ...
; #pragma unroll
;   for (int nt = 0; nt < 4; nt++)
; #pragma unroll
;     for (int r = 0; r < 4; r++) {
;       l[nt * 4 + r] = __uint_as_float((__float_as_uint(acc[nt][r]) & ~127u) | (unsigned)(nt * 16 + quad * 4 + r));
;       hi[nt * 4 + r] = __uint_as_float((__float_as_uint(acc[nt + 4][r]) & ~127u) | (unsigned)((nt + 4) * 16 + quad * 4 + r));
;     }
;   sort16_desc(l);
;   sort16_desc(hi);
	v_mfma_f32_16x16x32_bf16 v[2:5], v[108:111], v[160:163], v[2:5]
	global_load_dwordx4 v[160:163], v[102:103], off offset:448
	s_movk_i32 s18, 0x100
	v_lshlrev_b32_e32 v0, 2, v0
	s_movk_i32 s18, 0xff80
	v_and_or_b32 v30, v30, s18, v0
	v_and_b32_e32 v27, 0xffffff80, v27
	s_movk_i32 s18, 0x41
	v_or3_b32 v27, v0, v27, s18
	v_and_b32_e32 v28, 0xffffff80, v28
	s_movk_i32 s18, 0x42
	v_or3_b32 v28, v0, v28, s18
	v_and_b32_e32 v29, 0xffffff80, v29
	s_movk_i32 s18, 0x43
	v_or3_b32 v29, v0, v29, s18
	v_and_b32_e32 v18, 0xffffff80, v18
	s_movk_i32 s18, 0x50
	v_or3_b32 v18, v0, v18, s18
	v_and_b32_e32 v19, 0xffffff80, v19
	s_movk_i32 s18, 0x51
	v_or3_b32 v19, v0, v19, s18
	v_and_b32_e32 v20, 0xffffff80, v20
	s_movk_i32 s18, 0x52
	v_or3_b32 v20, v0, v20, s18
	v_and_b32_e32 v21, 0xffffff80, v21
	s_movk_i32 s18, 0x53
	v_or3_b32 v21, v0, v21, s18
	v_and_b32_e32 v10, 0xffffff80, v10
	s_movk_i32 s18, 0x60
	v_or3_b32 v10, v0, v10, s18
	v_and_b32_e32 v11, 0xffffff80, v11
	s_movk_i32 s18, 0x61
	v_or3_b32 v11, v0, v11, s18
	v_and_b32_e32 v12, 0xffffff80, v12
	s_movk_i32 s18, 0x62
	v_or3_b32 v12, v0, v12, s18
	v_and_b32_e32 v13, 0xffffff80, v13
	s_movk_i32 s18, 0x63
	v_or3_b32 v13, v0, v13, s18
	v_and_b32_e32 v2, 0xffffff80, v2
	s_movk_i32 s18, 0x70
	v_or3_b32 v2, v0, v2, s18
	v_and_b32_e32 v3, 0xffffff80, v3
	s_movk_i32 s18, 0x71
	v_and_b32_e32 v26, 0xffffff80, v26
	v_and_b32_e32 v31, 0xffffff80, v31
	v_or3_b32 v3, v0, v3, s18
	v_and_b32_e32 v4, 0xffffff80, v4
	s_movk_i32 s18, 0x72
	v_or3_b32 v26, v0, v26, 64
	v_or3_b32 v31, v0, v31, 1
	v_and_b32_e32 v32, 0xffffff80, v32
	v_and_b32_e32 v33, 0xffffff80, v33
	v_and_b32_e32 v22, 0xffffff80, v22
	v_and_b32_e32 v23, 0xffffff80, v23
	v_and_b32_e32 v24, 0xffffff80, v24
	v_and_b32_e32 v25, 0xffffff80, v25
	v_and_b32_e32 v14, 0xffffff80, v14
	v_and_b32_e32 v15, 0xffffff80, v15
	v_and_b32_e32 v16, 0xffffff80, v16
	v_and_b32_e32 v17, 0xffffff80, v17
	v_and_b32_e32 v6, 0xffffff80, v6
	v_and_b32_e32 v7, 0xffffff80, v7
	v_and_b32_e32 v8, 0xffffff80, v8
	v_or3_b32 v4, v0, v4, s18
	v_and_b32_e32 v9, 0xffffff80, v9
	v_and_b32_e32 v5, 0xffffff80, v5
	s_movk_i32 s18, 0x73
	v_or3_b32 v32, v0, v32, 2
	v_or3_b32 v33, v0, v33, 3
	v_or3_b32 v22, v0, v22, 16
	v_or3_b32 v23, v0, v23, 17
	v_or3_b32 v24, v0, v24, 18
	v_or3_b32 v25, v0, v25, 19
	v_or3_b32 v14, v0, v14, 32
	v_or3_b32 v15, v0, v15, 33
	v_or3_b32 v16, v0, v16, 34
	v_or3_b32 v17, v0, v17, 35
	v_or3_b32 v6, v0, v6, 48
	v_or3_b32 v7, v0, v7, 49
	v_or3_b32 v8, v0, v8, 50
	v_or3_b32 v9, v0, v9, 51
	v_or3_b32 v0, v0, v5, s18
	v_max_f32_e32 v180, v30, v27
	v_min_f32_e32 v27, v30, v27
	v_max_f32_e32 v30, v28, v29
	v_min_f32_e32 v29, v28, v29
	v_max_f32_e32 v28, v180, v30
	v_min_f32_e32 v30, v180, v30
	v_max_f32_e32 v180, v27, v29
	v_min_f32_e32 v29, v27, v29
	v_max_f32_e32 v27, v180, v30
	v_min_f32_e32 v30, v180, v30
	v_max_f32_e32 v180, v18, v19
	v_min_f32_e32 v19, v18, v19
	v_max_f32_e32 v18, v20, v21
	v_min_f32_e32 v21, v20, v21
	v_max_f32_e32 v20, v180, v18
	v_min_f32_e32 v18, v180, v18
	v_max_f32_e32 v180, v19, v21
	v_min_f32_e32 v21, v19, v21
	v_max_f32_e32 v19, v180, v18
	v_min_f32_e32 v18, v180, v18
	v_max_f32_e32 v180, v28, v20
	v_min_f32_e32 v20, v28, v20
	v_max_f32_e32 v28, v30, v18
	v_min_f32_e32 v18, v30, v18
	v_max_f32_e32 v30, v28, v20
	v_min_f32_e32 v20, v28, v20
	v_max_f32_e32 v28, v27, v19
	v_min_f32_e32 v19, v27, v19
	v_max_f32_e32 v27, v29, v21
	v_min_f32_e32 v21, v29, v21
	v_max_f32_e32 v29, v27, v19
	v_min_f32_e32 v19, v27, v19
	v_max_f32_e32 v27, v28, v30
	v_min_f32_e32 v30, v28, v30
	v_max_f32_e32 v28, v29, v20
	v_min_f32_e32 v20, v29, v20
	v_max_f32_e32 v29, v19, v18
	v_min_f32_e32 v18, v19, v18
	v_max_f32_e32 v19, v10, v11
	v_min_f32_e32 v11, v10, v11
	v_max_f32_e32 v10, v12, v13
	v_min_f32_e32 v13, v12, v13
	v_max_f32_e32 v12, v19, v10
	v_min_f32_e32 v10, v19, v10
	v_max_f32_e32 v19, v11, v13
	v_min_f32_e32 v13, v11, v13
	v_max_f32_e32 v11, v19, v10
	v_min_f32_e32 v10, v19, v10
	v_max_f32_e32 v19, v2, v3
	v_min_f32_e32 v3, v2, v3
	v_max_f32_e32 v2, v26, v31
	v_min_f32_e32 v31, v26, v31
	v_max_f32_e32 v26, v19, v2
	v_min_f32_e32 v2, v19, v2
	v_max_f32_e32 v19, v3, v31
	v_min_f32_e32 v31, v3, v31
	v_max_f32_e32 v3, v19, v2
	v_min_f32_e32 v2, v19, v2
	v_max_f32_e32 v19, v12, v26
	v_min_f32_e32 v26, v12, v26
	v_max_f32_e32 v12, v10, v2
	v_min_f32_e32 v2, v10, v2
	v_max_f32_e32 v10, v12, v26
	v_min_f32_e32 v26, v12, v26
	v_max_f32_e32 v12, v11, v3
	v_min_f32_e32 v3, v11, v3
	v_max_f32_e32 v11, v13, v31
	v_min_f32_e32 v31, v13, v31
	v_max_f32_e32 v13, v11, v3
	v_min_f32_e32 v3, v11, v3
	v_max_f32_e32 v11, v12, v10
	v_min_f32_e32 v10, v12, v10
	v_max_f32_e32 v12, v13, v26
	v_min_f32_e32 v26, v13, v26
	v_max_f32_e32 v13, v3, v2
	v_min_f32_e32 v2, v3, v2
	v_max_f32_e32 v3, v180, v19
	v_min_f32_e32 v19, v180, v19
	v_max_f32_e32 v180, v20, v26
	v_min_f32_e32 v26, v20, v26
	v_max_f32_e32 v20, v180, v19
	v_min_f32_e32 v19, v180, v19
	v_max_f32_e32 v180, v30, v10
	v_min_f32_e32 v10, v30, v10
	v_max_f32_e32 v30, v18, v2
	v_min_f32_e32 v2, v18, v2
	v_max_f32_e32 v18, v30, v10
	v_min_f32_e32 v10, v30, v10
	v_max_f32_e32 v30, v180, v20
	v_min_f32_e32 v20, v180, v20
	v_max_f32_e32 v180, v18, v19
	v_min_f32_e32 v19, v18, v19
	v_max_f32_e32 v18, v10, v26
	v_min_f32_e32 v26, v10, v26
	v_max_f32_e32 v10, v27, v11
	v_min_f32_e32 v11, v27, v11
	v_max_f32_e32 v27, v29, v13
	v_min_f32_e32 v13, v29, v13
	v_max_f32_e32 v29, v27, v11
	v_min_f32_e32 v11, v27, v11
	v_max_f32_e32 v27, v28, v12
	v_min_f32_e32 v12, v28, v12
	v_max_f32_e32 v28, v21, v31
	v_min_f32_e32 v31, v21, v31
	v_max_f32_e32 v21, v28, v12
	v_min_f32_e32 v12, v28, v12
	v_max_f32_e32 v28, v27, v29
	v_min_f32_e32 v29, v27, v29
; DEV void ce(float& a, float& b) { float hi = fmaxf(a, b), lo = fminf(a, b); a = hi; b = lo; }
; DEV void bitonic16(float (&l)[16]) {
; #pragma unroll
;   for (int s = 8; s > 0; s >>= 1)
; #pragma unroll
;     for (int i = 0; i < 16; i++)
;       if (!(i & s)) ce(l[i], l[i + s]);
; }
; DEV void peer_top16(const bf16_t* __restrict__ pq, const bf16_t* sk  , float (&l)[16]) {
;     ...
;   sort16_desc(l);
;   sort16_desc(hi);
; #pragma unroll
;   for (int i = 0; i < 16; i++) l[i] = fmaxf(l[i], hi[15 - i]);
;   bitonic16(l);
;   merge_xor(l, 16);
	v_max_f32_e32 v27, v21, v11
	v_min_f32_e32 v11, v21, v11
	v_max_f32_e32 v21, v12, v13
	v_min_f32_e32 v13, v12, v13
	v_max_f32_e32 v12, v10, v30
	v_min_f32_e32 v30, v10, v30
	v_max_f32_e32 v10, v28, v20
	v_min_f32_e32 v20, v28, v20
	v_max_f32_e32 v28, v29, v180
	v_min_f32_e32 v180, v29, v180
	v_max_f32_e32 v29, v27, v19
	v_min_f32_e32 v19, v27, v19
	v_max_f32_e32 v27, v11, v18
	v_min_f32_e32 v18, v11, v18
	v_max_f32_e32 v11, v21, v26
	v_min_f32_e32 v26, v21, v26
	v_max_f32_e32 v21, v13, v2
	v_min_f32_e32 v2, v13, v2
	v_max_f32_e32 v13, v4, v32
	v_min_f32_e32 v32, v4, v32
	v_max_f32_e32 v4, v33, v22
	v_min_f32_e32 v22, v33, v22
	v_max_f32_e32 v33, v13, v4
	v_min_f32_e32 v4, v13, v4
	v_max_f32_e32 v13, v32, v22
	v_min_f32_e32 v22, v32, v22
	v_max_f32_e32 v32, v13, v4
	v_min_f32_e32 v4, v13, v4
	v_max_f32_e32 v13, v23, v24
	v_min_f32_e32 v24, v23, v24
	v_max_f32_e32 v23, v25, v14
	v_min_f32_e32 v14, v25, v14
	v_max_f32_e32 v25, v13, v23
	v_min_f32_e32 v23, v13, v23
	v_max_f32_e32 v13, v24, v14
	v_min_f32_e32 v14, v24, v14
	v_max_f32_e32 v24, v13, v23
	v_min_f32_e32 v23, v13, v23
	v_max_f32_e32 v13, v33, v25
	v_min_f32_e32 v25, v33, v25
	v_max_f32_e32 v33, v4, v23
	v_min_f32_e32 v23, v4, v23
	v_max_f32_e32 v4, v33, v25
	v_min_f32_e32 v25, v33, v25
	v_max_f32_e32 v33, v32, v24
	v_min_f32_e32 v24, v32, v24
	v_max_f32_e32 v32, v22, v14
	v_min_f32_e32 v14, v22, v14
	v_max_f32_e32 v22, v32, v24
	v_min_f32_e32 v24, v32, v24
	v_max_f32_e32 v32, v33, v4
	v_min_f32_e32 v4, v33, v4
	v_max_f32_e32 v33, v22, v25
	v_min_f32_e32 v25, v22, v25
	v_max_f32_e32 v22, v24, v23
	v_min_f32_e32 v23, v24, v23
	v_max_f32_e32 v24, v15, v16
	v_min_f32_e32 v16, v15, v16
	v_max_f32_e32 v15, v17, v6
	v_min_f32_e32 v6, v17, v6
	v_max_f32_e32 v17, v24, v15
	v_min_f32_e32 v15, v24, v15
	v_max_f32_e32 v24, v16, v6
	v_min_f32_e32 v6, v16, v6
	v_max_f32_e32 v16, v24, v15
	v_min_f32_e32 v15, v24, v15
	v_max_f32_e32 v24, v7, v8
	v_min_f32_e32 v8, v7, v8
	v_max_f32_e32 v7, v9, v0
	v_min_f32_e32 v0, v9, v0
	v_max_f32_e32 v9, v24, v7
	v_min_f32_e32 v7, v24, v7
	v_max_f32_e32 v24, v8, v0
	v_min_f32_e32 v0, v8, v0
	v_max_f32_e32 v8, v24, v7
	v_min_f32_e32 v7, v24, v7
	v_max_f32_e32 v24, v17, v9
	v_min_f32_e32 v9, v17, v9
	v_max_f32_e32 v17, v15, v7
	v_min_f32_e32 v7, v15, v7
	v_max_f32_e32 v15, v17, v9
	v_min_f32_e32 v9, v17, v9
	v_max_f32_e32 v17, v16, v8
	v_min_f32_e32 v8, v16, v8
	v_max_f32_e32 v16, v6, v0
	v_min_f32_e32 v0, v6, v0
	v_max_f32_e32 v6, v16, v8
	v_min_f32_e32 v8, v16, v8
	v_max_f32_e32 v16, v17, v15
	v_min_f32_e32 v15, v17, v15
	v_max_f32_e32 v17, v6, v9
	v_min_f32_e32 v9, v6, v9
	v_max_f32_e32 v6, v8, v7
	v_min_f32_e32 v7, v8, v7
	v_max_f32_e32 v8, v13, v24
	v_min_f32_e32 v24, v13, v24
	v_max_f32_e32 v13, v25, v9
	v_min_f32_e32 v9, v25, v9
	v_max_f32_e32 v25, v13, v24
	v_min_f32_e32 v24, v13, v24
	v_max_f32_e32 v13, v4, v15
	v_min_f32_e32 v15, v4, v15
	v_max_f32_e32 v4, v23, v7
	v_min_f32_e32 v7, v23, v7
	v_max_f32_e32 v23, v4, v15
	v_min_f32_e32 v15, v4, v15
	v_max_f32_e32 v4, v13, v25
	v_min_f32_e32 v25, v13, v25
	v_max_f32_e32 v13, v23, v24
	v_min_f32_e32 v24, v23, v24
	v_max_f32_e32 v23, v15, v9
	v_min_f32_e32 v9, v15, v9
	v_max_f32_e32 v15, v32, v16
	v_min_f32_e32 v16, v32, v16
	v_max_f32_e32 v32, v22, v6
	v_min_f32_e32 v6, v22, v6
	v_max_f32_e32 v22, v32, v16
	v_min_f32_e32 v16, v32, v16
	v_max_f32_e32 v32, v33, v17
	v_min_f32_e32 v17, v33, v17
	v_max_f32_e32 v33, v14, v0
	v_min_f32_e32 v0, v14, v0
	v_max_f32_e32 v14, v33, v17
	v_min_f32_e32 v17, v33, v17
	v_max_f32_e32 v33, v32, v22
	v_min_f32_e32 v22, v32, v22
	v_max_f32_e32 v32, v14, v16
	v_min_f32_e32 v16, v14, v16
	v_max_f32_e32 v14, v17, v6
	v_min_f32_e32 v6, v17, v6
	v_max_f32_e32 v17, v15, v4
	v_min_f32_e32 v4, v15, v4
	v_max_f32_e32 v15, v33, v25
	v_min_f32_e32 v25, v33, v25
	v_max_f32_e32 v33, v22, v13
	v_min_f32_e32 v13, v22, v13
	v_max_f32_e32 v22, v32, v24
	v_min_f32_e32 v24, v32, v24
	v_max_f32_e32 v32, v16, v23
	v_min_f32_e32 v23, v16, v23
	v_max_f32_e32 v16, v14, v9
	v_min_f32_e32 v9, v14, v9
	v_max_f32_e32 v14, v6, v7
	v_min_f32_e32 v7, v6, v7
	v_max_f32_e32 v3, v3, v0
	v_max_f32_e32 v12, v12, v7
	v_max_f32_e32 v30, v30, v14
	v_max_f32_e32 v10, v10, v9
	v_max_f32_e32 v20, v20, v16
	v_max_f32_e32 v28, v28, v23
	v_max_f32_e32 v180, v180, v32
	v_max_f32_e32 v29, v29, v24
	v_max_f32_e32 v19, v19, v22
	v_max_f32_e32 v27, v27, v13
	v_max_f32_e32 v18, v18, v33
	v_max_f32_e32 v11, v11, v25
	v_max_f32_e32 v26, v26, v15
	v_max_f32_e32 v21, v21, v4
	v_max_f32_e32 v2, v2, v17
	v_max_f32_e32 v31, v31, v8
	v_max_f32_e32 v6, v3, v19
	v_min_f32_e32 v19, v3, v19
	v_max_f32_e32 v3, v12, v27
	v_min_f32_e32 v27, v12, v27
	v_max_f32_e32 v12, v30, v18
	v_min_f32_e32 v18, v30, v18
	v_max_f32_e32 v30, v10, v11
	v_min_f32_e32 v11, v10, v11
	v_max_f32_e32 v10, v20, v26
	v_min_f32_e32 v26, v20, v26
	v_max_f32_e32 v20, v28, v21
	v_min_f32_e32 v21, v28, v21
	v_max_f32_e32 v28, v180, v2
	v_min_f32_e32 v2, v180, v2
	v_max_f32_e32 v180, v29, v31
	v_min_f32_e32 v31, v29, v31
	v_max_f32_e32 v29, v6, v10
	v_min_f32_e32 v10, v6, v10
	v_max_f32_e32 v6, v3, v20
	v_min_f32_e32 v20, v3, v20
	v_max_f32_e32 v3, v12, v28
	v_min_f32_e32 v28, v12, v28
	v_max_f32_e32 v12, v30, v180
	v_min_f32_e32 v180, v30, v180
	v_max_f32_e32 v30, v19, v26
	v_min_f32_e32 v26, v19, v26
	v_max_f32_e32 v19, v27, v21
	v_min_f32_e32 v21, v27, v21
	v_max_f32_e32 v27, v18, v2
	v_min_f32_e32 v2, v18, v2
	v_max_f32_e32 v18, v11, v31
	v_min_f32_e32 v31, v11, v31
	v_max_f32_e32 v11, v29, v3
	v_min_f32_e32 v3, v29, v3
	v_max_f32_e32 v29, v6, v12
	v_min_f32_e32 v12, v6, v12
	v_max_f32_e32 v6, v10, v28
	v_min_f32_e32 v28, v10, v28
	v_max_f32_e32 v10, v20, v180
	v_min_f32_e32 v180, v20, v180
	v_max_f32_e32 v20, v30, v27
	v_min_f32_e32 v27, v30, v27
	v_max_f32_e32 v30, v19, v18
	v_min_f32_e32 v18, v19, v18
	v_max_f32_e32 v19, v26, v2
	v_min_f32_e32 v2, v26, v2
	v_max_f32_e32 v26, v21, v31
	v_min_f32_e32 v31, v21, v31
	v_max_f32_e32 v164, v11, v29
	v_min_f32_e32 v165, v11, v29
	v_max_f32_e32 v166, v3, v12
	v_min_f32_e32 v167, v3, v12
	v_max_f32_e32 v168, v6, v10
	v_min_f32_e32 v169, v6, v10
	v_max_f32_e32 v170, v28, v180
	v_min_f32_e32 v171, v28, v180
	v_max_f32_e32 v172, v20, v30
	v_min_f32_e32 v173, v20, v30
	v_max_f32_e32 v174, v27, v18
	v_min_f32_e32 v175, v27, v18
	v_max_f32_e32 v176, v19, v26
	v_min_f32_e32 v177, v19, v26
	v_max_f32_e32 v178, v2, v31
	v_min_f32_e32 v179, v2, v31
	v_mbcnt_hi_u32_b32 v2, -1, v215
	v_and_b32_e32 v19, 64, v2
	v_xor_b32_e32 v18, 16, v2
	v_add_u32_e32 v19, 64, v19
	v_cmp_lt_i32_e32 vcc, v18, v19
	s_add_u32 s8, s12, s8
	s_addc_u32 s9, s13, s9
	v_cndmask_b32_e32 v18, v2, v18, vcc
	v_lshlrev_b32_e32 v95, 2, v18
	ds_bpermute_b32 v18, v95, v179
	ds_bpermute_b32 v20, v95, v178
	ds_bpermute_b32 v21, v95, v177
	ds_bpermute_b32 v22, v95, v176
	ds_bpermute_b32 v23, v95, v175
	ds_bpermute_b32 v24, v95, v174
	s_waitcnt lgkmcnt(5)
; DEV int tidx() { int t = threadIdx.x; asm volatile("" : "+v"(t)); return t; }
; DEV void merge_xor(float (&l)[16], int mask) {
;   float t[16];
; #pragma unroll
;   for (int i = 0; i < 16; i++) t[i] = __shfl_xor(l[15 - i], mask);
; #pragma unroll
;   for (int i = 0; i < 16; i++) l[i] = fmaxf(l[i], t[i]);
;   bitonic16(l);
; DEV void peer_top16(const bf16_t* __restrict__ pq, const bf16_t* sk  , float (&l)[16]) {
;   const int lane = tidx() & 63, l15 = lane & 15, quad = lane >> 4;
;   f32x4 acc[8];
; #pragma unroll
;   for (int nt = 0; nt < 8; nt++) acc[nt] = (f32x4){0.f, 0.f, 0.f, 0.f};
	ds_bpermute_b32 v25, v95, v173
	ds_bpermute_b32 v39, v95, v164
	v_max_f32_e32 v3, v164, v18
	s_waitcnt lgkmcnt(6)
	ds_bpermute_b32 v26, v95, v172
	ds_bpermute_b32 v33, v95, v165
	v_max_f32_e32 v9, v165, v20
	s_waitcnt lgkmcnt(7)
	ds_bpermute_b32 v27, v95, v171
	ds_bpermute_b32 v32, v95, v166
	v_max_f32_e32 v17, v166, v21
	s_waitcnt lgkmcnt(8)
	ds_bpermute_b32 v28, v95, v170
	ds_bpermute_b32 v31, v95, v167
	v_max_f32_e32 v11, v167, v22
	s_waitcnt lgkmcnt(9)
	ds_bpermute_b32 v29, v95, v169
	ds_bpermute_b32 v30, v95, v168
	v_max_f32_e32 v13, v168, v23
	s_waitcnt lgkmcnt(10)
	v_max_f32_e32 v10, v169, v24
	s_waitcnt lgkmcnt(9)
	v_max_f32_e32 v16, v170, v25
	s_waitcnt lgkmcnt(7)
	v_max_f32_e32 v5, v171, v26
	s_waitcnt lgkmcnt(5)
	v_max_f32_e32 v7, v172, v27
	s_waitcnt lgkmcnt(3)
	v_max_f32_e32 v14, v173, v28
	s_waitcnt lgkmcnt(1)
	v_max_f32_e32 v15, v174, v29
	s_waitcnt lgkmcnt(0)
	v_max_f32_e32 v4, v175, v30
	v_max_f32_e32 v12, v176, v31
	v_max_f32_e32 v6, v177, v32
	v_max_f32_e32 v8, v178, v33
	v_max_f32_e32 v0, v179, v39
	v_max_f32_e32 v18, v3, v7
	v_min_f32_e32 v3, v3, v7
	v_max_f32_e32 v7, v9, v14
	v_min_f32_e32 v9, v9, v14
	v_max_f32_e32 v14, v17, v15
	v_min_f32_e32 v15, v17, v15
	v_max_f32_e32 v17, v11, v4
	v_min_f32_e32 v4, v11, v4
	v_max_f32_e32 v11, v13, v12
	v_min_f32_e32 v12, v13, v12
	v_max_f32_e32 v13, v10, v6
	v_min_f32_e32 v6, v10, v6
	v_max_f32_e32 v10, v16, v8
	v_min_f32_e32 v8, v16, v8
	v_max_f32_e32 v16, v5, v0
	v_min_f32_e32 v0, v5, v0
	v_max_f32_e32 v5, v18, v11
	v_min_f32_e32 v11, v18, v11
	v_max_f32_e32 v18, v7, v13
	v_min_f32_e32 v7, v7, v13
	v_max_f32_e32 v13, v14, v10
	v_min_f32_e32 v10, v14, v10
	v_max_f32_e32 v14, v17, v16
	v_min_f32_e32 v16, v17, v16
	v_max_f32_e32 v17, v3, v12
	v_min_f32_e32 v3, v3, v12
	v_max_f32_e32 v12, v9, v6
	v_min_f32_e32 v6, v9, v6
	v_max_f32_e32 v9, v15, v8
	v_min_f32_e32 v8, v15, v8
	v_max_f32_e32 v15, v4, v0
	v_min_f32_e32 v0, v4, v0
	v_max_f32_e32 v4, v5, v13
	v_min_f32_e32 v5, v5, v13
	v_max_f32_e32 v13, v18, v14
	v_min_f32_e32 v14, v18, v14
	v_max_f32_e32 v18, v11, v10
	v_min_f32_e32 v10, v11, v10
	v_max_f32_e32 v11, v7, v16
	v_min_f32_e32 v7, v7, v16
	v_max_f32_e32 v16, v17, v9
	v_min_f32_e32 v9, v17, v9
	v_max_f32_e32 v17, v12, v15
	v_min_f32_e32 v12, v12, v15
	v_max_f32_e32 v15, v3, v8
	v_min_f32_e32 v3, v3, v8
	v_max_f32_e32 v8, v6, v0
	v_min_f32_e32 v0, v6, v0
	v_max_f32_e32 v43, v3, v0
	v_min_f32_e32 v39, v3, v0
	v_xor_b32_e32 v0, 32, v2
	v_cmp_lt_i32_e32 vcc, v0, v19
	v_max_f32_e32 v109, v4, v13
	v_min_f32_e32 v107, v4, v13
	v_cndmask_b32_e32 v0, v2, v0, vcc
	v_max_f32_e32 v105, v5, v14
	v_min_f32_e32 v103, v5, v14
	v_max_f32_e32 v87, v18, v11
	v_min_f32_e32 v79, v18, v11
	v_max_f32_e32 v75, v10, v7
	v_min_f32_e32 v71, v10, v7
	v_max_f32_e32 v67, v16, v17
	v_min_f32_e32 v63, v16, v17
	v_max_f32_e32 v59, v9, v12
	v_min_f32_e32 v55, v9, v12
	v_max_f32_e32 v51, v15, v8
	v_min_f32_e32 v47, v15, v8
	v_lshlrev_b32_e32 v99, 2, v0
	v_mov_b32_e32 v0, v195
	ds_bpermute_b32 v121, v99, v39
	ds_bpermute_b32 v120, v99, v43
	ds_bpermute_b32 v119, v99, v47
	ds_bpermute_b32 v118, v99, v51
	ds_bpermute_b32 v116, v99, v55
	ds_bpermute_b32 v115, v99, v59
	ds_bpermute_b32 v114, v99, v63
	ds_bpermute_b32 v113, v99, v67
	ds_bpermute_b32 v112, v99, v71
	ds_bpermute_b32 v111, v99, v75
	ds_bpermute_b32 v110, v99, v79
	ds_bpermute_b32 v108, v99, v87
	ds_bpermute_b32 v106, v99, v103
	ds_bpermute_b32 v104, v99, v105
	ds_bpermute_b32 v91, v99, v107
	ds_bpermute_b32 v83, v99, v109
	s_mov_b32 s18, 0
	v_bfe_u32 v102, v0, 4, 2
	v_and_b32_e32 v2, 15, v0
	v_lshlrev_b32_e32 v0, 4, v102
	v_mad_u32_u24 v122, v2, s20, v0
	v_lshl_add_u64 v[2:3], v[100:101], 0, v[0:1]
	v_lshl_add_u64 v[100:101], s[8:9], 0, v[2:3]
	v_mov_b32_e32 v2, 0
	v_mov_b32_e32 v3, v2
	v_mov_b32_e32 v4, v2
	v_mov_b32_e32 v5, v2
	v_mov_b32_e32 v10, v2
	v_mov_b32_e32 v11, v2
	v_mov_b32_e32 v12, v2
	v_mov_b32_e32 v13, v2
	v_mov_b32_e32 v18, v2
	v_mov_b32_e32 v19, v2
	v_mov_b32_e32 v20, v2
	v_mov_b32_e32 v21, v2
	v_mov_b32_e32 v26, v2
	v_mov_b32_e32 v27, v2
	v_mov_b32_e32 v28, v2
	v_mov_b32_e32 v29, v2
	v_mov_b32_e32 v6, v2
	v_mov_b32_e32 v7, v2
	v_mov_b32_e32 v8, v2
	v_mov_b32_e32 v9, v2
	v_mov_b32_e32 v14, v2
	v_mov_b32_e32 v15, v2
	v_mov_b32_e32 v16, v2
	v_mov_b32_e32 v17, v2
	v_mov_b32_e32 v22, v2
	v_mov_b32_e32 v23, v2
	v_mov_b32_e32 v24, v2
	v_mov_b32_e32 v25, v2
	v_mov_b32_e32 v30, v2
	v_mov_b32_e32 v31, v2
	v_mov_b32_e32 v32, v2
	v_mov_b32_e32 v33, v2
; DEV f32x4 mfma16(bf16x8 a, bf16x8 b, f32x4 c) { return __builtin_amdgcn_mfma_f32_16x16x32_bf16(a, b, c, 0, 0, 0); }
; DEV void peer_top16(const bf16_t* __restrict__ pq, const bf16_t* sk  , float (&l)[16]) {
;     ...
; #pragma unroll 1
;   for (int ks = 0; ks < 4; ks++) {
;     const bf16x8 bqk = *(const bf16x8*)(pq + ks * 32 + quad * 8);
; #pragma unroll
;     for (int nt = 0; nt < 8; nt++) {
;       bf16x8 ak = *(const bf16x8*)(sk + (nt * 16 + l15) * 144 + ks * 32 + quad * 8);
;       acc[nt] = mfma16(ak, bqk, acc[nt]);
;     }
;   }
.LBB0_635:
	v_add_u32_e32 v139, 0x10e00, v122
	ds_read_b128 v[164:167], v122 offset:36864
	ds_read_b128 v[168:171], v122 offset:41472
	ds_read_b128 v[172:175], v122 offset:46080
	ds_read_b128 v[176:179], v122 offset:50688
	ds_read_b128 v[180:183], v122 offset:55296
	ds_read_b128 v[184:187], v122 offset:59904
	ds_read_b128 v[188:191], v122 offset:64512
	ds_read_b128 v[128:131], v139
	s_waitcnt vmcnt(3) lgkmcnt(7)
	v_mfma_f32_16x16x32_bf16 v[30:33], v[164:167], v[148:151], v[30:33]
	ds_read_b128 v[164:167], v122 offset:36928
	s_waitcnt lgkmcnt(7)
	v_mfma_f32_16x16x32_bf16 v[22:25], v[168:171], v[148:151], v[22:25]
	ds_read_b128 v[168:171], v122 offset:41536
	s_waitcnt lgkmcnt(7)
	v_mfma_f32_16x16x32_bf16 v[14:17], v[172:175], v[148:151], v[14:17]
	ds_read_b128 v[172:175], v122 offset:46144
	s_waitcnt lgkmcnt(7)
	v_mfma_f32_16x16x32_bf16 v[6:9], v[176:179], v[148:151], v[6:9]
	ds_read_b128 v[176:179], v122 offset:50752
	s_waitcnt lgkmcnt(7)
	v_mfma_f32_16x16x32_bf16 v[26:29], v[180:183], v[148:151], v[26:29]
	ds_read_b128 v[180:183], v122 offset:55360
	s_waitcnt lgkmcnt(7)
	v_mfma_f32_16x16x32_bf16 v[18:21], v[184:187], v[148:151], v[18:21]
	ds_read_b128 v[184:187], v122 offset:59968
	s_waitcnt lgkmcnt(7)
	v_mfma_f32_16x16x32_bf16 v[10:13], v[188:191], v[148:151], v[10:13]
	ds_read_b128 v[188:191], v122 offset:64576
	s_waitcnt lgkmcnt(7)
	v_mfma_f32_16x16x32_bf16 v[2:5], v[128:131], v[148:151], v[2:5]
	ds_read_b128 v[128:131], v139 offset:64
	s_waitcnt vmcnt(2) lgkmcnt(7)
	v_mfma_f32_16x16x32_bf16 v[30:33], v[164:167], v[152:155], v[30:33]
	ds_read_b128 v[164:167], v122 offset:36992
	s_waitcnt lgkmcnt(7)
	v_mfma_f32_16x16x32_bf16 v[22:25], v[168:171], v[152:155], v[22:25]
	ds_read_b128 v[168:171], v122 offset:41600
	s_waitcnt lgkmcnt(7)
	v_mfma_f32_16x16x32_bf16 v[14:17], v[172:175], v[152:155], v[14:17]
	ds_read_b128 v[172:175], v122 offset:46208
	s_waitcnt lgkmcnt(7)
	v_mfma_f32_16x16x32_bf16 v[6:9], v[176:179], v[152:155], v[6:9]
	ds_read_b128 v[176:179], v122 offset:50816
	s_waitcnt lgkmcnt(7)
	v_mfma_f32_16x16x32_bf16 v[26:29], v[180:183], v[152:155], v[26:29]
	ds_read_b128 v[180:183], v122 offset:55424
	s_waitcnt lgkmcnt(7)
	v_mfma_f32_16x16x32_bf16 v[18:21], v[184:187], v[152:155], v[18:21]
	ds_read_b128 v[184:187], v122 offset:60032
	s_waitcnt lgkmcnt(7)
	v_mfma_f32_16x16x32_bf16 v[10:13], v[188:191], v[152:155], v[10:13]
	ds_read_b128 v[188:191], v122 offset:64640
	s_waitcnt lgkmcnt(7)
	v_mfma_f32_16x16x32_bf16 v[2:5], v[128:131], v[152:155], v[2:5]
	ds_read_b128 v[128:131], v139 offset:128
	s_waitcnt vmcnt(1) lgkmcnt(7)
	v_mfma_f32_16x16x32_bf16 v[30:33], v[164:167], v[156:159], v[30:33]
	ds_read_b128 v[164:167], v122 offset:37056
	s_waitcnt lgkmcnt(7)
	v_mfma_f32_16x16x32_bf16 v[22:25], v[168:171], v[156:159], v[22:25]
	ds_read_b128 v[168:171], v122 offset:41664
	s_waitcnt lgkmcnt(7)
	v_mfma_f32_16x16x32_bf16 v[14:17], v[172:175], v[156:159], v[14:17]
	ds_read_b128 v[172:175], v122 offset:46272
	s_waitcnt lgkmcnt(7)
	v_mfma_f32_16x16x32_bf16 v[6:9], v[176:179], v[156:159], v[6:9]
	ds_read_b128 v[176:179], v122 offset:50880
	s_waitcnt lgkmcnt(7)
	v_mfma_f32_16x16x32_bf16 v[26:29], v[180:183], v[156:159], v[26:29]
	ds_read_b128 v[180:183], v122 offset:55488
	s_waitcnt lgkmcnt(7)
	v_mfma_f32_16x16x32_bf16 v[18:21], v[184:187], v[156:159], v[18:21]
	ds_read_b128 v[184:187], v122 offset:60096
	s_waitcnt lgkmcnt(7)
	v_mfma_f32_16x16x32_bf16 v[10:13], v[188:191], v[156:159], v[10:13]
	ds_read_b128 v[188:191], v122 offset:64704
	s_waitcnt lgkmcnt(7)
	v_mfma_f32_16x16x32_bf16 v[2:5], v[128:131], v[156:159], v[2:5]
	ds_read_b128 v[128:131], v139 offset:192
	s_waitcnt vmcnt(0) lgkmcnt(7)
	v_mfma_f32_16x16x32_bf16 v[30:33], v[164:167], v[160:163], v[30:33]
	s_waitcnt lgkmcnt(6)
	v_mfma_f32_16x16x32_bf16 v[22:25], v[168:171], v[160:163], v[22:25]
	s_waitcnt lgkmcnt(5)
	v_mfma_f32_16x16x32_bf16 v[14:17], v[172:175], v[160:163], v[14:17]
	s_waitcnt lgkmcnt(4)
	v_mfma_f32_16x16x32_bf16 v[6:9], v[176:179], v[160:163], v[6:9]
	s_waitcnt lgkmcnt(3)
	v_mfma_f32_16x16x32_bf16 v[26:29], v[180:183], v[160:163], v[26:29]
	s_waitcnt lgkmcnt(2)
	v_mfma_f32_16x16x32_bf16 v[18:21], v[184:187], v[160:163], v[18:21]
	s_waitcnt lgkmcnt(1)
	v_mfma_f32_16x16x32_bf16 v[10:13], v[188:191], v[160:163], v[10:13]
	s_waitcnt lgkmcnt(0)
; DEV void ce(float& a, float& b) { float hi = fmaxf(a, b), lo = fminf(a, b); a = hi; b = lo; }
; DEV void sort16_desc(float (&a)[16]) {
; #pragma unroll
;   for (int k = 2; k <= 16; k <<= 1)
; #pragma unroll
;     for (int j = k >> 1; j > 0; j >>= 1)
; #pragma unroll
;       for (int i = 0; i < 16; i++) {
;         const int p = i ^ j;
;         if (p > i) { if ((i & k) == 0) ce(a[i], a[p]); else ce(a[p], a[i]); }
;       }
; }
; DEV void merge_xor(float (&l)[16], int mask) {
;   float t[16];
; #pragma unroll
;   for (int i = 0; i < 16; i++) t[i] = __shfl_xor(l[15 - i], mask);
; #pragma unroll
;   for (int i = 0; i < 16; i++) l[i] = fmaxf(l[i], t[i]);
;   bitonic16(l);
; DEV void peer_top16(const bf16_t* __restrict__ pq, const bf16_t* sk  , float (&l)[16]) {
;     ...
; #pragma unroll
;   for (int nt = 0; nt < 4; nt++)
; #pragma unroll
;     for (int r = 0; r < 4; r++) {
;       l[nt * 4 + r] = __uint_as_float((__float_as_uint(acc[nt][r]) & ~127u) | (unsigned)(nt * 16 + quad * 4 + r));
;       hi[nt * 4 + r] = __uint_as_float((__float_as_uint(acc[nt + 4][r]) & ~127u) | (unsigned)((nt + 4) * 16 + quad * 4 + r));
;     }
;   sort16_desc(l);
;   sort16_desc(hi);
	v_mfma_f32_16x16x32_bf16 v[2:5], v[128:131], v[160:163], v[2:5]
	s_movk_i32 s18, 0x100
	v_max_f32_e32 v0, v109, v121
	v_max_f32_e32 v100, v107, v120
	v_max_f32_e32 v101, v105, v119
	v_max_f32_e32 v103, v103, v118
	v_max_f32_e32 v87, v87, v116
	v_max_f32_e32 v79, v79, v115
	v_max_f32_e32 v75, v75, v114
	v_max_f32_e32 v71, v71, v113
	v_max_f32_e32 v67, v67, v112
	v_max_f32_e32 v63, v63, v111
	v_max_f32_e32 v59, v59, v110
	v_max_f32_e32 v55, v55, v108
	v_max_f32_e32 v51, v51, v106
	v_max_f32_e32 v47, v47, v104
	v_max_f32_e32 v43, v43, v91
	v_max_f32_e32 v39, v39, v83
	v_max_f32_e32 v83, v0, v67
	v_min_f32_e32 v0, v0, v67
	v_max_f32_e32 v67, v100, v63
	v_min_f32_e32 v63, v100, v63
	v_max_f32_e32 v91, v101, v59
	v_min_f32_e32 v59, v101, v59
	v_max_f32_e32 v100, v103, v55
	v_min_f32_e32 v55, v103, v55
	v_max_f32_e32 v101, v87, v51
	v_min_f32_e32 v51, v87, v51
	v_max_f32_e32 v87, v79, v47
	v_min_f32_e32 v47, v79, v47
	v_max_f32_e32 v79, v75, v43
	v_min_f32_e32 v43, v75, v43
	v_max_f32_e32 v75, v71, v39
	v_min_f32_e32 v39, v71, v39
	v_max_f32_e32 v71, v83, v101
	v_min_f32_e32 v101, v83, v101
	v_max_f32_e32 v103, v67, v87
	v_min_f32_e32 v67, v67, v87
	v_max_f32_e32 v87, v91, v79
	v_min_f32_e32 v79, v91, v79
	v_max_f32_e32 v91, v100, v75
	v_min_f32_e32 v75, v100, v75
	v_max_f32_e32 v100, v0, v51
	v_min_f32_e32 v0, v0, v51
	v_max_f32_e32 v51, v63, v47
	v_max_f32_e32 v105, v59, v43
	v_min_f32_e32 v43, v59, v43
	v_max_f32_e32 v59, v55, v39
	v_min_f32_e32 v107, v101, v79
	v_min_f32_e32 v108, v67, v75
	v_min_f32_e32 v110, v51, v59
	v_max_f32_e32 v79, v101, v79
	v_max_f32_e32 v67, v67, v75
	v_max_f32_e32 v101, v100, v105
	v_max_f32_e32 v51, v51, v59
	v_min_f32_e32 v75, v79, v67
	v_min_f32_e32 v59, v101, v51
	v_max_f32_e32 v79, v79, v67
	v_max_f32_e32 v67, v101, v51
	v_lshlrev_b32_e32 v101, 2, v102
	s_movk_i32 s8, 0xff80
	v_and_or_b32 v30, v30, s8, v101
	v_and_b32_e32 v27, 0xffffff80, v27
	s_movk_i32 s8, 0x41
	v_or3_b32 v27, v101, v27, s8
	v_and_b32_e32 v28, 0xffffff80, v28
	s_movk_i32 s8, 0x42
	v_or3_b32 v28, v101, v28, s8
	v_and_b32_e32 v29, 0xffffff80, v29
	s_movk_i32 s8, 0x43
	v_or3_b32 v29, v101, v29, s8
	v_and_b32_e32 v18, 0xffffff80, v18
	s_movk_i32 s8, 0x50
	v_or3_b32 v18, v101, v18, s8
	v_and_b32_e32 v19, 0xffffff80, v19
	s_movk_i32 s8, 0x51
	v_or3_b32 v19, v101, v19, s8
	v_and_b32_e32 v20, 0xffffff80, v20
	s_movk_i32 s8, 0x52
	v_or3_b32 v20, v101, v20, s8
	v_and_b32_e32 v21, 0xffffff80, v21
	s_movk_i32 s8, 0x53
	v_or3_b32 v21, v101, v21, s8
	v_and_b32_e32 v10, 0xffffff80, v10
	s_movk_i32 s8, 0x60
	v_or3_b32 v10, v101, v10, s8
	v_and_b32_e32 v11, 0xffffff80, v11
	s_movk_i32 s8, 0x61
	v_or3_b32 v11, v101, v11, s8
	v_and_b32_e32 v12, 0xffffff80, v12
	s_movk_i32 s8, 0x62
	v_or3_b32 v12, v101, v12, s8
	v_and_b32_e32 v13, 0xffffff80, v13
	s_movk_i32 s8, 0x63
	v_or3_b32 v13, v101, v13, s8
	v_and_b32_e32 v2, 0xffffff80, v2
	s_movk_i32 s8, 0x70
	v_and_b32_e32 v26, 0xffffff80, v26
	v_and_b32_e32 v31, 0xffffff80, v31
	v_or3_b32 v2, v101, v2, s8
	v_and_b32_e32 v3, 0xffffff80, v3
	s_movk_i32 s8, 0x71
	v_or3_b32 v26, v101, v26, 64
	v_or3_b32 v31, v101, v31, 1
	v_and_b32_e32 v32, 0xffffff80, v32
	v_and_b32_e32 v33, 0xffffff80, v33
	v_and_b32_e32 v22, 0xffffff80, v22
	v_and_b32_e32 v23, 0xffffff80, v23
	v_or3_b32 v3, v101, v3, s8
	v_and_b32_e32 v4, 0xffffff80, v4
	s_movk_i32 s8, 0x72
	v_min_f32_e32 v39, v55, v39
	v_min_f32_e32 v55, v71, v87
	v_min_f32_e32 v106, v103, v91
	v_min_f32_e32 v109, v100, v105
	v_max_f32_e32 v71, v71, v87
	v_max_f32_e32 v87, v103, v91
	v_or3_b32 v32, v101, v32, 2
	v_or3_b32 v33, v101, v33, 3
	v_or3_b32 v22, v101, v22, 16
	v_or3_b32 v23, v101, v23, 17
	v_and_b32_e32 v24, 0xffffff80, v24
	v_and_b32_e32 v25, 0xffffff80, v25
	v_and_b32_e32 v14, 0xffffff80, v14
	v_and_b32_e32 v15, 0xffffff80, v15
	v_and_b32_e32 v16, 0xffffff80, v16
	v_and_b32_e32 v17, 0xffffff80, v17
	v_and_b32_e32 v6, 0xffffff80, v6
	v_and_b32_e32 v7, 0xffffff80, v7
	v_and_b32_e32 v8, 0xffffff80, v8
	v_or3_b32 v4, v101, v4, s8
	v_and_b32_e32 v9, 0xffffff80, v9
	v_and_b32_e32 v5, 0xffffff80, v5
	s_movk_i32 s8, 0x73
	v_min_f32_e32 v104, v63, v47
	v_min_f32_e32 v83, v55, v106
	v_min_f32_e32 v47, v109, v110
	v_min_f32_e32 v91, v71, v87
	v_max_f32_e32 v100, v71, v87
	v_max_f32_e32 v87, v55, v106
	v_max_f32_e32 v55, v109, v110
	v_or3_b32 v24, v101, v24, 18
	v_or3_b32 v25, v101, v25, 19
	v_or3_b32 v14, v101, v14, 32
	v_or3_b32 v15, v101, v15, 33
	v_or3_b32 v16, v101, v16, 34
	v_or3_b32 v17, v101, v17, 35
	v_or3_b32 v6, v101, v6, 48
	v_or3_b32 v7, v101, v7, 49
	v_or3_b32 v8, v101, v8, 50
	v_or3_b32 v9, v101, v9, 51
	v_or3_b32 v5, v101, v5, s8
	v_max_f32_e32 v180, v30, v27
	v_min_f32_e32 v27, v30, v27
	v_max_f32_e32 v30, v28, v29
	v_min_f32_e32 v29, v28, v29
	v_max_f32_e32 v28, v180, v30
	v_min_f32_e32 v30, v180, v30
	v_max_f32_e32 v180, v27, v29
	v_min_f32_e32 v29, v27, v29
	v_max_f32_e32 v27, v180, v30
	v_min_f32_e32 v30, v180, v30
	v_max_f32_e32 v180, v18, v19
	v_min_f32_e32 v19, v18, v19
	v_max_f32_e32 v18, v20, v21
	v_min_f32_e32 v21, v20, v21
	v_max_f32_e32 v20, v180, v18
	v_min_f32_e32 v18, v180, v18
	v_max_f32_e32 v180, v19, v21
	v_min_f32_e32 v21, v19, v21
	v_max_f32_e32 v19, v180, v18
	v_min_f32_e32 v18, v180, v18
	v_max_f32_e32 v180, v28, v20
	v_min_f32_e32 v20, v28, v20
	v_max_f32_e32 v28, v30, v18
	v_min_f32_e32 v18, v30, v18
	v_max_f32_e32 v30, v28, v20
	v_min_f32_e32 v20, v28, v20
	v_max_f32_e32 v28, v27, v19
	v_min_f32_e32 v19, v27, v19
	v_max_f32_e32 v27, v29, v21
	v_min_f32_e32 v21, v29, v21
	v_max_f32_e32 v29, v27, v19
	v_min_f32_e32 v19, v27, v19
	v_max_f32_e32 v27, v28, v30
	v_min_f32_e32 v30, v28, v30
	v_max_f32_e32 v28, v29, v20
	v_min_f32_e32 v20, v29, v20
; DEV void ce(float& a, float& b) { float hi = fmaxf(a, b), lo = fminf(a, b); a = hi; b = lo; }
; DEV void sort16_desc(float (&a)[16]) {
; #pragma unroll
;   for (int k = 2; k <= 16; k <<= 1)
; #pragma unroll
;     for (int j = k >> 1; j > 0; j >>= 1)
; #pragma unroll
;       for (int i = 0; i < 16; i++) {
;         const int p = i ^ j;
;         if (p > i) { if ((i & k) == 0) ce(a[i], a[p]); else ce(a[p], a[i]); }
;       }
; }
	v_max_f32_e32 v29, v19, v18
	v_min_f32_e32 v18, v19, v18
	v_max_f32_e32 v19, v10, v11
	v_min_f32_e32 v11, v10, v11
	v_max_f32_e32 v10, v12, v13
	v_min_f32_e32 v13, v12, v13
	v_max_f32_e32 v12, v19, v10
	v_min_f32_e32 v10, v19, v10
	v_max_f32_e32 v19, v11, v13
	v_min_f32_e32 v13, v11, v13
	v_max_f32_e32 v11, v19, v10
	v_min_f32_e32 v10, v19, v10
	v_max_f32_e32 v19, v2, v26
	v_min_f32_e32 v26, v2, v26
	v_max_f32_e32 v2, v31, v3
	v_min_f32_e32 v3, v31, v3
	v_max_f32_e32 v31, v19, v2
	v_min_f32_e32 v2, v19, v2
	v_max_f32_e32 v19, v26, v3
	v_min_f32_e32 v3, v26, v3
	v_max_f32_e32 v26, v19, v2
	v_min_f32_e32 v2, v19, v2
	v_max_f32_e32 v19, v12, v31
	v_min_f32_e32 v31, v12, v31
	v_max_f32_e32 v12, v10, v2
	v_min_f32_e32 v2, v10, v2
	v_max_f32_e32 v10, v12, v31
	v_min_f32_e32 v31, v12, v31
	v_max_f32_e32 v12, v11, v26
	v_min_f32_e32 v26, v11, v26
	v_max_f32_e32 v11, v13, v3
	v_min_f32_e32 v3, v13, v3
	v_max_f32_e32 v13, v11, v26
	v_min_f32_e32 v26, v11, v26
	v_max_f32_e32 v11, v12, v10
	v_min_f32_e32 v10, v12, v10
	v_max_f32_e32 v12, v13, v31
	v_min_f32_e32 v31, v13, v31
	v_max_f32_e32 v13, v26, v2
	v_min_f32_e32 v2, v26, v2
	v_max_f32_e32 v26, v180, v19
	v_min_f32_e32 v19, v180, v19
	v_max_f32_e32 v180, v20, v31
	v_min_f32_e32 v31, v20, v31
	v_max_f32_e32 v20, v180, v19
	v_min_f32_e32 v19, v180, v19
	v_max_f32_e32 v180, v30, v10
	v_min_f32_e32 v10, v30, v10
	v_max_f32_e32 v30, v18, v2
	v_min_f32_e32 v2, v18, v2
	v_max_f32_e32 v18, v30, v10
	v_min_f32_e32 v10, v30, v10
	v_max_f32_e32 v30, v180, v20
	v_min_f32_e32 v20, v180, v20
	v_max_f32_e32 v180, v18, v19
	v_min_f32_e32 v19, v18, v19
	v_max_f32_e32 v18, v10, v31
	v_min_f32_e32 v31, v10, v31
	v_max_f32_e32 v10, v27, v11
	v_min_f32_e32 v11, v27, v11
	v_max_f32_e32 v27, v29, v13
	v_min_f32_e32 v13, v29, v13
	v_max_f32_e32 v29, v27, v11
	v_min_f32_e32 v11, v27, v11
	v_max_f32_e32 v27, v28, v12
	v_min_f32_e32 v12, v28, v12
	v_max_f32_e32 v28, v21, v3
	v_min_f32_e32 v3, v21, v3
	v_max_f32_e32 v21, v28, v12
	v_min_f32_e32 v12, v28, v12
	v_max_f32_e32 v28, v27, v29
	v_min_f32_e32 v29, v27, v29
	v_max_f32_e32 v27, v21, v11
	v_min_f32_e32 v11, v21, v11
	v_max_f32_e32 v21, v12, v13
	v_min_f32_e32 v13, v12, v13
	v_max_f32_e32 v12, v10, v30
	v_min_f32_e32 v30, v10, v30
	v_max_f32_e32 v10, v28, v20
	v_min_f32_e32 v20, v28, v20
	v_max_f32_e32 v28, v29, v180
	v_min_f32_e32 v180, v29, v180
	v_max_f32_e32 v29, v27, v19
	v_min_f32_e32 v19, v27, v19
	v_max_f32_e32 v27, v11, v18
	v_min_f32_e32 v18, v11, v18
	v_max_f32_e32 v11, v21, v31
	v_min_f32_e32 v31, v21, v31
	v_max_f32_e32 v21, v13, v2
	v_min_f32_e32 v2, v13, v2
	v_max_f32_e32 v13, v32, v33
	v_min_f32_e32 v33, v32, v33
	v_max_f32_e32 v32, v22, v23
	v_min_f32_e32 v23, v22, v23
	v_max_f32_e32 v22, v13, v32
	v_min_f32_e32 v32, v13, v32
	v_max_f32_e32 v13, v33, v23
	v_min_f32_e32 v23, v33, v23
	v_max_f32_e32 v33, v13, v32
	v_min_f32_e32 v32, v13, v32
	v_max_f32_e32 v13, v4, v24
	v_min_f32_e32 v24, v4, v24
	v_max_f32_e32 v4, v25, v14
	v_min_f32_e32 v14, v25, v14
	v_max_f32_e32 v25, v13, v4
	v_min_f32_e32 v4, v13, v4
	v_max_f32_e32 v13, v24, v14
	v_min_f32_e32 v14, v24, v14
	v_max_f32_e32 v24, v13, v4
	v_min_f32_e32 v4, v13, v4
	v_max_f32_e32 v13, v22, v25
	v_min_f32_e32 v25, v22, v25
	v_max_f32_e32 v22, v32, v4
	v_min_f32_e32 v4, v32, v4
	v_max_f32_e32 v32, v22, v25
	v_min_f32_e32 v25, v22, v25
	v_max_f32_e32 v22, v33, v24
	v_min_f32_e32 v24, v33, v24
	v_max_f32_e32 v33, v23, v14
	v_min_f32_e32 v14, v23, v14
	v_max_f32_e32 v23, v33, v24
	v_min_f32_e32 v24, v33, v24
	v_max_f32_e32 v33, v22, v32
	v_min_f32_e32 v32, v22, v32
	v_max_f32_e32 v22, v23, v25
	v_min_f32_e32 v25, v23, v25
	v_max_f32_e32 v23, v24, v4
	v_min_f32_e32 v4, v24, v4
	v_max_f32_e32 v24, v15, v16
	v_min_f32_e32 v16, v15, v16
	v_max_f32_e32 v15, v17, v6
	v_min_f32_e32 v6, v17, v6
	v_max_f32_e32 v17, v24, v15
	v_min_f32_e32 v15, v24, v15
	v_max_f32_e32 v24, v16, v6
	v_min_f32_e32 v6, v16, v6
	v_max_f32_e32 v16, v24, v15
	v_min_f32_e32 v15, v24, v15
	v_max_f32_e32 v24, v7, v8
	v_min_f32_e32 v8, v7, v8
	v_max_f32_e32 v7, v9, v5
	v_min_f32_e32 v5, v9, v5
	v_max_f32_e32 v9, v24, v7
	v_min_f32_e32 v7, v24, v7
	v_max_f32_e32 v24, v8, v5
	v_min_f32_e32 v5, v8, v5
	v_max_f32_e32 v8, v24, v7
	v_min_f32_e32 v7, v24, v7
	v_max_f32_e32 v24, v17, v9
	v_min_f32_e32 v9, v17, v9
	v_max_f32_e32 v17, v15, v7
	v_min_f32_e32 v7, v15, v7
	v_max_f32_e32 v15, v17, v9
	v_min_f32_e32 v9, v17, v9
	v_max_f32_e32 v17, v16, v8
	v_min_f32_e32 v8, v16, v8
	v_max_f32_e32 v16, v6, v5
	v_min_f32_e32 v5, v6, v5
	v_max_f32_e32 v6, v16, v8
	v_min_f32_e32 v8, v16, v8
	v_max_f32_e32 v16, v17, v15
	v_min_f32_e32 v15, v17, v15
	v_max_f32_e32 v17, v6, v9
	v_min_f32_e32 v9, v6, v9
	v_max_f32_e32 v6, v8, v7
	v_min_f32_e32 v7, v8, v7
	v_max_f32_e32 v8, v13, v24
	v_min_f32_e32 v24, v13, v24
	v_max_f32_e32 v13, v25, v9
	v_min_f32_e32 v9, v25, v9
	v_max_f32_e32 v25, v13, v24
	v_min_f32_e32 v24, v13, v24
	v_max_f32_e32 v13, v32, v15
	v_min_f32_e32 v15, v32, v15
	v_max_f32_e32 v32, v4, v7
	v_min_f32_e32 v7, v4, v7
	v_max_f32_e32 v4, v32, v15
	v_min_f32_e32 v15, v32, v15
	v_max_f32_e32 v32, v13, v25
	v_min_f32_e32 v25, v13, v25
	v_max_f32_e32 v13, v4, v24
	v_min_f32_e32 v24, v4, v24
	v_max_f32_e32 v4, v15, v9
	v_min_f32_e32 v9, v15, v9
	v_max_f32_e32 v15, v33, v16
	v_min_f32_e32 v16, v33, v16
	v_max_f32_e32 v33, v23, v6
	v_min_f32_e32 v6, v23, v6
	v_max_f32_e32 v23, v33, v16
	v_min_f32_e32 v16, v33, v16
	v_max_f32_e32 v33, v22, v17
	v_min_f32_e32 v17, v22, v17
	v_max_f32_e32 v22, v14, v5
	v_min_f32_e32 v5, v14, v5
	v_max_f32_e32 v14, v22, v17
	v_min_f32_e32 v17, v22, v17
	v_max_f32_e32 v22, v33, v23
	v_min_f32_e32 v23, v33, v23
	v_max_f32_e32 v33, v14, v16
; DEV void merge_xor(float (&l)[16], int mask) {
;   float t[16];
; #pragma unroll
;   for (int i = 0; i < 16; i++) t[i] = __shfl_xor(l[15 - i], mask);
; #pragma unroll
;   for (int i = 0; i < 16; i++) l[i] = fmaxf(l[i], t[i]);
;   bitonic16(l);
; DEV void peer_top16(const bf16_t* __restrict__ pq, const bf16_t* sk  , float (&l)[16]) {
;     ...
;   sort16_desc(l);
;   sort16_desc(hi);
; #pragma unroll
;   for (int i = 0; i < 16; i++) l[i] = fmaxf(l[i], hi[15 - i]);
;   bitonic16(l);
;   merge_xor(l, 16);
;   merge_xor(l, 32);
	v_min_f32_e32 v16, v14, v16
	v_max_f32_e32 v14, v17, v6
	v_min_f32_e32 v6, v17, v6
	v_max_f32_e32 v17, v15, v32
	v_min_f32_e32 v32, v15, v32
	v_max_f32_e32 v15, v22, v25
	v_min_f32_e32 v25, v22, v25
	v_max_f32_e32 v22, v23, v13
	v_min_f32_e32 v13, v23, v13
	v_max_f32_e32 v23, v33, v24
	v_min_f32_e32 v24, v33, v24
	v_max_f32_e32 v33, v16, v4
	v_min_f32_e32 v4, v16, v4
	v_max_f32_e32 v16, v14, v9
	v_min_f32_e32 v9, v14, v9
	v_max_f32_e32 v14, v6, v7
	v_min_f32_e32 v7, v6, v7
	v_max_f32_e32 v26, v26, v5
	v_max_f32_e32 v12, v12, v7
	v_max_f32_e32 v30, v30, v14
	v_max_f32_e32 v10, v10, v9
	v_max_f32_e32 v20, v20, v16
	v_max_f32_e32 v28, v28, v4
	v_max_f32_e32 v180, v180, v33
	v_max_f32_e32 v29, v29, v24
	v_max_f32_e32 v19, v19, v23
	v_max_f32_e32 v27, v27, v13
	v_max_f32_e32 v18, v18, v22
	v_max_f32_e32 v11, v11, v25
	v_max_f32_e32 v31, v31, v15
	v_max_f32_e32 v21, v21, v32
	v_max_f32_e32 v2, v2, v17
	v_max_f32_e32 v3, v3, v8
	v_max_f32_e32 v6, v26, v19
	v_min_f32_e32 v19, v26, v19
	v_max_f32_e32 v26, v12, v27
	v_min_f32_e32 v27, v12, v27
	v_max_f32_e32 v12, v30, v18
	v_min_f32_e32 v18, v30, v18
	v_max_f32_e32 v30, v10, v11
	v_min_f32_e32 v11, v10, v11
	v_max_f32_e32 v10, v20, v31
	v_min_f32_e32 v31, v20, v31
	v_max_f32_e32 v20, v28, v21
	v_min_f32_e32 v21, v28, v21
	v_max_f32_e32 v28, v180, v2
	v_min_f32_e32 v2, v180, v2
	v_max_f32_e32 v180, v29, v3
	v_min_f32_e32 v3, v29, v3
	v_max_f32_e32 v29, v6, v10
	v_min_f32_e32 v10, v6, v10
	v_max_f32_e32 v6, v26, v20
	v_min_f32_e32 v20, v26, v20
	v_max_f32_e32 v26, v12, v28
	v_min_f32_e32 v28, v12, v28
	v_max_f32_e32 v12, v30, v180
	v_min_f32_e32 v180, v30, v180
	v_max_f32_e32 v30, v19, v31
	v_min_f32_e32 v31, v19, v31
	v_max_f32_e32 v19, v27, v21
	v_min_f32_e32 v21, v27, v21
	v_max_f32_e32 v27, v18, v2
	v_min_f32_e32 v2, v18, v2
	v_max_f32_e32 v18, v11, v3
	v_min_f32_e32 v3, v11, v3
	v_max_f32_e32 v11, v29, v26
	v_min_f32_e32 v26, v29, v26
	v_max_f32_e32 v29, v6, v12
	v_min_f32_e32 v12, v6, v12
	v_max_f32_e32 v6, v10, v28
	v_min_f32_e32 v28, v10, v28
	v_max_f32_e32 v10, v20, v180
	v_min_f32_e32 v180, v20, v180
	v_max_f32_e32 v20, v30, v27
	v_min_f32_e32 v27, v30, v27
	v_max_f32_e32 v30, v19, v18
	v_min_f32_e32 v18, v19, v18
	v_max_f32_e32 v19, v31, v2
	v_min_f32_e32 v2, v31, v2
	v_max_f32_e32 v31, v21, v3
	v_min_f32_e32 v3, v21, v3
	v_max_f32_e32 v164, v11, v29
	v_min_f32_e32 v165, v11, v29
	v_max_f32_e32 v166, v26, v12
	v_min_f32_e32 v167, v26, v12
	v_max_f32_e32 v168, v6, v10
	v_min_f32_e32 v169, v6, v10
	v_max_f32_e32 v170, v28, v180
	v_min_f32_e32 v171, v28, v180
	v_max_f32_e32 v172, v20, v30
	v_min_f32_e32 v173, v20, v30
	v_max_f32_e32 v174, v27, v18
	v_min_f32_e32 v175, v27, v18
	v_max_f32_e32 v176, v19, v31
	v_min_f32_e32 v177, v19, v31
	v_max_f32_e32 v178, v2, v3
	v_min_f32_e32 v179, v2, v3
	v_max_f32_e32 v111, v0, v43
	v_min_f32_e32 v112, v104, v39
	v_max_f32_e32 v103, v104, v39
	v_min_f32_e32 v0, v0, v43
	v_min_f32_e32 v63, v107, v108
	v_min_f32_e32 v39, v111, v103
	v_max_f32_e32 v71, v107, v108
	v_max_f32_e32 v51, v111, v103
	v_max_f32_e32 v43, v0, v112
	v_min_f32_e32 v0, v0, v112
	ds_bpermute_b32 v3, v95, v179
	ds_bpermute_b32 v19, v95, v178
	ds_bpermute_b32 v20, v95, v177
	ds_bpermute_b32 v21, v95, v176
	ds_bpermute_b32 v22, v95, v175
	ds_bpermute_b32 v23, v95, v174
	s_waitcnt lgkmcnt(5)
	ds_bpermute_b32 v24, v95, v173
	ds_bpermute_b32 v33, v95, v164
	v_max_f32_e32 v3, v164, v3
	s_waitcnt lgkmcnt(6)
	ds_bpermute_b32 v25, v95, v172
	ds_bpermute_b32 v32, v95, v165
	v_max_f32_e32 v4, v165, v19
	s_waitcnt lgkmcnt(7)
	ds_bpermute_b32 v26, v95, v171
	ds_bpermute_b32 v31, v95, v166
	v_max_f32_e32 v9, v166, v20
	s_waitcnt lgkmcnt(8)
	ds_bpermute_b32 v27, v95, v170
	ds_bpermute_b32 v30, v95, v167
	v_max_f32_e32 v13, v167, v21
	s_waitcnt lgkmcnt(9)
	ds_bpermute_b32 v28, v95, v169
	ds_bpermute_b32 v29, v95, v168
	v_max_f32_e32 v15, v168, v22
	s_waitcnt lgkmcnt(10)
	v_max_f32_e32 v10, v169, v23
	s_waitcnt lgkmcnt(9)
	v_max_f32_e32 v17, v170, v24
	s_waitcnt lgkmcnt(7)
	v_max_f32_e32 v6, v171, v25
	s_waitcnt lgkmcnt(5)
	v_max_f32_e32 v8, v172, v26
	s_waitcnt lgkmcnt(3)
	v_max_f32_e32 v14, v173, v27
	s_waitcnt lgkmcnt(1)
	v_max_f32_e32 v16, v174, v28
	s_waitcnt lgkmcnt(0)
	v_max_f32_e32 v5, v175, v29
	v_max_f32_e32 v12, v176, v30
	v_max_f32_e32 v7, v177, v31
	v_max_f32_e32 v11, v178, v32
	v_max_f32_e32 v2, v179, v33
	v_max_f32_e32 v18, v3, v8
	v_min_f32_e32 v3, v3, v8
	v_max_f32_e32 v8, v4, v14
	v_min_f32_e32 v4, v4, v14
	v_max_f32_e32 v14, v9, v16
	v_min_f32_e32 v9, v9, v16
	v_max_f32_e32 v16, v13, v5
	v_min_f32_e32 v5, v13, v5
	v_max_f32_e32 v13, v15, v12
	v_min_f32_e32 v12, v15, v12
	v_max_f32_e32 v15, v10, v7
	v_min_f32_e32 v7, v10, v7
	v_max_f32_e32 v10, v17, v11
	v_min_f32_e32 v11, v17, v11
	v_max_f32_e32 v17, v6, v2
	v_min_f32_e32 v2, v6, v2
	v_max_f32_e32 v6, v18, v13
	v_min_f32_e32 v13, v18, v13
	v_max_f32_e32 v18, v8, v15
	v_min_f32_e32 v8, v8, v15
	v_max_f32_e32 v15, v14, v10
	v_min_f32_e32 v10, v14, v10
	v_max_f32_e32 v14, v16, v17
	v_min_f32_e32 v16, v16, v17
	v_max_f32_e32 v17, v3, v12
	v_min_f32_e32 v3, v3, v12
	v_max_f32_e32 v12, v4, v7
	v_min_f32_e32 v4, v4, v7
	v_max_f32_e32 v7, v9, v11
	v_min_f32_e32 v9, v9, v11
	v_max_f32_e32 v11, v5, v2
	v_min_f32_e32 v2, v5, v2
	v_max_f32_e32 v5, v6, v15
	v_min_f32_e32 v6, v6, v15
	v_max_f32_e32 v15, v18, v14
	v_min_f32_e32 v14, v18, v14
	v_max_f32_e32 v18, v13, v10
	v_min_f32_e32 v10, v13, v10
	v_max_f32_e32 v13, v8, v16
	v_min_f32_e32 v8, v8, v16
	v_max_f32_e32 v16, v17, v7
	v_min_f32_e32 v7, v17, v7
	v_max_f32_e32 v17, v12, v11
	v_min_f32_e32 v11, v12, v11
	v_max_f32_e32 v12, v3, v9
	v_min_f32_e32 v3, v3, v9
	v_max_f32_e32 v9, v4, v2
	v_min_f32_e32 v2, v4, v2
	v_max_f32_e32 v4, v5, v15
	v_min_f32_e32 v5, v5, v15
	v_max_f32_e32 v15, v6, v14
	v_min_f32_e32 v6, v6, v14
	v_max_f32_e32 v14, v18, v13
	v_min_f32_e32 v13, v18, v13
	v_max_f32_e32 v18, v10, v8
	v_min_f32_e32 v8, v10, v8
	v_max_f32_e32 v10, v16, v17
	v_min_f32_e32 v16, v16, v17
	v_max_f32_e32 v17, v7, v11
	v_min_f32_e32 v7, v7, v11
	v_max_f32_e32 v11, v12, v9
	v_min_f32_e32 v9, v12, v9
	v_max_f32_e32 v12, v3, v2
	v_min_f32_e32 v2, v3, v2
	ds_bpermute_b32 v3, v99, v2
	ds_bpermute_b32 v19, v99, v12
	ds_bpermute_b32 v20, v99, v9
	ds_bpermute_b32 v21, v99, v11
	ds_bpermute_b32 v22, v99, v7
	ds_bpermute_b32 v23, v99, v17
	s_waitcnt lgkmcnt(5)
; DEV void merge_xor(float (&l)[16], int mask) {
;   float t[16];
; #pragma unroll
;   for (int i = 0; i < 16; i++) t[i] = __shfl_xor(l[15 - i], mask);
; #pragma unroll
;   for (int i = 0; i < 16; i++) l[i] = fmaxf(l[i], t[i]);
;   bitonic16(l);
; DEV void phase_peer_score(const Params& p, int layer, int M, char* smem) {
;     ...
;     unsigned char* tab = (unsigned char*)smem + 73728 + (w * 16 + l15) * 32;
; #pragma unroll
;     for (int i = 0; i < 16; i++) { tab[i] = (unsigned char)(__float_as_uint(L0[i]) & 127u); tab[16 + i] = (unsigned char)(__float_as_uint(L1[i]) & 127u); }
	ds_bpermute_b32 v24, v99, v16
	ds_bpermute_b32 v33, v99, v4
	v_max_f32_e32 v3, v4, v3
	s_waitcnt lgkmcnt(6)
	ds_bpermute_b32 v25, v99, v10
	ds_bpermute_b32 v32, v99, v5
	v_max_f32_e32 v4, v5, v19
	s_waitcnt lgkmcnt(7)
	ds_bpermute_b32 v26, v99, v8
	ds_bpermute_b32 v31, v99, v15
	v_max_f32_e32 v5, v15, v20
	s_waitcnt lgkmcnt(8)
	ds_bpermute_b32 v27, v99, v18
	ds_bpermute_b32 v30, v99, v6
	v_max_f32_e32 v6, v6, v21
	s_waitcnt lgkmcnt(9)
	ds_bpermute_b32 v28, v99, v13
	ds_bpermute_b32 v29, v99, v14
	v_max_f32_e32 v14, v14, v22
	s_waitcnt lgkmcnt(10)
	v_max_f32_e32 v13, v13, v23
	s_waitcnt lgkmcnt(9)
	v_max_f32_e32 v15, v18, v24
	s_waitcnt lgkmcnt(7)
	v_max_f32_e32 v8, v8, v25
	s_waitcnt lgkmcnt(5)
	v_max_f32_e32 v10, v10, v26
	s_waitcnt lgkmcnt(3)
	v_max_f32_e32 v16, v16, v27
	s_waitcnt lgkmcnt(1)
	v_max_f32_e32 v17, v17, v28
	s_waitcnt lgkmcnt(0)
	v_max_f32_e32 v7, v7, v29
	v_max_f32_e32 v11, v11, v30
	v_max_f32_e32 v9, v9, v31
	v_max_f32_e32 v12, v12, v32
	v_max_f32_e32 v2, v2, v33
	v_max_f32_e32 v18, v3, v10
	v_min_f32_e32 v3, v3, v10
	v_max_f32_e32 v10, v4, v16
	v_min_f32_e32 v4, v4, v16
	v_max_f32_e32 v16, v5, v17
	v_min_f32_e32 v5, v5, v17
	v_max_f32_e32 v17, v6, v7
	v_min_f32_e32 v6, v6, v7
	v_max_f32_e32 v7, v14, v11
	v_min_f32_e32 v11, v14, v11
	v_max_f32_e32 v14, v13, v9
	v_min_f32_e32 v9, v13, v9
	v_max_f32_e32 v13, v15, v12
	v_min_f32_e32 v12, v15, v12
	v_max_f32_e32 v15, v8, v2
	v_min_f32_e32 v2, v8, v2
	v_max_f32_e32 v8, v18, v7
	v_min_f32_e32 v7, v18, v7
	v_max_f32_e32 v18, v10, v14
	v_min_f32_e32 v10, v10, v14
	v_max_f32_e32 v14, v16, v13
	v_min_f32_e32 v13, v16, v13
	v_max_f32_e32 v16, v17, v15
	v_min_f32_e32 v15, v17, v15
	v_max_f32_e32 v17, v3, v11
	v_min_f32_e32 v3, v3, v11
	v_max_f32_e32 v11, v4, v9
	v_min_f32_e32 v4, v4, v9
	v_max_f32_e32 v9, v5, v12
	v_min_f32_e32 v5, v5, v12
	v_max_f32_e32 v12, v6, v2
	v_min_f32_e32 v2, v6, v2
	v_max_f32_e32 v6, v8, v14
	v_min_f32_e32 v8, v8, v14
	v_max_f32_e32 v14, v18, v16
	v_min_f32_e32 v16, v18, v16
	v_max_f32_e32 v18, v7, v13
	v_max_f32_e32 v19, v10, v15
	s_movk_i32 s8, 0x7f
	v_min_f32_e32 v13, v7, v13
	v_min_f32_e32 v10, v10, v15
	v_max_f32_e32 v15, v17, v9
	v_min_f32_e32 v21, v17, v9
	v_max_f32_e32 v17, v11, v12
	v_min_f32_e32 v22, v11, v12
	v_max_f32_e32 v23, v3, v5
	v_min_f32_e32 v3, v3, v5
	v_max_f32_e32 v5, v4, v2
	v_min_f32_e32 v24, v4, v2
	v_max_f32_e32 v9, v18, v19
	v_min_f32_e32 v12, v18, v19
	v_and_b32_sdwa v18, v63, s8 dst_sel:BYTE_1 dst_unused:UNUSED_PAD src0_sel:DWORD src1_sel:DWORD
	v_max_f32_e32 v2, v6, v14
	v_min_f32_e32 v4, v6, v14
	v_max_f32_e32 v11, v13, v10
	v_min_f32_e32 v10, v13, v10
	v_max_f32_e32 v14, v23, v5
	v_min_f32_e32 v13, v23, v5
	v_max_f32_e32 v6, v3, v24
	v_min_f32_e32 v5, v3, v24
	v_and_b32_sdwa v3, v75, s8 dst_sel:BYTE_1 dst_unused:UNUSED_PAD src0_sel:DWORD src1_sel:DWORD
	v_bitop3_b16 v18, v71, v18, s8 bitop3:0xec
	v_bitop3_b16 v3, v79, v3, s8 bitop3:0xec
	v_lshlrev_b32_e32 v18, 16, v18
	v_or_b32_sdwa v23, v3, v18 dst_sel:DWORD dst_unused:UNUSED_PAD src0_sel:WORD_0 src1_sel:DWORD
	v_and_b32_sdwa v18, v83, s8 dst_sel:BYTE_1 dst_unused:UNUSED_PAD src0_sel:DWORD src1_sel:DWORD
	v_and_b32_sdwa v3, v91, s8 dst_sel:BYTE_1 dst_unused:UNUSED_PAD src0_sel:DWORD src1_sel:DWORD
	v_bitop3_b16 v18, v87, v18, s8 bitop3:0xec
	v_bitop3_b16 v3, v100, v3, s8 bitop3:0xec
	v_lshlrev_b32_e32 v18, 16, v18
	v_max_f32_e32 v7, v8, v16
	v_min_f32_e32 v8, v8, v16
	v_max_f32_e32 v20, v15, v17
	v_min_f32_e32 v17, v15, v17
	v_max_f32_e32 v16, v21, v22
	v_min_f32_e32 v15, v21, v22
	v_or_b32_sdwa v22, v3, v18 dst_sel:DWORD dst_unused:UNUSED_PAD src0_sel:WORD_0 src1_sel:DWORD
	v_and_b32_sdwa v18, v10, s8 dst_sel:BYTE_1 dst_unused:UNUSED_PAD src0_sel:DWORD src1_sel:DWORD
	v_and_b32_sdwa v3, v12, s8 dst_sel:BYTE_1 dst_unused:UNUSED_PAD src0_sel:DWORD src1_sel:DWORD
	v_bitop3_b16 v18, v11, v18, s8 bitop3:0xec
	v_bitop3_b16 v3, v9, v3, s8 bitop3:0xec
	v_lshlrev_b32_e32 v18, 16, v18
	v_or_b32_sdwa v27, v3, v18 dst_sel:DWORD dst_unused:UNUSED_PAD src0_sel:WORD_0 src1_sel:DWORD
	v_and_b32_sdwa v18, v8, s8 dst_sel:BYTE_1 dst_unused:UNUSED_PAD src0_sel:DWORD src1_sel:DWORD
	v_and_b32_sdwa v3, v4, s8 dst_sel:BYTE_1 dst_unused:UNUSED_PAD src0_sel:DWORD src1_sel:DWORD
	v_bitop3_b16 v18, v7, v18, s8 bitop3:0xec
	v_bitop3_b16 v3, v2, v3, s8 bitop3:0xec
	v_lshlrev_b32_e32 v18, 16, v18
	v_or_b32_sdwa v26, v3, v18 dst_sel:DWORD dst_unused:UNUSED_PAD src0_sel:WORD_0 src1_sel:DWORD
	v_and_b32_sdwa v18, v0, s8 dst_sel:BYTE_1 dst_unused:UNUSED_PAD src0_sel:DWORD src1_sel:DWORD
	v_and_b32_sdwa v3, v39, s8 dst_sel:BYTE_1 dst_unused:UNUSED_PAD src0_sel:DWORD src1_sel:DWORD
	v_bitop3_b16 v18, v43, v18, s8 bitop3:0xec
	v_bitop3_b16 v3, v51, v3, s8 bitop3:0xec
	v_lshlrev_b32_e32 v18, 16, v18
	v_or_b32_sdwa v25, v3, v18 dst_sel:DWORD dst_unused:UNUSED_PAD src0_sel:WORD_0 src1_sel:DWORD
	v_and_b32_sdwa v18, v47, s8 dst_sel:BYTE_1 dst_unused:UNUSED_PAD src0_sel:DWORD src1_sel:DWORD
	v_and_b32_sdwa v3, v59, s8 dst_sel:BYTE_1 dst_unused:UNUSED_PAD src0_sel:DWORD src1_sel:DWORD
	v_bitop3_b16 v18, v55, v18, s8 bitop3:0xec
	v_bitop3_b16 v3, v67, v3, s8 bitop3:0xec
	v_lshlrev_b32_e32 v18, 16, v18
	v_or_b32_sdwa v24, v3, v18 dst_sel:DWORD dst_unused:UNUSED_PAD src0_sel:WORD_0 src1_sel:DWORD
	v_and_b32_sdwa v18, v5, s8 dst_sel:BYTE_1 dst_unused:UNUSED_PAD src0_sel:DWORD src1_sel:DWORD
	v_and_b32_sdwa v3, v13, s8 dst_sel:BYTE_1 dst_unused:UNUSED_PAD src0_sel:DWORD src1_sel:DWORD
	v_bitop3_b16 v18, v6, v18, s8 bitop3:0xec
	v_bitop3_b16 v3, v14, v3, s8 bitop3:0xec
	v_lshlrev_b32_e32 v18, 16, v18
	v_or_b32_sdwa v29, v3, v18 dst_sel:DWORD dst_unused:UNUSED_PAD src0_sel:WORD_0 src1_sel:DWORD
	v_and_b32_sdwa v18, v15, s8 dst_sel:BYTE_1 dst_unused:UNUSED_PAD src0_sel:DWORD src1_sel:DWORD
	v_and_b32_sdwa v3, v17, s8 dst_sel:BYTE_1 dst_unused:UNUSED_PAD src0_sel:DWORD src1_sel:DWORD
	v_bitop3_b16 v18, v16, v18, s8 bitop3:0xec
	v_bitop3_b16 v3, v20, v3, s8 bitop3:0xec
	v_lshlrev_b32_e32 v18, 16, v18
	v_or_b32_sdwa v28, v3, v18 dst_sel:DWORD dst_unused:UNUSED_PAD src0_sel:WORD_0 src1_sel:DWORD
	ds_write_b128 v138, v[22:25]
	ds_write_b128 v138, v[26:29] offset:16
	s_and_saveexec_b64 s[8:9], s[38:39]
	s_cbranch_execz .LBB0_627
; DEV void ce(float& a, float& b) { float hi = fmaxf(a, b), lo = fminf(a, b); a = hi; b = lo; }
; DEV void phase_peer_score(const Params& p, int layer, int M, char* smem) {
;     ...
; #pragma unroll
;     for (int i = 0; i < 16; i++) R[i] = -3.0e38f;
; #pragma unroll
;     for (int i = 0; i < 16; i++)
; #pragma unroll
;       for (int j = 0; j < 16; j++)
;         if ((i + 1) * (j + 1) <= 16) {
;           float v = L0[i] + L1[j];
;           v = __uint_as_float((__float_as_uint(v) & ~255u) | (unsigned)(i * 16 + j));
; #pragma unroll
;           for (int t = 0; t < 16; t++)
;             if (t >= (i + 1) * (j + 1) - 1) ce(R[t], v);
;         }
	s_movk_i32 s18, 0xff00
	v_add_f32_e32 v164, v100, v2
	v_and_or_b32 v164, v164, s18, 0
	v_max_f32_e32 v148, 0xff61b1e6, v164
	v_add_f32_e32 v164, v100, v4
	v_and_or_b32 v164, v164, s18, 1
	v_max_f32_e32 v149, 0xff61b1e6, v164
	v_add_f32_e32 v164, v100, v7
	v_and_or_b32 v164, v164, s18, 2
	v_max_f32_e32 v150, 0xff61b1e6, v164
	v_add_f32_e32 v164, v100, v8
	v_and_or_b32 v164, v164, s18, 3
	v_max_f32_e32 v151, 0xff61b1e6, v164
	v_add_f32_e32 v164, v100, v9
	v_and_or_b32 v164, v164, s18, 4
	v_max_f32_e32 v152, 0xff61b1e6, v164
	v_add_f32_e32 v164, v100, v12
	v_and_or_b32 v164, v164, s18, 5
	v_max_f32_e32 v153, 0xff61b1e6, v164
	v_add_f32_e32 v164, v100, v11
	v_and_or_b32 v164, v164, s18, 6
	v_max_f32_e32 v154, 0xff61b1e6, v164
	v_add_f32_e32 v164, v100, v10
	v_and_or_b32 v164, v164, s18, 7
	v_max_f32_e32 v155, 0xff61b1e6, v164
	v_add_f32_e32 v164, v100, v20
	v_and_or_b32 v164, v164, s18, 8
	v_max_f32_e32 v156, 0xff61b1e6, v164
	v_add_f32_e32 v164, v100, v17
	v_and_or_b32 v164, v164, s18, 9
	v_max_f32_e32 v157, 0xff61b1e6, v164
	v_add_f32_e32 v164, v100, v16
	v_and_or_b32 v164, v164, s18, 10
	v_max_f32_e32 v158, 0xff61b1e6, v164
	v_add_f32_e32 v164, v100, v15
	v_and_or_b32 v164, v164, s18, 11
	v_max_f32_e32 v159, 0xff61b1e6, v164
	v_add_f32_e32 v164, v100, v14
	v_and_or_b32 v164, v164, s18, 12
	v_max_f32_e32 v160, 0xff61b1e6, v164
	v_add_f32_e32 v164, v100, v13
	v_and_or_b32 v164, v164, s18, 13
	v_max_f32_e32 v161, 0xff61b1e6, v164
	v_add_f32_e32 v164, v100, v6
	v_and_or_b32 v164, v164, s18, 14
	v_max_f32_e32 v162, 0xff61b1e6, v164
	v_add_f32_e32 v164, v100, v5
	v_and_or_b32 v164, v164, s18, 15
	v_max_f32_e32 v163, 0xff61b1e6, v164
	v_min_f32_e32 v164, v148, v149
	v_max_f32_e32 v148, v148, v149
	v_min_f32_e32 v149, v164, v150
	v_max_f32_e32 v164, v164, v150
	v_min_f32_e32 v150, v149, v151
	v_max_f32_e32 v149, v149, v151
	v_min_f32_e32 v151, v150, v152
	v_max_f32_e32 v150, v150, v152
	v_min_f32_e32 v152, v151, v153
	v_max_f32_e32 v151, v151, v153
	v_min_f32_e32 v153, v152, v154
	v_max_f32_e32 v152, v152, v154
	v_min_f32_e32 v154, v153, v155
	v_max_f32_e32 v153, v153, v155
	v_min_f32_e32 v155, v154, v156
	v_max_f32_e32 v154, v154, v156
	v_min_f32_e32 v156, v155, v157
	v_max_f32_e32 v155, v155, v157
	v_min_f32_e32 v157, v156, v158
	v_max_f32_e32 v156, v156, v158
	v_min_f32_e32 v158, v157, v159
	v_max_f32_e32 v157, v157, v159
	v_min_f32_e32 v159, v158, v160
	v_max_f32_e32 v158, v158, v160
	v_min_f32_e32 v160, v159, v161
	v_max_f32_e32 v159, v159, v161
	v_min_f32_e32 v161, v160, v162
	v_max_f32_e32 v160, v160, v162
	v_min_f32_e32 v162, v161, v163
	v_max_f32_e32 v161, v161, v163
	v_add_f32_e32 v163, v91, v2
	v_and_or_b32 v163, v163, s18, 16
	v_med3_f32 v162, v161, v162, v163
	v_med3_f32 v161, v160, v161, v163
	v_med3_f32 v160, v159, v160, v163
	v_med3_f32 v159, v158, v159, v163
	v_med3_f32 v158, v157, v158, v163
	v_med3_f32 v157, v156, v157, v163
	v_med3_f32 v156, v155, v156, v163
	v_med3_f32 v155, v154, v155, v163
	v_med3_f32 v154, v153, v154, v163
	v_med3_f32 v153, v152, v153, v163
	v_med3_f32 v152, v151, v152, v163
	v_med3_f32 v151, v150, v151, v163
	v_med3_f32 v150, v149, v150, v163
	v_med3_f32 v149, v164, v149, v163
	v_med3_f32 v164, v148, v164, v163
	v_max_f32_e32 v148, v148, v163
	v_add_f32_e32 v163, v91, v4
	v_and_or_b32 v163, v163, s18, 17
	v_med3_f32 v162, v161, v162, v163
	v_med3_f32 v161, v160, v161, v163
	v_med3_f32 v160, v159, v160, v163
	v_med3_f32 v159, v158, v159, v163
	v_med3_f32 v158, v157, v158, v163
	v_med3_f32 v157, v156, v157, v163
	v_med3_f32 v156, v155, v156, v163
	v_med3_f32 v155, v154, v155, v163
	v_med3_f32 v154, v153, v154, v163
	v_med3_f32 v153, v152, v153, v163
	v_med3_f32 v152, v151, v152, v163
	v_med3_f32 v151, v150, v151, v163
	v_med3_f32 v150, v149, v150, v163
	v_max_f32_e32 v149, v149, v163
	v_add_f32_e32 v163, v91, v7
	v_and_or_b32 v163, v163, s18, 18
	v_med3_f32 v162, v161, v162, v163
	v_med3_f32 v161, v160, v161, v163
	v_med3_f32 v160, v159, v160, v163
	v_med3_f32 v159, v158, v159, v163
	v_med3_f32 v158, v157, v158, v163
	v_med3_f32 v157, v156, v157, v163
	v_med3_f32 v156, v155, v156, v163
	v_med3_f32 v155, v154, v155, v163
	v_med3_f32 v154, v153, v154, v163
	v_med3_f32 v153, v152, v153, v163
	v_med3_f32 v152, v151, v152, v163
	v_max_f32_e32 v151, v151, v163
	v_add_f32_e32 v163, v91, v8
	v_and_or_b32 v163, v163, s18, 19
	v_med3_f32 v162, v161, v162, v163
	v_med3_f32 v161, v160, v161, v163
	v_med3_f32 v160, v159, v160, v163
	v_med3_f32 v159, v158, v159, v163
	v_med3_f32 v158, v157, v158, v163
	v_med3_f32 v157, v156, v157, v163
	v_med3_f32 v156, v155, v156, v163
	v_med3_f32 v155, v154, v155, v163
	v_med3_f32 v154, v153, v154, v163
	v_max_f32_e32 v153, v153, v163
	v_add_f32_e32 v163, v91, v9
	v_and_or_b32 v163, v163, s18, 20
	v_med3_f32 v162, v161, v162, v163
	v_med3_f32 v161, v160, v161, v163
	v_med3_f32 v160, v159, v160, v163
	v_med3_f32 v159, v158, v159, v163
	v_med3_f32 v158, v157, v158, v163
	v_med3_f32 v157, v156, v157, v163
	v_med3_f32 v156, v155, v156, v163
	v_max_f32_e32 v155, v155, v163
	v_add_f32_e32 v163, v91, v12
	v_and_or_b32 v163, v163, s18, 21
	v_med3_f32 v162, v161, v162, v163
	v_med3_f32 v161, v160, v161, v163
	v_med3_f32 v160, v159, v160, v163
	v_med3_f32 v159, v158, v159, v163
	v_med3_f32 v158, v157, v158, v163
	v_max_f32_e32 v157, v157, v163
	v_add_f32_e32 v163, v91, v11
	v_and_or_b32 v163, v163, s18, 22
	v_med3_f32 v162, v161, v162, v163
	v_med3_f32 v161, v160, v161, v163
	v_med3_f32 v160, v159, v160, v163
	v_max_f32_e32 v159, v159, v163
	v_add_f32_e32 v163, v91, v10
	v_and_or_b32 v163, v163, s18, 23
	v_med3_f32 v162, v161, v162, v163
	v_max_f32_e32 v161, v161, v163
	v_add_f32_e32 v163, v87, v2
; DEV void ce(float& a, float& b) { float hi = fmaxf(a, b), lo = fminf(a, b); a = hi; b = lo; }
; DEV void phase_peer_score(const Params& p, int layer, int M, char* smem) {
;     ...
; #pragma unroll
;     for (int i = 0; i < 16; i++) R[i] = -3.0e38f;
; #pragma unroll
;     for (int i = 0; i < 16; i++)
; #pragma unroll
;       for (int j = 0; j < 16; j++)
;         if ((i + 1) * (j + 1) <= 16) {
;           float v = L0[i] + L1[j];
;           v = __uint_as_float((__float_as_uint(v) & ~255u) | (unsigned)(i * 16 + j));
; #pragma unroll
;           for (int t = 0; t < 16; t++)
;             if (t >= (i + 1) * (j + 1) - 1) ce(R[t], v);
;         }
	v_and_or_b32 v163, v163, s18, 32
	v_med3_f32 v162, v161, v162, v163
	v_med3_f32 v161, v160, v161, v163
	v_med3_f32 v160, v159, v160, v163
	v_med3_f32 v159, v158, v159, v163
	v_med3_f32 v158, v157, v158, v163
	v_med3_f32 v157, v156, v157, v163
	v_med3_f32 v156, v155, v156, v163
	v_med3_f32 v155, v154, v155, v163
	v_med3_f32 v154, v153, v154, v163
	v_med3_f32 v153, v152, v153, v163
	v_med3_f32 v152, v151, v152, v163
	v_med3_f32 v151, v150, v151, v163
	v_med3_f32 v150, v149, v150, v163
	v_med3_f32 v149, v164, v149, v163
	v_max_f32_e32 v164, v164, v163
	v_add_f32_e32 v163, v87, v4
	v_and_or_b32 v163, v163, s18, 33
	v_med3_f32 v162, v161, v162, v163
	v_med3_f32 v161, v160, v161, v163
	v_med3_f32 v160, v159, v160, v163
	v_med3_f32 v159, v158, v159, v163
	v_med3_f32 v158, v157, v158, v163
	v_med3_f32 v157, v156, v157, v163
	v_med3_f32 v156, v155, v156, v163
	v_med3_f32 v155, v154, v155, v163
	v_med3_f32 v154, v153, v154, v163
	v_med3_f32 v153, v152, v153, v163
	v_med3_f32 v152, v151, v152, v163
	v_max_f32_e32 v151, v151, v163
	v_add_f32_e32 v163, v87, v7
	v_and_or_b32 v163, v163, s18, 34
	v_med3_f32 v162, v161, v162, v163
	v_med3_f32 v161, v160, v161, v163
	v_med3_f32 v160, v159, v160, v163
	v_med3_f32 v159, v158, v159, v163
	v_med3_f32 v158, v157, v158, v163
	v_med3_f32 v157, v156, v157, v163
	v_med3_f32 v156, v155, v156, v163
	v_med3_f32 v155, v154, v155, v163
	v_max_f32_e32 v154, v154, v163
	v_add_f32_e32 v163, v87, v8
	v_and_or_b32 v163, v163, s18, 35
	v_med3_f32 v162, v161, v162, v163
	v_med3_f32 v161, v160, v161, v163
	v_med3_f32 v160, v159, v160, v163
	v_med3_f32 v159, v158, v159, v163
	v_med3_f32 v158, v157, v158, v163
	v_max_f32_e32 v157, v157, v163
	v_add_f32_e32 v163, v87, v9
	v_and_or_b32 v163, v163, s18, 36
	v_med3_f32 v162, v161, v162, v163
	v_med3_f32 v161, v160, v161, v163
	v_max_f32_e32 v160, v160, v163
	v_add_f32_e32 v163, v83, v2
	v_and_or_b32 v163, v163, s18, 48
	v_med3_f32 v162, v161, v162, v163
	v_med3_f32 v161, v160, v161, v163
	v_med3_f32 v160, v159, v160, v163
	v_med3_f32 v159, v158, v159, v163
	v_med3_f32 v158, v157, v158, v163
	v_med3_f32 v157, v156, v157, v163
	v_med3_f32 v156, v155, v156, v163
	v_med3_f32 v155, v154, v155, v163
	v_med3_f32 v154, v153, v154, v163
	v_med3_f32 v153, v152, v153, v163
	v_med3_f32 v152, v151, v152, v163
	v_med3_f32 v151, v150, v151, v163
	v_med3_f32 v150, v149, v150, v163
	v_max_f32_e32 v149, v149, v163
	v_add_f32_e32 v163, v83, v4
	v_and_or_b32 v163, v163, s18, 49
	v_med3_f32 v162, v161, v162, v163
	v_med3_f32 v161, v160, v161, v163
	v_med3_f32 v160, v159, v160, v163
	v_med3_f32 v159, v158, v159, v163
	v_med3_f32 v158, v157, v158, v163
	v_med3_f32 v157, v156, v157, v163
	v_med3_f32 v156, v155, v156, v163
	v_med3_f32 v155, v154, v155, v163
	v_med3_f32 v154, v153, v154, v163
	v_max_f32_e32 v153, v153, v163
	v_add_f32_e32 v163, v83, v7
	v_and_or_b32 v163, v163, s18, 50
	v_med3_f32 v162, v161, v162, v163
	v_med3_f32 v161, v160, v161, v163
	v_med3_f32 v160, v159, v160, v163
	v_med3_f32 v159, v158, v159, v163
	v_med3_f32 v158, v157, v158, v163
	v_max_f32_e32 v157, v157, v163
	v_add_f32_e32 v163, v83, v8
	v_and_or_b32 v163, v163, s18, 51
	v_med3_f32 v162, v161, v162, v163
	v_max_f32_e32 v161, v161, v163
	v_add_f32_e32 v163, v79, v2
	v_and_or_b32 v163, v163, s18, 64
	v_med3_f32 v162, v161, v162, v163
	v_med3_f32 v161, v160, v161, v163
	v_med3_f32 v160, v159, v160, v163
	v_med3_f32 v159, v158, v159, v163
	v_med3_f32 v158, v157, v158, v163
	v_med3_f32 v157, v156, v157, v163
	v_med3_f32 v156, v155, v156, v163
	v_med3_f32 v155, v154, v155, v163
	v_med3_f32 v154, v153, v154, v163
	v_med3_f32 v153, v152, v153, v163
	v_med3_f32 v152, v151, v152, v163
	v_med3_f32 v151, v150, v151, v163
	v_max_f32_e32 v150, v150, v163
	v_add_f32_e32 v163, v79, v4
	v_and_b32_e32 v163, 0xffffff00, v163
	v_or_b32_e32 v163, 0x41, v163
	v_med3_f32 v162, v161, v162, v163
	v_med3_f32 v161, v160, v161, v163
	v_med3_f32 v160, v159, v160, v163
	v_med3_f32 v159, v158, v159, v163
	v_med3_f32 v158, v157, v158, v163
	v_med3_f32 v157, v156, v157, v163
	v_med3_f32 v156, v155, v156, v163
	v_max_f32_e32 v155, v155, v163
	v_add_f32_e32 v163, v79, v7
	v_and_b32_e32 v163, 0xffffff00, v163
	v_or_b32_e32 v163, 0x42, v163
	v_med3_f32 v162, v161, v162, v163
	v_med3_f32 v161, v160, v161, v163
	v_max_f32_e32 v160, v160, v163
	v_add_f32_e32 v163, v75, v2
	v_and_b32_e32 v163, 0xffffff00, v163
	v_or_b32_e32 v163, 0x50, v163
	v_med3_f32 v162, v161, v162, v163
	v_med3_f32 v161, v160, v161, v163
	v_med3_f32 v160, v159, v160, v163
	v_med3_f32 v159, v158, v159, v163
	v_med3_f32 v158, v157, v158, v163
	v_med3_f32 v157, v156, v157, v163
	v_med3_f32 v156, v155, v156, v163
	v_med3_f32 v155, v154, v155, v163
	v_med3_f32 v154, v153, v154, v163
	v_med3_f32 v153, v152, v153, v163
	v_med3_f32 v152, v151, v152, v163
	v_max_f32_e32 v151, v151, v163
	v_add_f32_e32 v163, v75, v4
	v_and_b32_e32 v163, 0xffffff00, v163
	v_or_b32_e32 v163, 0x51, v163
	v_med3_f32 v162, v161, v162, v163
	v_med3_f32 v161, v160, v161, v163
	v_med3_f32 v160, v159, v160, v163
	v_med3_f32 v159, v158, v159, v163
	v_med3_f32 v158, v157, v158, v163
	v_max_f32_e32 v157, v157, v163
	v_add_f32_e32 v163, v71, v2
	v_and_b32_e32 v163, 0xffffff00, v163
	v_or_b32_e32 v163, 0x60, v163
	v_med3_f32 v162, v161, v162, v163
	v_med3_f32 v161, v160, v161, v163
	v_med3_f32 v160, v159, v160, v163
	v_med3_f32 v159, v158, v159, v163
	v_med3_f32 v158, v157, v158, v163
	v_med3_f32 v157, v156, v157, v163
	v_med3_f32 v156, v155, v156, v163
	v_med3_f32 v155, v154, v155, v163
	v_med3_f32 v154, v153, v154, v163
	v_med3_f32 v153, v152, v153, v163
	v_max_f32_e32 v152, v152, v163
	v_add_f32_e32 v163, v71, v4
; DEV void ce(float& a, float& b) { float hi = fmaxf(a, b), lo = fminf(a, b); a = hi; b = lo; }
; DEV void phase_peer_score(const Params& p, int layer, int M, char* smem) {
;     ...
; #pragma unroll
;     for (int i = 0; i < 16; i++) R[i] = -3.0e38f;
; #pragma unroll
;     for (int i = 0; i < 16; i++)
; #pragma unroll
;       for (int j = 0; j < 16; j++)
;         if ((i + 1) * (j + 1) <= 16) {
;           float v = L0[i] + L1[j];
;           v = __uint_as_float((__float_as_uint(v) & ~255u) | (unsigned)(i * 16 + j));
; #pragma unroll
;           for (int t = 0; t < 16; t++)
;             if (t >= (i + 1) * (j + 1) - 1) ce(R[t], v);
;         }
	v_and_b32_e32 v163, 0xffffff00, v163
	v_or_b32_e32 v163, 0x61, v163
	v_med3_f32 v162, v161, v162, v163
	v_med3_f32 v161, v160, v161, v163
	v_med3_f32 v160, v159, v160, v163
	v_max_f32_e32 v159, v159, v163
	v_add_f32_e32 v163, v63, v2
	v_and_b32_e32 v163, 0xffffff00, v163
	v_or_b32_e32 v163, 0x70, v163
	v_med3_f32 v162, v161, v162, v163
	v_med3_f32 v161, v160, v161, v163
	v_med3_f32 v160, v159, v160, v163
	v_med3_f32 v159, v158, v159, v163
	v_med3_f32 v158, v157, v158, v163
	v_med3_f32 v157, v156, v157, v163
	v_med3_f32 v156, v155, v156, v163
	v_med3_f32 v155, v154, v155, v163
	v_med3_f32 v154, v153, v154, v163
	v_max_f32_e32 v153, v153, v163
	v_add_f32_e32 v163, v63, v4
	v_and_b32_e32 v163, 0xffffff00, v163
	v_or_b32_e32 v163, 0x71, v163
	v_med3_f32 v162, v161, v162, v163
	v_max_f32_e32 v161, v161, v163
	v_add_f32_e32 v163, v67, v2
	v_and_b32_e32 v163, 0xffffff00, v163
	v_or_b32_e32 v163, 0x80, v163
	v_med3_f32 v162, v161, v162, v163
	v_med3_f32 v161, v160, v161, v163
	v_med3_f32 v160, v159, v160, v163
	v_med3_f32 v159, v158, v159, v163
	v_med3_f32 v158, v157, v158, v163
	v_med3_f32 v157, v156, v157, v163
	v_med3_f32 v156, v155, v156, v163
	v_med3_f32 v155, v154, v155, v163
	v_max_f32_e32 v154, v154, v163
	v_add_f32_e32 v163, v59, v2
	v_and_b32_e32 v163, 0xffffff00, v163
	v_or_b32_e32 v163, 0x90, v163
	v_med3_f32 v162, v161, v162, v163
	v_med3_f32 v161, v160, v161, v163
	v_med3_f32 v160, v159, v160, v163
	v_med3_f32 v159, v158, v159, v163
	v_med3_f32 v158, v157, v158, v163
	v_med3_f32 v157, v156, v157, v163
	v_med3_f32 v156, v155, v156, v163
	v_max_f32_e32 v155, v155, v163
	v_add_f32_e32 v163, v55, v2
	v_and_b32_e32 v163, 0xffffff00, v163
	v_or_b32_e32 v163, 0xa0, v163
	v_med3_f32 v162, v161, v162, v163
	v_med3_f32 v161, v160, v161, v163
	v_med3_f32 v160, v159, v160, v163
	v_med3_f32 v159, v158, v159, v163
	v_med3_f32 v158, v157, v158, v163
	v_med3_f32 v157, v156, v157, v163
	v_max_f32_e32 v156, v156, v163
	v_add_f32_e32 v163, v47, v2
	v_and_b32_e32 v163, 0xffffff00, v163
	v_or_b32_e32 v163, 0xb0, v163
	v_med3_f32 v162, v161, v162, v163
	v_med3_f32 v161, v160, v161, v163
	v_med3_f32 v160, v159, v160, v163
	v_med3_f32 v159, v158, v159, v163
	v_med3_f32 v158, v157, v158, v163
	v_max_f32_e32 v157, v157, v163
	v_add_f32_e32 v163, v51, v2
	v_and_b32_e32 v163, 0xffffff00, v163
	v_or_b32_e32 v163, 0xc0, v163
	v_med3_f32 v162, v161, v162, v163
	v_med3_f32 v161, v160, v161, v163
	v_med3_f32 v160, v159, v160, v163
	v_med3_f32 v159, v158, v159, v163
	v_max_f32_e32 v158, v158, v163
	v_add_f32_e32 v163, v39, v2
	v_and_b32_e32 v163, 0xffffff00, v163
	v_or_b32_e32 v163, 0xd0, v163
	v_med3_f32 v162, v161, v162, v163
	v_med3_f32 v161, v160, v161, v163
	v_med3_f32 v160, v159, v160, v163
	v_max_f32_e32 v159, v159, v163
	v_add_f32_e32 v163, v43, v2
	v_and_b32_e32 v163, 0xffffff00, v163
	v_or_b32_e32 v163, 0xe0, v163
	v_med3_f32 v162, v161, v162, v163
	v_med3_f32 v161, v160, v161, v163
	v_max_f32_e32 v160, v160, v163
	v_add_f32_e32 v163, v0, v2
	v_and_b32_e32 v163, 0xffffff00, v163
	v_or_b32_e32 v163, 0xf0, v163
	v_med3_f32 v162, v161, v162, v163
	v_max_f32_e32 v161, v161, v163
	v_cmp_le_f32_e64 s[40:41], v148, v164
	v_cmp_le_f32_e32 vcc, v164, v149
	s_or_b64 s[40:41], s[40:41], vcc
	v_cmp_le_f32_e32 vcc, v149, v150
	s_or_b64 s[40:41], s[40:41], vcc
	v_cmp_le_f32_e32 vcc, v150, v151
	s_or_b64 s[40:41], s[40:41], vcc
	v_cmp_le_f32_e32 vcc, v151, v152
	s_or_b64 s[40:41], s[40:41], vcc
	v_cmp_le_f32_e32 vcc, v152, v153
	s_or_b64 s[40:41], s[40:41], vcc
	v_cmp_le_f32_e32 vcc, v153, v154
	s_or_b64 s[40:41], s[40:41], vcc
	v_cmp_le_f32_e32 vcc, v154, v155
	s_or_b64 s[40:41], s[40:41], vcc
	v_cmp_le_f32_e32 vcc, v155, v156
	s_or_b64 s[40:41], s[40:41], vcc
	v_cmp_le_f32_e32 vcc, v156, v157
	s_or_b64 s[40:41], s[40:41], vcc
	v_cmp_le_f32_e32 vcc, v157, v158
	s_or_b64 s[40:41], s[40:41], vcc
	v_cmp_le_f32_e32 vcc, v158, v159
	s_or_b64 s[40:41], s[40:41], vcc
	v_cmp_le_f32_e32 vcc, v159, v160
	s_or_b64 s[40:41], s[40:41], vcc
	v_cmp_le_f32_e32 vcc, v160, v161
	s_or_b64 s[40:41], s[40:41], vcc
	v_cmp_le_f32_e32 vcc, v161, v162
	s_or_b64 s[40:41], s[40:41], vcc
	s_and_b64 s[40:41], s[40:41], exec
	s_cbranch_scc0 .Lmed3_ok_bb_637
	v_mov_b32_e32 v148, 0xff61b1e6
	v_mov_b32_e32 v164, 0xff61b1e6
	v_mov_b32_e32 v149, 0xff61b1e6
	v_mov_b32_e32 v150, 0xff61b1e6
	v_mov_b32_e32 v151, 0xff61b1e6
	v_mov_b32_e32 v152, 0xff61b1e6
	v_mov_b32_e32 v153, 0xff61b1e6
	v_mov_b32_e32 v154, 0xff61b1e6
	v_mov_b32_e32 v155, 0xff61b1e6
	v_mov_b32_e32 v156, 0xff61b1e6
	v_mov_b32_e32 v157, 0xff61b1e6
	v_mov_b32_e32 v158, 0xff61b1e6
	v_mov_b32_e32 v159, 0xff61b1e6
	v_mov_b32_e32 v160, 0xff61b1e6
	v_mov_b32_e32 v161, 0xff61b1e6
	v_mov_b32_e32 v162, 0xff61b1e6
	v_add_f32_e32 v163, v100, v2
	v_and_or_b32 v163, v163, s18, 0
	v_min_f32_e32 v165, v148, v163
	v_max_f32_e32 v148, v148, v163
	v_min_f32_e32 v163, v164, v165
	v_max_f32_e32 v164, v164, v165
	v_min_f32_e32 v165, v149, v163
	v_max_f32_e32 v149, v149, v163
	v_min_f32_e32 v163, v150, v165
	v_max_f32_e32 v150, v150, v165
	v_min_f32_e32 v165, v151, v163
	v_max_f32_e32 v151, v151, v163
	v_min_f32_e32 v163, v152, v165
	v_max_f32_e32 v152, v152, v165
	v_min_f32_e32 v165, v153, v163
	v_max_f32_e32 v153, v153, v163
	v_min_f32_e32 v163, v154, v165
	v_max_f32_e32 v154, v154, v165
	v_min_f32_e32 v165, v155, v163
	v_max_f32_e32 v155, v155, v163
	v_min_f32_e32 v163, v156, v165
	v_max_f32_e32 v156, v156, v165
	v_min_f32_e32 v165, v157, v163
	v_max_f32_e32 v157, v157, v163
	v_min_f32_e32 v163, v158, v165
	v_max_f32_e32 v158, v158, v165
	v_min_f32_e32 v165, v159, v163
	v_max_f32_e32 v159, v159, v163
	v_min_f32_e32 v163, v160, v165
	v_max_f32_e32 v160, v160, v165
; DEV void ce(float& a, float& b) { float hi = fmaxf(a, b), lo = fminf(a, b); a = hi; b = lo; }
; DEV void phase_peer_score(const Params& p, int layer, int M, char* smem) {
;     ...
; #pragma unroll
;     for (int i = 0; i < 16; i++) R[i] = -3.0e38f;
; #pragma unroll
;     for (int i = 0; i < 16; i++)
; #pragma unroll
;       for (int j = 0; j < 16; j++)
;         if ((i + 1) * (j + 1) <= 16) {
;           float v = L0[i] + L1[j];
;           v = __uint_as_float((__float_as_uint(v) & ~255u) | (unsigned)(i * 16 + j));
; #pragma unroll
;           for (int t = 0; t < 16; t++)
;             if (t >= (i + 1) * (j + 1) - 1) ce(R[t], v);
;         }
	v_min_f32_e32 v165, v161, v163
	v_max_f32_e32 v161, v161, v163
	v_max_f32_e32 v162, v162, v165
	v_add_f32_e32 v163, v100, v4
	v_and_or_b32 v163, v163, s18, 1
	v_min_f32_e32 v165, v164, v163
	v_max_f32_e32 v164, v164, v163
	v_min_f32_e32 v163, v149, v165
	v_max_f32_e32 v149, v149, v165
	v_min_f32_e32 v165, v150, v163
	v_max_f32_e32 v150, v150, v163
	v_min_f32_e32 v163, v151, v165
	v_max_f32_e32 v151, v151, v165
	v_min_f32_e32 v165, v152, v163
	v_max_f32_e32 v152, v152, v163
	v_min_f32_e32 v163, v153, v165
	v_max_f32_e32 v153, v153, v165
	v_min_f32_e32 v165, v154, v163
	v_max_f32_e32 v154, v154, v163
	v_min_f32_e32 v163, v155, v165
	v_max_f32_e32 v155, v155, v165
	v_min_f32_e32 v165, v156, v163
	v_max_f32_e32 v156, v156, v163
	v_min_f32_e32 v163, v157, v165
	v_max_f32_e32 v157, v157, v165
	v_min_f32_e32 v165, v158, v163
	v_max_f32_e32 v158, v158, v163
	v_min_f32_e32 v163, v159, v165
	v_max_f32_e32 v159, v159, v165
	v_min_f32_e32 v165, v160, v163
	v_max_f32_e32 v160, v160, v163
	v_min_f32_e32 v163, v161, v165
	v_max_f32_e32 v161, v161, v165
	v_max_f32_e32 v162, v162, v163
	v_add_f32_e32 v163, v100, v7
	v_and_or_b32 v163, v163, s18, 2
	v_min_f32_e32 v165, v149, v163
	v_max_f32_e32 v149, v149, v163
	v_min_f32_e32 v163, v150, v165
	v_max_f32_e32 v150, v150, v165
	v_min_f32_e32 v165, v151, v163
	v_max_f32_e32 v151, v151, v163
	v_min_f32_e32 v163, v152, v165
	v_max_f32_e32 v152, v152, v165
	v_min_f32_e32 v165, v153, v163
	v_max_f32_e32 v153, v153, v163
	v_min_f32_e32 v163, v154, v165
	v_max_f32_e32 v154, v154, v165
	v_min_f32_e32 v165, v155, v163
	v_max_f32_e32 v155, v155, v163
	v_min_f32_e32 v163, v156, v165
	v_max_f32_e32 v156, v156, v165
	v_min_f32_e32 v165, v157, v163
	v_max_f32_e32 v157, v157, v163
	v_min_f32_e32 v163, v158, v165
	v_max_f32_e32 v158, v158, v165
	v_min_f32_e32 v165, v159, v163
	v_max_f32_e32 v159, v159, v163
	v_min_f32_e32 v163, v160, v165
	v_max_f32_e32 v160, v160, v165
	v_min_f32_e32 v165, v161, v163
	v_max_f32_e32 v161, v161, v163
	v_max_f32_e32 v162, v162, v165
	v_add_f32_e32 v163, v100, v8
	v_and_or_b32 v163, v163, s18, 3
	v_min_f32_e32 v165, v150, v163
	v_max_f32_e32 v150, v150, v163
	v_min_f32_e32 v163, v151, v165
	v_max_f32_e32 v151, v151, v165
	v_min_f32_e32 v165, v152, v163
	v_max_f32_e32 v152, v152, v163
	v_min_f32_e32 v163, v153, v165
	v_max_f32_e32 v153, v153, v165
	v_min_f32_e32 v165, v154, v163
	v_max_f32_e32 v154, v154, v163
	v_min_f32_e32 v163, v155, v165
	v_max_f32_e32 v155, v155, v165
	v_min_f32_e32 v165, v156, v163
	v_max_f32_e32 v156, v156, v163
	v_min_f32_e32 v163, v157, v165
	v_max_f32_e32 v157, v157, v165
	v_min_f32_e32 v165, v158, v163
	v_max_f32_e32 v158, v158, v163
	v_min_f32_e32 v163, v159, v165
	v_max_f32_e32 v159, v159, v165
	v_min_f32_e32 v165, v160, v163
	v_max_f32_e32 v160, v160, v163
	v_min_f32_e32 v163, v161, v165
	v_max_f32_e32 v161, v161, v165
	v_max_f32_e32 v162, v162, v163
	v_add_f32_e32 v163, v100, v9
	v_and_or_b32 v163, v163, s18, 4
	v_min_f32_e32 v165, v151, v163
	v_max_f32_e32 v151, v151, v163
	v_min_f32_e32 v163, v152, v165
	v_max_f32_e32 v152, v152, v165
	v_min_f32_e32 v165, v153, v163
	v_max_f32_e32 v153, v153, v163
	v_min_f32_e32 v163, v154, v165
	v_max_f32_e32 v154, v154, v165
	v_min_f32_e32 v165, v155, v163
	v_max_f32_e32 v155, v155, v163
	v_min_f32_e32 v163, v156, v165
	v_max_f32_e32 v156, v156, v165
	v_min_f32_e32 v165, v157, v163
	v_max_f32_e32 v157, v157, v163
	v_min_f32_e32 v163, v158, v165
	v_max_f32_e32 v158, v158, v165
	v_min_f32_e32 v165, v159, v163
	v_max_f32_e32 v159, v159, v163
	v_min_f32_e32 v163, v160, v165
	v_max_f32_e32 v160, v160, v165
	v_min_f32_e32 v165, v161, v163
	v_max_f32_e32 v161, v161, v163
	v_max_f32_e32 v162, v162, v165
	v_add_f32_e32 v163, v100, v12
	v_and_or_b32 v163, v163, s18, 5
	v_min_f32_e32 v165, v152, v163
	v_max_f32_e32 v152, v152, v163
	v_min_f32_e32 v163, v153, v165
	v_max_f32_e32 v153, v153, v165
	v_min_f32_e32 v165, v154, v163
	v_max_f32_e32 v154, v154, v163
	v_min_f32_e32 v163, v155, v165
	v_max_f32_e32 v155, v155, v165
	v_min_f32_e32 v165, v156, v163
	v_max_f32_e32 v156, v156, v163
	v_min_f32_e32 v163, v157, v165
	v_max_f32_e32 v157, v157, v165
	v_min_f32_e32 v165, v158, v163
	v_max_f32_e32 v158, v158, v163
	v_min_f32_e32 v163, v159, v165
	v_max_f32_e32 v159, v159, v165
	v_min_f32_e32 v165, v160, v163
	v_max_f32_e32 v160, v160, v163
	v_min_f32_e32 v163, v161, v165
	v_max_f32_e32 v161, v161, v165
	v_max_f32_e32 v162, v162, v163
	v_add_f32_e32 v163, v100, v11
	v_and_or_b32 v163, v163, s18, 6
	v_min_f32_e32 v165, v153, v163
	v_max_f32_e32 v153, v153, v163
	v_min_f32_e32 v163, v154, v165
	v_max_f32_e32 v154, v154, v165
	v_min_f32_e32 v165, v155, v163
	v_max_f32_e32 v155, v155, v163
	v_min_f32_e32 v163, v156, v165
	v_max_f32_e32 v156, v156, v165
	v_min_f32_e32 v165, v157, v163
	v_max_f32_e32 v157, v157, v163
	v_min_f32_e32 v163, v158, v165
	v_max_f32_e32 v158, v158, v165
	v_min_f32_e32 v165, v159, v163
	v_max_f32_e32 v159, v159, v163
	v_min_f32_e32 v163, v160, v165
	v_max_f32_e32 v160, v160, v165
	v_min_f32_e32 v165, v161, v163
	v_max_f32_e32 v161, v161, v163
	v_max_f32_e32 v162, v162, v165
	v_add_f32_e32 v163, v100, v10
	v_and_or_b32 v163, v163, s18, 7
	v_min_f32_e32 v165, v154, v163
	v_max_f32_e32 v154, v154, v163
	v_min_f32_e32 v163, v155, v165
	v_max_f32_e32 v155, v155, v165
	v_min_f32_e32 v165, v156, v163
	v_max_f32_e32 v156, v156, v163
	v_min_f32_e32 v163, v157, v165
	v_max_f32_e32 v157, v157, v165
	v_min_f32_e32 v165, v158, v163
	v_max_f32_e32 v158, v158, v163
	v_min_f32_e32 v163, v159, v165
	v_max_f32_e32 v159, v159, v165
	v_min_f32_e32 v165, v160, v163
	v_max_f32_e32 v160, v160, v163
	v_min_f32_e32 v163, v161, v165
; DEV void ce(float& a, float& b) { float hi = fmaxf(a, b), lo = fminf(a, b); a = hi; b = lo; }
; DEV void phase_peer_score(const Params& p, int layer, int M, char* smem) {
;     ...
; #pragma unroll
;     for (int i = 0; i < 16; i++) R[i] = -3.0e38f;
; #pragma unroll
;     for (int i = 0; i < 16; i++)
; #pragma unroll
;       for (int j = 0; j < 16; j++)
;         if ((i + 1) * (j + 1) <= 16) {
;           float v = L0[i] + L1[j];
;           v = __uint_as_float((__float_as_uint(v) & ~255u) | (unsigned)(i * 16 + j));
; #pragma unroll
;           for (int t = 0; t < 16; t++)
;             if (t >= (i + 1) * (j + 1) - 1) ce(R[t], v);
;         }
	v_max_f32_e32 v161, v161, v165
	v_max_f32_e32 v162, v162, v163
	v_add_f32_e32 v163, v100, v20
	v_and_or_b32 v163, v163, s18, 8
	v_min_f32_e32 v165, v155, v163
	v_max_f32_e32 v155, v155, v163
	v_min_f32_e32 v163, v156, v165
	v_max_f32_e32 v156, v156, v165
	v_min_f32_e32 v165, v157, v163
	v_max_f32_e32 v157, v157, v163
	v_min_f32_e32 v163, v158, v165
	v_max_f32_e32 v158, v158, v165
	v_min_f32_e32 v165, v159, v163
	v_max_f32_e32 v159, v159, v163
	v_min_f32_e32 v163, v160, v165
	v_max_f32_e32 v160, v160, v165
	v_min_f32_e32 v165, v161, v163
	v_max_f32_e32 v161, v161, v163
	v_max_f32_e32 v162, v162, v165
	v_add_f32_e32 v163, v100, v17
	v_and_or_b32 v163, v163, s18, 9
	v_min_f32_e32 v165, v156, v163
	v_max_f32_e32 v156, v156, v163
	v_min_f32_e32 v163, v157, v165
	v_max_f32_e32 v157, v157, v165
	v_min_f32_e32 v165, v158, v163
	v_max_f32_e32 v158, v158, v163
	v_min_f32_e32 v163, v159, v165
	v_max_f32_e32 v159, v159, v165
	v_min_f32_e32 v165, v160, v163
	v_max_f32_e32 v160, v160, v163
	v_min_f32_e32 v163, v161, v165
	v_max_f32_e32 v161, v161, v165
	v_max_f32_e32 v162, v162, v163
	v_add_f32_e32 v163, v100, v16
	v_and_or_b32 v163, v163, s18, 10
	v_min_f32_e32 v165, v157, v163
	v_max_f32_e32 v157, v157, v163
	v_min_f32_e32 v163, v158, v165
	v_max_f32_e32 v158, v158, v165
	v_min_f32_e32 v165, v159, v163
	v_max_f32_e32 v159, v159, v163
	v_min_f32_e32 v163, v160, v165
	v_max_f32_e32 v160, v160, v165
	v_min_f32_e32 v165, v161, v163
	v_max_f32_e32 v161, v161, v163
	v_max_f32_e32 v162, v162, v165
	v_add_f32_e32 v163, v100, v15
	v_and_or_b32 v163, v163, s18, 11
	v_min_f32_e32 v165, v158, v163
	v_max_f32_e32 v158, v158, v163
	v_min_f32_e32 v163, v159, v165
	v_max_f32_e32 v159, v159, v165
	v_min_f32_e32 v165, v160, v163
	v_max_f32_e32 v160, v160, v163
	v_min_f32_e32 v163, v161, v165
	v_max_f32_e32 v161, v161, v165
	v_max_f32_e32 v162, v162, v163
	v_add_f32_e32 v163, v100, v14
	v_and_or_b32 v163, v163, s18, 12
	v_min_f32_e32 v165, v159, v163
	v_max_f32_e32 v159, v159, v163
	v_min_f32_e32 v163, v160, v165
	v_max_f32_e32 v160, v160, v165
	v_min_f32_e32 v165, v161, v163
	v_max_f32_e32 v161, v161, v163
	v_max_f32_e32 v162, v162, v165
	v_add_f32_e32 v163, v100, v13
	v_and_or_b32 v163, v163, s18, 13
	v_min_f32_e32 v165, v160, v163
	v_max_f32_e32 v160, v160, v163
	v_min_f32_e32 v163, v161, v165
	v_max_f32_e32 v161, v161, v165
	v_max_f32_e32 v162, v162, v163
	v_add_f32_e32 v163, v100, v6
	v_and_or_b32 v163, v163, s18, 14
	v_min_f32_e32 v165, v161, v163
	v_max_f32_e32 v161, v161, v163
	v_max_f32_e32 v162, v162, v165
	v_add_f32_e32 v163, v100, v5
	v_and_or_b32 v163, v163, s18, 15
	v_max_f32_e32 v162, v162, v163
	v_add_f32_e32 v163, v91, v2
	v_and_or_b32 v163, v163, s18, 16
	v_min_f32_e32 v165, v164, v163
	v_max_f32_e32 v164, v164, v163
	v_min_f32_e32 v163, v149, v165
	v_max_f32_e32 v149, v149, v165
	v_min_f32_e32 v165, v150, v163
	v_max_f32_e32 v150, v150, v163
	v_min_f32_e32 v163, v151, v165
	v_max_f32_e32 v151, v151, v165
	v_min_f32_e32 v165, v152, v163
	v_max_f32_e32 v152, v152, v163
	v_min_f32_e32 v163, v153, v165
	v_max_f32_e32 v153, v153, v165
	v_min_f32_e32 v165, v154, v163
	v_max_f32_e32 v154, v154, v163
	v_min_f32_e32 v163, v155, v165
	v_max_f32_e32 v155, v155, v165
	v_min_f32_e32 v165, v156, v163
	v_max_f32_e32 v156, v156, v163
	v_min_f32_e32 v163, v157, v165
	v_max_f32_e32 v157, v157, v165
	v_min_f32_e32 v165, v158, v163
	v_max_f32_e32 v158, v158, v163
	v_min_f32_e32 v163, v159, v165
	v_max_f32_e32 v159, v159, v165
	v_min_f32_e32 v165, v160, v163
	v_max_f32_e32 v160, v160, v163
	v_min_f32_e32 v163, v161, v165
	v_max_f32_e32 v161, v161, v165
	v_max_f32_e32 v162, v162, v163
	v_add_f32_e32 v163, v91, v4
	v_and_or_b32 v163, v163, s18, 17
	v_min_f32_e32 v165, v150, v163
	v_max_f32_e32 v150, v150, v163
	v_min_f32_e32 v163, v151, v165
	v_max_f32_e32 v151, v151, v165
	v_min_f32_e32 v165, v152, v163
	v_max_f32_e32 v152, v152, v163
	v_min_f32_e32 v163, v153, v165
	v_max_f32_e32 v153, v153, v165
	v_min_f32_e32 v165, v154, v163
	v_max_f32_e32 v154, v154, v163
	v_min_f32_e32 v163, v155, v165
	v_max_f32_e32 v155, v155, v165
	v_min_f32_e32 v165, v156, v163
	v_max_f32_e32 v156, v156, v163
	v_min_f32_e32 v163, v157, v165
	v_max_f32_e32 v157, v157, v165
	v_min_f32_e32 v165, v158, v163
	v_max_f32_e32 v158, v158, v163
	v_min_f32_e32 v163, v159, v165
	v_max_f32_e32 v159, v159, v165
	v_min_f32_e32 v165, v160, v163
	v_max_f32_e32 v160, v160, v163
	v_min_f32_e32 v163, v161, v165
	v_max_f32_e32 v161, v161, v165
	v_max_f32_e32 v162, v162, v163
	v_add_f32_e32 v163, v91, v7
	v_and_or_b32 v163, v163, s18, 18
	v_min_f32_e32 v165, v152, v163
	v_max_f32_e32 v152, v152, v163
	v_min_f32_e32 v163, v153, v165
	v_max_f32_e32 v153, v153, v165
	v_min_f32_e32 v165, v154, v163
	v_max_f32_e32 v154, v154, v163
	v_min_f32_e32 v163, v155, v165
	v_max_f32_e32 v155, v155, v165
	v_min_f32_e32 v165, v156, v163
	v_max_f32_e32 v156, v156, v163
	v_min_f32_e32 v163, v157, v165
	v_max_f32_e32 v157, v157, v165
	v_min_f32_e32 v165, v158, v163
	v_max_f32_e32 v158, v158, v163
	v_min_f32_e32 v163, v159, v165
	v_max_f32_e32 v159, v159, v165
	v_min_f32_e32 v165, v160, v163
	v_max_f32_e32 v160, v160, v163
	v_min_f32_e32 v163, v161, v165
	v_max_f32_e32 v161, v161, v165
	v_max_f32_e32 v162, v162, v163
	v_add_f32_e32 v163, v91, v8
	v_and_or_b32 v163, v163, s18, 19
	v_min_f32_e32 v165, v154, v163
	v_max_f32_e32 v154, v154, v163
	v_min_f32_e32 v163, v155, v165
	v_max_f32_e32 v155, v155, v165
	v_min_f32_e32 v165, v156, v163
	v_max_f32_e32 v156, v156, v163
	v_min_f32_e32 v163, v157, v165
	v_max_f32_e32 v157, v157, v165
	v_min_f32_e32 v165, v158, v163
	v_max_f32_e32 v158, v158, v163
	v_min_f32_e32 v163, v159, v165
; DEV void ce(float& a, float& b) { float hi = fmaxf(a, b), lo = fminf(a, b); a = hi; b = lo; }
; DEV void phase_peer_score(const Params& p, int layer, int M, char* smem) {
;     ...
; #pragma unroll
;     for (int i = 0; i < 16; i++) R[i] = -3.0e38f;
; #pragma unroll
;     for (int i = 0; i < 16; i++)
; #pragma unroll
;       for (int j = 0; j < 16; j++)
;         if ((i + 1) * (j + 1) <= 16) {
;           float v = L0[i] + L1[j];
;           v = __uint_as_float((__float_as_uint(v) & ~255u) | (unsigned)(i * 16 + j));
; #pragma unroll
;           for (int t = 0; t < 16; t++)
;             if (t >= (i + 1) * (j + 1) - 1) ce(R[t], v);
;         }
	v_max_f32_e32 v159, v159, v165
	v_min_f32_e32 v165, v160, v163
	v_max_f32_e32 v160, v160, v163
	v_min_f32_e32 v163, v161, v165
	v_max_f32_e32 v161, v161, v165
	v_max_f32_e32 v162, v162, v163
	v_add_f32_e32 v163, v91, v9
	v_and_or_b32 v163, v163, s18, 20
	v_min_f32_e32 v165, v156, v163
	v_max_f32_e32 v156, v156, v163
	v_min_f32_e32 v163, v157, v165
	v_max_f32_e32 v157, v157, v165
	v_min_f32_e32 v165, v158, v163
	v_max_f32_e32 v158, v158, v163
	v_min_f32_e32 v163, v159, v165
	v_max_f32_e32 v159, v159, v165
	v_min_f32_e32 v165, v160, v163
	v_max_f32_e32 v160, v160, v163
	v_min_f32_e32 v163, v161, v165
	v_max_f32_e32 v161, v161, v165
	v_max_f32_e32 v162, v162, v163
	v_add_f32_e32 v163, v91, v12
	v_and_or_b32 v163, v163, s18, 21
	v_min_f32_e32 v165, v158, v163
	v_max_f32_e32 v158, v158, v163
	v_min_f32_e32 v163, v159, v165
	v_max_f32_e32 v159, v159, v165
	v_min_f32_e32 v165, v160, v163
	v_max_f32_e32 v160, v160, v163
	v_min_f32_e32 v163, v161, v165
	v_max_f32_e32 v161, v161, v165
	v_max_f32_e32 v162, v162, v163
	v_add_f32_e32 v163, v91, v11
	v_and_or_b32 v163, v163, s18, 22
	v_min_f32_e32 v165, v160, v163
	v_max_f32_e32 v160, v160, v163
	v_min_f32_e32 v163, v161, v165
	v_max_f32_e32 v161, v161, v165
	v_max_f32_e32 v162, v162, v163
	v_add_f32_e32 v163, v91, v10
	v_and_or_b32 v163, v163, s18, 23
	v_max_f32_e32 v162, v162, v163
	v_add_f32_e32 v163, v87, v2
	v_and_or_b32 v163, v163, s18, 32
	v_min_f32_e32 v165, v149, v163
	v_max_f32_e32 v149, v149, v163
	v_min_f32_e32 v163, v150, v165
	v_max_f32_e32 v150, v150, v165
	v_min_f32_e32 v165, v151, v163
	v_max_f32_e32 v151, v151, v163
	v_min_f32_e32 v163, v152, v165
	v_max_f32_e32 v152, v152, v165
	v_min_f32_e32 v165, v153, v163
	v_max_f32_e32 v153, v153, v163
	v_min_f32_e32 v163, v154, v165
	v_max_f32_e32 v154, v154, v165
	v_min_f32_e32 v165, v155, v163
	v_max_f32_e32 v155, v155, v163
	v_min_f32_e32 v163, v156, v165
	v_max_f32_e32 v156, v156, v165
	v_min_f32_e32 v165, v157, v163
	v_max_f32_e32 v157, v157, v163
	v_min_f32_e32 v163, v158, v165
	v_max_f32_e32 v158, v158, v165
	v_min_f32_e32 v165, v159, v163
	v_max_f32_e32 v159, v159, v163
	v_min_f32_e32 v163, v160, v165
	v_max_f32_e32 v160, v160, v165
	v_min_f32_e32 v165, v161, v163
	v_max_f32_e32 v161, v161, v163
	v_max_f32_e32 v162, v162, v165
	v_add_f32_e32 v163, v87, v4
	v_and_or_b32 v163, v163, s18, 33
	v_min_f32_e32 v165, v152, v163
	v_max_f32_e32 v152, v152, v163
	v_min_f32_e32 v163, v153, v165
	v_max_f32_e32 v153, v153, v165
	v_min_f32_e32 v165, v154, v163
	v_max_f32_e32 v154, v154, v163
	v_min_f32_e32 v163, v155, v165
	v_max_f32_e32 v155, v155, v165
	v_min_f32_e32 v165, v156, v163
	v_max_f32_e32 v156, v156, v163
	v_min_f32_e32 v163, v157, v165
	v_max_f32_e32 v157, v157, v165
	v_min_f32_e32 v165, v158, v163
	v_max_f32_e32 v158, v158, v163
	v_min_f32_e32 v163, v159, v165
	v_max_f32_e32 v159, v159, v165
	v_min_f32_e32 v165, v160, v163
	v_max_f32_e32 v160, v160, v163
	v_min_f32_e32 v163, v161, v165
	v_max_f32_e32 v161, v161, v165
	v_max_f32_e32 v162, v162, v163
	v_add_f32_e32 v163, v87, v7
	v_and_or_b32 v163, v163, s18, 34
	v_min_f32_e32 v165, v155, v163
	v_max_f32_e32 v155, v155, v163
	v_min_f32_e32 v163, v156, v165
	v_max_f32_e32 v156, v156, v165
	v_min_f32_e32 v165, v157, v163
	v_max_f32_e32 v157, v157, v163
	v_min_f32_e32 v163, v158, v165
	v_max_f32_e32 v158, v158, v165
	v_min_f32_e32 v165, v159, v163
	v_max_f32_e32 v159, v159, v163
	v_min_f32_e32 v163, v160, v165
	v_max_f32_e32 v160, v160, v165
	v_min_f32_e32 v165, v161, v163
	v_max_f32_e32 v161, v161, v163
	v_max_f32_e32 v162, v162, v165
	v_add_f32_e32 v163, v87, v8
	v_and_or_b32 v163, v163, s18, 35
	v_min_f32_e32 v165, v158, v163
	v_max_f32_e32 v158, v158, v163
	v_min_f32_e32 v163, v159, v165
	v_max_f32_e32 v159, v159, v165
	v_min_f32_e32 v165, v160, v163
	v_max_f32_e32 v160, v160, v163
	v_min_f32_e32 v163, v161, v165
	v_max_f32_e32 v161, v161, v165
	v_max_f32_e32 v162, v162, v163
	v_add_f32_e32 v163, v87, v9
	v_and_or_b32 v163, v163, s18, 36
	v_min_f32_e32 v165, v161, v163
	v_max_f32_e32 v161, v161, v163
	v_max_f32_e32 v162, v162, v165
	v_add_f32_e32 v163, v83, v2
	v_and_or_b32 v163, v163, s18, 48
	v_min_f32_e32 v165, v150, v163
	v_max_f32_e32 v150, v150, v163
	v_min_f32_e32 v163, v151, v165
	v_max_f32_e32 v151, v151, v165
	v_min_f32_e32 v165, v152, v163
	v_max_f32_e32 v152, v152, v163
	v_min_f32_e32 v163, v153, v165
	v_max_f32_e32 v153, v153, v165
	v_min_f32_e32 v165, v154, v163
	v_max_f32_e32 v154, v154, v163
	v_min_f32_e32 v163, v155, v165
	v_max_f32_e32 v155, v155, v165
	v_min_f32_e32 v165, v156, v163
	v_max_f32_e32 v156, v156, v163
	v_min_f32_e32 v163, v157, v165
	v_max_f32_e32 v157, v157, v165
	v_min_f32_e32 v165, v158, v163
	v_max_f32_e32 v158, v158, v163
	v_min_f32_e32 v163, v159, v165
	v_max_f32_e32 v159, v159, v165
	v_min_f32_e32 v165, v160, v163
	v_max_f32_e32 v160, v160, v163
	v_min_f32_e32 v163, v161, v165
	v_max_f32_e32 v161, v161, v165
	v_max_f32_e32 v162, v162, v163
	v_add_f32_e32 v163, v83, v4
	v_and_or_b32 v163, v163, s18, 49
	v_min_f32_e32 v165, v154, v163
	v_max_f32_e32 v154, v154, v163
	v_min_f32_e32 v163, v155, v165
	v_max_f32_e32 v155, v155, v165
	v_min_f32_e32 v165, v156, v163
	v_max_f32_e32 v156, v156, v163
	v_min_f32_e32 v163, v157, v165
	v_max_f32_e32 v157, v157, v165
	v_min_f32_e32 v165, v158, v163
	v_max_f32_e32 v158, v158, v163
	v_min_f32_e32 v163, v159, v165
	v_max_f32_e32 v159, v159, v165
	v_min_f32_e32 v165, v160, v163
	v_max_f32_e32 v160, v160, v163
	v_min_f32_e32 v163, v161, v165
	v_max_f32_e32 v161, v161, v165
	v_max_f32_e32 v162, v162, v163
	v_add_f32_e32 v163, v83, v7
	v_and_or_b32 v163, v163, s18, 50
	v_min_f32_e32 v165, v158, v163
	v_max_f32_e32 v158, v158, v163
; DEV void ce(float& a, float& b) { float hi = fmaxf(a, b), lo = fminf(a, b); a = hi; b = lo; }
; DEV void phase_peer_score(const Params& p, int layer, int M, char* smem) {
;     ...
; #pragma unroll
;     for (int i = 0; i < 16; i++) R[i] = -3.0e38f;
; #pragma unroll
;     for (int i = 0; i < 16; i++)
; #pragma unroll
;       for (int j = 0; j < 16; j++)
;         if ((i + 1) * (j + 1) <= 16) {
;           float v = L0[i] + L1[j];
;           v = __uint_as_float((__float_as_uint(v) & ~255u) | (unsigned)(i * 16 + j));
; #pragma unroll
;           for (int t = 0; t < 16; t++)
;             if (t >= (i + 1) * (j + 1) - 1) ce(R[t], v);
;         }
	v_min_f32_e32 v163, v159, v165
	v_max_f32_e32 v159, v159, v165
	v_min_f32_e32 v165, v160, v163
	v_max_f32_e32 v160, v160, v163
	v_min_f32_e32 v163, v161, v165
	v_max_f32_e32 v161, v161, v165
	v_max_f32_e32 v162, v162, v163
	v_add_f32_e32 v163, v83, v8
	v_and_or_b32 v163, v163, s18, 51
	v_max_f32_e32 v162, v162, v163
	v_add_f32_e32 v163, v79, v2
	v_and_or_b32 v163, v163, s18, 64
	v_min_f32_e32 v165, v151, v163
	v_max_f32_e32 v151, v151, v163
	v_min_f32_e32 v163, v152, v165
	v_max_f32_e32 v152, v152, v165
	v_min_f32_e32 v165, v153, v163
	v_max_f32_e32 v153, v153, v163
	v_min_f32_e32 v163, v154, v165
	v_max_f32_e32 v154, v154, v165
	v_min_f32_e32 v165, v155, v163
	v_max_f32_e32 v155, v155, v163
	v_min_f32_e32 v163, v156, v165
	v_max_f32_e32 v156, v156, v165
	v_min_f32_e32 v165, v157, v163
	v_max_f32_e32 v157, v157, v163
	v_min_f32_e32 v163, v158, v165
	v_max_f32_e32 v158, v158, v165
	v_min_f32_e32 v165, v159, v163
	v_max_f32_e32 v159, v159, v163
	v_min_f32_e32 v163, v160, v165
	v_max_f32_e32 v160, v160, v165
	v_min_f32_e32 v165, v161, v163
	v_max_f32_e32 v161, v161, v163
	v_max_f32_e32 v162, v162, v165
	v_add_f32_e32 v163, v79, v4
	v_and_b32_e32 v163, 0xffffff00, v163
	v_or_b32_e32 v163, 0x41, v163
	v_min_f32_e32 v165, v156, v163
	v_max_f32_e32 v156, v156, v163
	v_min_f32_e32 v163, v157, v165
	v_max_f32_e32 v157, v157, v165
	v_min_f32_e32 v165, v158, v163
	v_max_f32_e32 v158, v158, v163
	v_min_f32_e32 v163, v159, v165
	v_max_f32_e32 v159, v159, v165
	v_min_f32_e32 v165, v160, v163
	v_max_f32_e32 v160, v160, v163
	v_min_f32_e32 v163, v161, v165
	v_max_f32_e32 v161, v161, v165
	v_max_f32_e32 v162, v162, v163
	v_add_f32_e32 v163, v79, v7
	v_and_b32_e32 v163, 0xffffff00, v163
	v_or_b32_e32 v163, 0x42, v163
	v_min_f32_e32 v165, v161, v163
	v_max_f32_e32 v161, v161, v163
	v_max_f32_e32 v162, v162, v165
	v_add_f32_e32 v163, v75, v2
	v_and_b32_e32 v163, 0xffffff00, v163
	v_or_b32_e32 v163, 0x50, v163
	v_min_f32_e32 v165, v152, v163
	v_max_f32_e32 v152, v152, v163
	v_min_f32_e32 v163, v153, v165
	v_max_f32_e32 v153, v153, v165
	v_min_f32_e32 v165, v154, v163
	v_max_f32_e32 v154, v154, v163
	v_min_f32_e32 v163, v155, v165
	v_max_f32_e32 v155, v155, v165
	v_min_f32_e32 v165, v156, v163
	v_max_f32_e32 v156, v156, v163
	v_min_f32_e32 v163, v157, v165
	v_max_f32_e32 v157, v157, v165
	v_min_f32_e32 v165, v158, v163
	v_max_f32_e32 v158, v158, v163
	v_min_f32_e32 v163, v159, v165
	v_max_f32_e32 v159, v159, v165
	v_min_f32_e32 v165, v160, v163
	v_max_f32_e32 v160, v160, v163
	v_min_f32_e32 v163, v161, v165
	v_max_f32_e32 v161, v161, v165
	v_max_f32_e32 v162, v162, v163
	v_add_f32_e32 v163, v75, v4
	v_and_b32_e32 v163, 0xffffff00, v163
	v_or_b32_e32 v163, 0x51, v163
	v_min_f32_e32 v165, v158, v163
	v_max_f32_e32 v158, v158, v163
	v_min_f32_e32 v163, v159, v165
	v_max_f32_e32 v159, v159, v165
	v_min_f32_e32 v165, v160, v163
	v_max_f32_e32 v160, v160, v163
	v_min_f32_e32 v163, v161, v165
	v_max_f32_e32 v161, v161, v165
	v_max_f32_e32 v162, v162, v163
	v_add_f32_e32 v163, v71, v2
	v_and_b32_e32 v163, 0xffffff00, v163
	v_or_b32_e32 v163, 0x60, v163
	v_min_f32_e32 v165, v153, v163
	v_max_f32_e32 v153, v153, v163
	v_min_f32_e32 v163, v154, v165
	v_max_f32_e32 v154, v154, v165
	v_min_f32_e32 v165, v155, v163
	v_max_f32_e32 v155, v155, v163
	v_min_f32_e32 v163, v156, v165
	v_max_f32_e32 v156, v156, v165
	v_min_f32_e32 v165, v157, v163
	v_max_f32_e32 v157, v157, v163
	v_min_f32_e32 v163, v158, v165
	v_max_f32_e32 v158, v158, v165
	v_min_f32_e32 v165, v159, v163
	v_max_f32_e32 v159, v159, v163
	v_min_f32_e32 v163, v160, v165
	v_max_f32_e32 v160, v160, v165
	v_min_f32_e32 v165, v161, v163
	v_max_f32_e32 v161, v161, v163
	v_max_f32_e32 v162, v162, v165
	v_add_f32_e32 v163, v71, v4
	v_and_b32_e32 v163, 0xffffff00, v163
	v_or_b32_e32 v163, 0x61, v163
; DEV void ce(float& a, float& b) { float hi = fmaxf(a, b), lo = fminf(a, b); a = hi; b = lo; }
; DEV void phase_peer_score(const Params& p, int layer, int M, char* smem) {
;     ...
; #pragma unroll
;     for (int i = 0; i < 16; i++)
; #pragma unroll
;       for (int j = 0; j < 16; j++)
;         if ((i + 1) * (j + 1) <= 16) {
;           float v = L0[i] + L1[j];
;           v = __uint_as_float((__float_as_uint(v) & ~255u) | (unsigned)(i * 16 + j));
; #pragma unroll
;           for (int t = 0; t < 16; t++)
;             if (t >= (i + 1) * (j + 1) - 1) ce(R[t], v);
;         }
	v_min_f32_e32 v165, v160, v163
	v_max_f32_e32 v160, v160, v163
	v_min_f32_e32 v163, v161, v165
	v_max_f32_e32 v161, v161, v165
	v_max_f32_e32 v162, v162, v163
	v_add_f32_e32 v163, v63, v2
	v_and_b32_e32 v163, 0xffffff00, v163
	v_or_b32_e32 v163, 0x70, v163
	v_min_f32_e32 v165, v154, v163
	v_max_f32_e32 v154, v154, v163
	v_min_f32_e32 v163, v155, v165
	v_max_f32_e32 v155, v155, v165
	v_min_f32_e32 v165, v156, v163
	v_max_f32_e32 v156, v156, v163
	v_min_f32_e32 v163, v157, v165
	v_max_f32_e32 v157, v157, v165
	v_min_f32_e32 v165, v158, v163
	v_max_f32_e32 v158, v158, v163
	v_min_f32_e32 v163, v159, v165
	v_max_f32_e32 v159, v159, v165
	v_min_f32_e32 v165, v160, v163
	v_max_f32_e32 v160, v160, v163
	v_min_f32_e32 v163, v161, v165
	v_max_f32_e32 v161, v161, v165
	v_max_f32_e32 v162, v162, v163
	v_add_f32_e32 v163, v63, v4
	v_and_b32_e32 v163, 0xffffff00, v163
	v_or_b32_e32 v163, 0x71, v163
	v_max_f32_e32 v162, v162, v163
	v_add_f32_e32 v163, v67, v2
	v_and_b32_e32 v163, 0xffffff00, v163
	v_or_b32_e32 v163, 0x80, v163
	v_min_f32_e32 v165, v155, v163
	v_max_f32_e32 v155, v155, v163
	v_min_f32_e32 v163, v156, v165
	v_max_f32_e32 v156, v156, v165
	v_min_f32_e32 v165, v157, v163
	v_max_f32_e32 v157, v157, v163
	v_min_f32_e32 v163, v158, v165
	v_max_f32_e32 v158, v158, v165
	v_min_f32_e32 v165, v159, v163
	v_max_f32_e32 v159, v159, v163
	v_min_f32_e32 v163, v160, v165
	v_max_f32_e32 v160, v160, v165
	v_min_f32_e32 v165, v161, v163
	v_max_f32_e32 v161, v161, v163
	v_max_f32_e32 v162, v162, v165
	v_add_f32_e32 v163, v59, v2
	v_and_b32_e32 v163, 0xffffff00, v163
	v_or_b32_e32 v163, 0x90, v163
	v_min_f32_e32 v165, v156, v163
	v_max_f32_e32 v156, v156, v163
	v_min_f32_e32 v163, v157, v165
	v_max_f32_e32 v157, v157, v165
	v_min_f32_e32 v165, v158, v163
	v_max_f32_e32 v158, v158, v163
	v_min_f32_e32 v163, v159, v165
	v_max_f32_e32 v159, v159, v165
	v_min_f32_e32 v165, v160, v163
	v_max_f32_e32 v160, v160, v163
	v_min_f32_e32 v163, v161, v165
	v_max_f32_e32 v161, v161, v165
	v_max_f32_e32 v162, v162, v163
	v_add_f32_e32 v163, v55, v2
	v_and_b32_e32 v163, 0xffffff00, v163
	v_or_b32_e32 v163, 0xa0, v163
	v_min_f32_e32 v165, v157, v163
	v_max_f32_e32 v157, v157, v163
	v_min_f32_e32 v163, v158, v165
	v_max_f32_e32 v158, v158, v165
	v_min_f32_e32 v165, v159, v163
	v_max_f32_e32 v159, v159, v163
	v_min_f32_e32 v163, v160, v165
	v_max_f32_e32 v160, v160, v165
	v_min_f32_e32 v165, v161, v163
	v_max_f32_e32 v161, v161, v163
	v_max_f32_e32 v162, v162, v165
	v_add_f32_e32 v163, v47, v2
	v_and_b32_e32 v163, 0xffffff00, v163
	v_or_b32_e32 v163, 0xb0, v163
	v_min_f32_e32 v165, v158, v163
	v_max_f32_e32 v158, v158, v163
	v_min_f32_e32 v163, v159, v165
	v_max_f32_e32 v159, v159, v165
	v_min_f32_e32 v165, v160, v163
	v_max_f32_e32 v160, v160, v163
	v_min_f32_e32 v163, v161, v165
	v_max_f32_e32 v161, v161, v165
	v_max_f32_e32 v162, v162, v163
	v_add_f32_e32 v163, v51, v2
	v_and_b32_e32 v163, 0xffffff00, v163
	v_or_b32_e32 v163, 0xc0, v163
	v_min_f32_e32 v165, v159, v163
	v_max_f32_e32 v159, v159, v163
	v_min_f32_e32 v163, v160, v165
	v_max_f32_e32 v160, v160, v165
	v_min_f32_e32 v165, v161, v163
	v_max_f32_e32 v161, v161, v163
	v_max_f32_e32 v162, v162, v165
	v_add_f32_e32 v163, v39, v2
	v_and_b32_e32 v163, 0xffffff00, v163
	v_or_b32_e32 v163, 0xd0, v163
	v_min_f32_e32 v165, v160, v163
	v_max_f32_e32 v160, v160, v163
	v_min_f32_e32 v163, v161, v165
	v_max_f32_e32 v161, v161, v165
	v_max_f32_e32 v162, v162, v163
	v_add_f32_e32 v163, v43, v2
	v_and_b32_e32 v163, 0xffffff00, v163
	v_or_b32_e32 v163, 0xe0, v163
	v_min_f32_e32 v165, v161, v163
	v_max_f32_e32 v161, v161, v163
	v_max_f32_e32 v162, v162, v165
	v_add_f32_e32 v163, v0, v2
	v_and_b32_e32 v163, 0xffffff00, v163
	v_or_b32_e32 v163, 0xf0, v163
	v_max_f32_e32 v162, v162, v163
